# v55 + ResLN permlane16/32 reductions instead of ds_bpermute + dead DPP zero-inits as s_nop 0 (both bit-identical)
# speedup vs baseline: 1.0162x; 1.0018x over previous
; #define LAS __attribute__((address_space(3)))
;     __device__ __forceinline__ void operator()(const f32x4 (&acc)[2][2][4][2], const Unit& u, int wr, int wc, int fr, int fq, const EpiCtx& X) const {
;     ...
;         char* yb = nullptr; char* xb = (char*)(XB + (size_t)u.pm * BM * DM + (size_t)(u.pn * 4 + wc) * (BM * 64));
;         unsigned lo = (unsigned)((wr * 64 + fe) * 64 + o32 + 8 * fq) * 2u; EPI_OPAQUE(lo);
;         const int col = u.pn * BM + wc * 64 + o32 + 8 * fq;
;         f32x4 g0, g1, b0, b1;
;         if (RESN) { ensure_tbl(PSp, sidp, u.pm, X);
;             g0 = *(const f32x4*)(gp + col); g1 = *(const f32x4*)(gp + col + 4); b0 = *(const f32x4*)(bp + col) * ALPHA; b1 = *(const f32x4*)(bp + col + 4) * ALPHA; }
;         const LAS f32x2* tbl = (const LAS f32x2*)(X.lds + TBL_OFF) + wr * 64 + fe;
;         f32x2* ps = PSn + ((size_t)u.pm * BM + wr * 64 + fe) * 64 + u.pn * 4 + wc;
; #pragma unroll
;         for (int ai = 0; ai < 2; ++ai) {
;             u32x4 raw[8];
; #pragma unroll
;             for (int m = 0; m < 4; ++m) { const unsigned off = lo + (unsigned)((ai * HALF + m * 16) * 64) * 2u; raw[2 * m] = *(const u32x4*)(xb + off); raw[2 * m + 1] = *(const u32x4*)(xb + off + 128); }
; #pragma unroll
;             for (int m = 0; m < 4; ++m) {
;                 const int rl = ai * HALF + m * 16; const unsigned off = lo + (unsigned)(rl * 64) * 2u;
;                 const f32x4 o0a = acc[ai][0][m][0], o0b = acc[ai][0][m][1], o1a = acc[ai][1][m][0], o1b = acc[ai][1][m][1];
;                 const f32x4 ra_ = dpp_swap1(odd ? o0a : o1a), rb_ = dpp_swap1(odd ? o0b : o1b);
;                 const f32x4 pa[2] = {odd ? ra_ : o0a, odd ? o1a : ra_}, pb[2] = {odd ? rb_ : o0b, odd ? o1b : rb_};
; #pragma unroll
;                 for (int q = 0; q < 2; ++q) {
;                     const u32x4 w0 = raw[2 * m + q];
;                     const f32x4 r0 = (f32x4){bf_lo(w0.x), bf_hi(w0.x), bf_lo(w0.y), bf_hi(w0.y)}, r1 = (f32x4){bf_lo(w0.z), bf_hi(w0.z), bf_lo(w0.w), bf_hi(w0.w)};
;                     f32x4 y0, y1;
;                     if (RESN) { const f32x2 t = tbl[rl + q]; const float mu = t.x, ra = t.y * ALPHA; y0 = (r0 - mu) * ra * g0 + b0 + pa[q]; y1 = (r1 - mu) * ra * g1 + b1 + pb[q]; }
;                     else { y0 = r0 * ALPHA + pa[q]; y1 = r1 * ALPHA + pb[q]; }
;                     { const u32x4 w = pack8f(y0, y1); *(u32x4*)(xb + off + q * 128) = w;
.LBB0_582:
	s_ashr_i32 s57, s56, 31
	s_lshl_b64 s[52:53], s[56:57], 21
	s_add_u32 s21, s46, s52
	s_addc_u32 s23, s47, s53
	s_lshl_b32 s58, s54, 2
	s_or_b32 s52, s58, s41
	s_ashr_i32 s53, s52, 31
	s_lshl_b64 s[52:53], s[52:53], 15
	s_add_u32 s54, s21, s52
	s_addc_u32 s55, s23, s53
	v_mov_b32_e32 v164, v183
	global_load_dwordx4 v[194:197], v164, s[54:55]
	v_add_u32_e32 v180, 0x800, v164
	v_add_u32_e32 v178, 0x1000, v164
	v_add_u32_e32 v176, 0x1800, v164
	global_load_dwordx4 v[152:155], v164, s[54:55] offset:128
	global_load_dwordx4 v[148:151], v180, s[54:55]
	global_load_dwordx4 v[144:147], v180, s[54:55] offset:128
	global_load_dwordx4 v[140:143], v178, s[54:55]
	global_load_dwordx4 v[136:139], v178, s[54:55] offset:128
	global_load_dwordx4 v[132:135], v176, s[54:55]
	global_load_dwordx4 v[120:123], v176, s[54:55] offset:128
	v_cndmask_b32_e64 v199, v129, v117, s[8:9]
	v_cndmask_b32_e64 v200, v128, v116, s[8:9]
	s_nop 0
	s_nop 0
	v_cndmask_b32_e64 v201, v127, v115, s[8:9]
	v_cndmask_b32_e64 v202, v126, v114, s[8:9]
	v_cndmask_b32_e64 v203, v125, v113, s[8:9]
	v_cndmask_b32_e64 v204, v124, v112, s[8:9]
	s_nop 0
	s_nop 0
	s_nop 0
	s_nop 0
	v_cndmask_b32_e64 v193, v131, v119, s[8:9]
	v_cndmask_b32_e64 v198, v130, v118, s[8:9]
	s_nop 0
	s_nop 0
	v_mov_b32_dpp v177, v200 quad_perm:[1,0,3,2] row_mask:0xf bank_mask:0xf
	v_mov_b32_dpp v181, v199 quad_perm:[1,0,3,2] row_mask:0xf bank_mask:0xf
	v_mov_b32_dpp v189, v204 quad_perm:[1,0,3,2] row_mask:0xf bank_mask:0xf
	v_mov_b32_dpp v191, v203 quad_perm:[1,0,3,2] row_mask:0xf bank_mask:0xf
	v_mov_b32_dpp v190, v202 quad_perm:[1,0,3,2] row_mask:0xf bank_mask:0xf
	v_mov_b32_dpp v192, v201 quad_perm:[1,0,3,2] row_mask:0xf bank_mask:0xf
	v_mov_b32_dpp v179, v198 quad_perm:[1,0,3,2] row_mask:0xf bank_mask:0xf
	v_mov_b32_dpp v188, v193 quad_perm:[1,0,3,2] row_mask:0xf bank_mask:0xf
	v_cndmask_b32_e64 v129, v181, v129, s[8:9]
	v_cndmask_b32_e64 v128, v177, v128, s[8:9]
	v_cndmask_b32_e64 v125, v191, v125, s[8:9]
	v_cndmask_b32_e64 v124, v189, v124, s[8:9]
	v_cndmask_b32_e64 v127, v192, v127, s[8:9]
	v_cndmask_b32_e64 v126, v190, v126, s[8:9]
	v_and_b32_e32 v206, 64, v187
	v_cndmask_b32_e64 v131, v188, v131, s[8:9]
	v_cndmask_b32_e64 v130, v179, v130, s[8:9]
	v_xor_b32_e32 v205, 16, v187
	v_add_u32_e32 v193, 64, v206
	v_cmp_lt_i32_e32 vcc, v205, v193
	s_lshl_b64 s[52:53], s[56:57], 17
	v_lshl_add_u64 v[198:199], v[166:167], 0, s[52:53]
	v_cndmask_b32_e32 v210, v187, v205, vcc
	s_ashr_i32 s59, s58, 31
	v_add_u32_e32 v246, 0x4000, v164
	v_add_u32_e32 v247, 0x4800, v164
	global_load_dwordx4 v[230:233], v246, s[54:55]
	global_load_dwordx4 v[234:237], v246, s[54:55] offset:128
	global_load_dwordx4 v[238:241], v247, s[54:55]
	global_load_dwordx4 v[242:245], v247, s[54:55] offset:128
	s_waitcnt vmcnt(11)
	v_lshlrev_b32_e32 v200, 16, v194
	v_and_b32_e32 v201, 0xffff0000, v194
	v_lshlrev_b32_e32 v202, 16, v196
	v_and_b32_e32 v203, 0xffff0000, v196
	v_lshlrev_b32_e32 v196, 16, v197
	v_and_b32_e32 v197, 0xffff0000, v197
	v_lshlrev_b32_e32 v194, 16, v195
	v_and_b32_e32 v195, 0xffff0000, v195
	v_pk_fma_f32 v[128:129], v[200:201], s[18:19], v[128:129] op_sel_hi:[1,0,1]
	v_pk_fma_f32 v[126:127], v[196:197], s[18:19], v[126:127] op_sel_hi:[1,0,1]
	v_pk_fma_f32 v[124:125], v[202:203], s[18:19], v[124:125] op_sel_hi:[1,0,1]
	v_pk_fma_f32 v[130:131], v[194:195], s[18:19], v[130:131] op_sel_hi:[1,0,1]
	v_cvt_pk_bf16_f32 v194, v128, v129
	s_nop 0
	v_cvt_pk_bf16_f32 v195, v130, v131
	v_cvt_pk_bf16_f32 v196, v124, v125
	v_cvt_pk_bf16_f32 v197, v126, v127
	v_lshlrev_b32_e32 v124, 16, v194
	v_and_b32_e32 v126, 0xffff0000, v194
	v_lshlrev_b32_e32 v128, 16, v195
	v_and_b32_e32 v200, 0xffff0000, v195
	v_lshlrev_b32_e32 v202, 16, v196
	v_and_b32_e32 v204, 0xffff0000, v196
	v_lshlrev_b32_e32 v206, 16, v197
	v_and_b32_e32 v208, 0xffff0000, v197
	v_mul_f32_e32 v125, v124, v124
	v_mul_f32_e32 v127, v126, v126
	v_mul_f32_e32 v129, v128, v128
	v_mul_f32_e32 v201, v200, v200
	v_mul_f32_e32 v203, v202, v202
	v_mul_f32_e32 v205, v204, v204
	v_mul_f32_e32 v207, v206, v206
	v_mul_f32_e32 v209, v208, v208
	v_pk_add_f32 v[124:125], v[124:125], v[126:127]
	v_pk_add_f32 v[126:127], v[128:129], v[200:201]
	v_pk_add_f32 v[128:129], v[206:207], v[208:209]
	v_pk_add_f32 v[124:125], v[124:125], v[126:127]
	v_pk_add_f32 v[126:127], v[202:203], v[204:205]
	v_lshlrev_b32_e32 v130, 2, v210
	v_pk_add_f32 v[126:127], v[126:127], v[128:129]
	v_xor_b32_e32 v128, 32, v187
	v_pk_add_f32 v[124:125], v[124:125], v[126:127]
	s_nop 0
	s_nop 0
	v_cmp_lt_i32_e32 vcc, v128, v193
	v_mov_b32_dpp v126, v124 quad_perm:[1,0,3,2] row_mask:0xf bank_mask:0xf
	v_mov_b32_dpp v127, v125 quad_perm:[1,0,3,2] row_mask:0xf bank_mask:0xf
	v_pk_add_f32 v[124:125], v[124:125], v[126:127]
	v_mov_b32_e32 v126, v124
	v_mov_b32_e32 v127, v125
	s_nop 1
	v_permlane16_swap_b32_e32 v124, v126
	v_permlane16_swap_b32_e32 v125, v127
	v_cndmask_b32_e32 v128, v187, v128, vcc
	v_lshlrev_b32_e32 v131, 2, v128
	global_store_dwordx4 v164, v[194:197], s[54:55]
	s_waitcnt lgkmcnt(0)
	v_pk_add_f32 v[126:127], v[124:125], v[126:127]
	v_mov_b32_e32 v128, v126
	v_mov_b32_e32 v129, v127
	s_nop 1
	v_permlane32_swap_b32_e32 v126, v128
	v_permlane32_swap_b32_e32 v127, v129
	v_lshl_add_u64 v[124:125], s[58:59], 3, v[198:199]
	v_lshl_add_u64 v[124:125], v[124:125], 0, s[14:15]
	s_and_saveexec_b64 s[52:53], s[10:11]
	s_waitcnt lgkmcnt(0)
	v_pk_add_f32 v[126:127], v[126:127], v[128:129]
	global_store_dwordx2 v[124:125], v[126:127], off

; __device__ __forceinline__ u32x4 pack8f(f32x4 a, f32x4 b) { u32x4 w; w.x = cvt_pk_bf16(a[0], a[1]); w.y = cvt_pk_bf16(a[2], a[3]); w.z = cvt_pk_bf16(b[0], b[1]); w.w = cvt_pk_bf16(b[2], b[3]); return w; }
;     __device__ __forceinline__ void operator()(const f32x4 (&acc)[2][2][4][2], const Unit& u, int wr, int wc, int fr, int fq, const EpiCtx& X) const {
;     ...
;             for (int m = 0; m < 4; ++m) {
;                 const int rl = ai * HALF + m * 16; const unsigned off = lo + (unsigned)(rl * 64) * 2u;
;                 const f32x4 o0a = acc[ai][0][m][0], o0b = acc[ai][0][m][1], o1a = acc[ai][1][m][0], o1b = acc[ai][1][m][1];
;                 const f32x4 ra_ = dpp_swap1(odd ? o0a : o1a), rb_ = dpp_swap1(odd ? o0b : o1b);
;                 const f32x4 pa[2] = {odd ? ra_ : o0a, odd ? o1a : ra_}, pb[2] = {odd ? rb_ : o0b, odd ? o1b : rb_};
; #pragma unroll
;                 for (int q = 0; q < 2; ++q) {
;                     const u32x4 w0 = raw[2 * m + q];
;                     const f32x4 r0 = (f32x4){bf_lo(w0.x), bf_hi(w0.x), bf_lo(w0.y), bf_hi(w0.y)}, r1 = (f32x4){bf_lo(w0.z), bf_hi(w0.z), bf_lo(w0.w), bf_hi(w0.w)};
;                     f32x4 y0, y1;
;                     if (RESN) { const f32x2 t = tbl[rl + q]; const float mu = t.x, ra = t.y * ALPHA; y0 = (r0 - mu) * ra * g0 + b0 + pa[q]; y1 = (r1 - mu) * ra * g1 + b1 + pb[q]; }
;                     else { y0 = r0 * ALPHA + pa[q]; y1 = r1 * ALPHA + pb[q]; }
;                     { const u32x4 w = pack8f(y0, y1); *(u32x4*)(xb + off + q * 128) = w;
;                         y0 = (f32x4){bf_lo(w.x), bf_hi(w.x), bf_lo(w.y), bf_hi(w.y)}; y1 = (f32x4){bf_lo(w.z), bf_hi(w.z), bf_lo(w.w), bf_hi(w.w)}; }
;                     float sa = ((y0[0] + y0[1]) + (y0[2] + y0[3])) + ((y1[0] + y1[1]) + (y1[2] + y1[3]));
;                     float sb = ((y0[0] * y0[0] + y0[1] * y0[1]) + (y0[2] * y0[2] + y0[3] * y0[3])) + ((y1[0] * y1[0] + y1[1] * y1[1]) + (y1[2] * y1[2] + y1[3] * y1[3]));
;                     sa += dpp_x1(sa);
;                     sb += dpp_x1(sb);
;                     sa += __shfl_xor(sa, 16); sa += __shfl_xor(sa, 32); sb += __shfl_xor(sb, 16); sb += __shfl_xor(sb, 32);
;                     if (fq == 0 && !odd) ps[(size_t)(rl + q) * 64] = (f32x2){sa, sb};
.LBB0_586:
	s_or_b64 exec, exec, s[52:53]
	s_waitcnt lgkmcnt(0)
	v_cndmask_b32_e64 v114, v108, v100, s[8:9]
	s_nop 0
	v_cndmask_b32_e64 v113, v109, v101, s[8:9]
	s_waitcnt lgkmcnt(0)
	v_cndmask_b32_e64 v115, v110, v102, s[8:9]
	v_mov_b32_dpp v112, v114 quad_perm:[1,0,3,2] row_mask:0xf bank_mask:0xf
	s_nop 0
	v_cndmask_b32_e64 v116, v111, v103, s[8:9]
	v_cndmask_b32_e64 v118, v104, v96, s[8:9]
	v_mov_b32_dpp v114, v113 quad_perm:[1,0,3,2] row_mask:0xf bank_mask:0xf
	s_nop 0
	v_cndmask_b32_e64 v117, v105, v97, s[8:9]
	v_cndmask_b32_e64 v119, v106, v98, s[8:9]
	v_mov_b32_dpp v113, v115 quad_perm:[1,0,3,2] row_mask:0xf bank_mask:0xf
	s_nop 0
	v_cndmask_b32_e64 v126, v107, v99, s[8:9]
	v_cndmask_b32_e64 v109, v114, v109, s[8:9]
	v_mov_b32_dpp v115, v116 quad_perm:[1,0,3,2] row_mask:0xf bank_mask:0xf
	s_nop 0
	v_cndmask_b32_e64 v108, v112, v108, s[8:9]
	v_cndmask_b32_e64 v111, v115, v111, s[8:9]
	v_mov_b32_dpp v116, v118 quad_perm:[1,0,3,2] row_mask:0xf bank_mask:0xf
	s_nop 0
	v_cndmask_b32_e64 v110, v113, v110, s[8:9]
	v_cndmask_b32_e64 v104, v116, v104, s[8:9]
	v_mov_b32_dpp v118, v117 quad_perm:[1,0,3,2] row_mask:0xf bank_mask:0xf
	s_nop 0
	v_cndmask_b32_e64 v105, v118, v105, s[8:9]
	s_waitcnt vmcnt(13)
	v_and_b32_e32 v127, 0xffff0000, v148
	v_mov_b32_dpp v117, v119 quad_perm:[1,0,3,2] row_mask:0xf bank_mask:0xf
	s_nop 0
	v_cndmask_b32_e64 v106, v117, v106, s[8:9]
	v_lshlrev_b32_e32 v128, 16, v149
	v_mov_b32_dpp v119, v126 quad_perm:[1,0,3,2] row_mask:0xf bank_mask:0xf
	v_cndmask_b32_e64 v107, v119, v107, s[8:9]
	v_lshlrev_b32_e32 v126, 16, v148
	v_and_b32_e32 v129, 0xffff0000, v149
	v_lshlrev_b32_e32 v148, 16, v150
	v_and_b32_e32 v149, 0xffff0000, v150
	v_lshlrev_b32_e32 v150, 16, v151
	v_and_b32_e32 v151, 0xffff0000, v151
	v_pk_fma_f32 v[110:111], v[128:129], s[18:19], v[110:111] op_sel_hi:[1,0,1]
	v_pk_fma_f32 v[108:109], v[126:127], s[18:19], v[108:109] op_sel_hi:[1,0,1]
	v_pk_fma_f32 v[106:107], v[150:151], s[18:19], v[106:107] op_sel_hi:[1,0,1]
	v_pk_fma_f32 v[104:105], v[148:149], s[18:19], v[104:105] op_sel_hi:[1,0,1]
	v_cvt_pk_bf16_f32 v126, v108, v109
	v_cvt_pk_bf16_f32 v127, v110, v111
	v_mov_b32_e32 v181, v165
	v_cvt_pk_bf16_f32 v128, v104, v105
	v_cvt_pk_bf16_f32 v129, v106, v107
	v_lshlrev_b32_e32 v104, 16, v126
	v_and_b32_e32 v106, 0xffff0000, v126
	v_lshlrev_b32_e32 v108, 16, v127
	v_and_b32_e32 v110, 0xffff0000, v127
	v_lshlrev_b32_e32 v148, 16, v128
	v_and_b32_e32 v150, 0xffff0000, v128
	v_lshlrev_b32_e32 v152, 16, v129
	v_and_b32_e32 v154, 0xffff0000, v129
	v_mul_f32_e32 v105, v104, v104
	v_mul_f32_e32 v107, v106, v106
	v_mul_f32_e32 v109, v108, v108
	v_mul_f32_e32 v111, v110, v110
	v_mul_f32_e32 v149, v148, v148
	v_mul_f32_e32 v151, v150, v150
	v_mul_f32_e32 v153, v152, v152
	v_mul_f32_e32 v155, v154, v154
	v_pk_add_f32 v[104:105], v[104:105], v[106:107]
	v_pk_add_f32 v[106:107], v[108:109], v[110:111]
	v_pk_add_f32 v[108:109], v[152:153], v[154:155]
	v_pk_add_f32 v[104:105], v[104:105], v[106:107]
	v_pk_add_f32 v[106:107], v[148:149], v[150:151]
	s_nop 0
	v_pk_add_f32 v[106:107], v[106:107], v[108:109]
	s_nop 0
	v_pk_add_f32 v[104:105], v[104:105], v[106:107]
	v_mov_b32_e32 v106, v165
	v_mov_b32_e32 v107, v165
	s_nop 0
	v_mov_b32_dpp v106, v104 quad_perm:[1,0,3,2] row_mask:0xf bank_mask:0xf
	v_mov_b32_dpp v107, v105 quad_perm:[1,0,3,2] row_mask:0xf bank_mask:0xf
	v_pk_add_f32 v[104:105], v[104:105], v[106:107]
	v_mov_b32_e32 v106, v104
	v_mov_b32_e32 v107, v105
	s_nop 1
	v_permlane16_swap_b32_e32 v104, v106
	v_permlane16_swap_b32_e32 v105, v107
	s_waitcnt lgkmcnt(0)
	v_pk_add_f32 v[106:107], v[104:105], v[106:107]
	v_mov_b32_e32 v108, v106
	v_mov_b32_e32 v109, v107
	s_nop 1
	v_permlane32_swap_b32_e32 v106, v108
	v_permlane32_swap_b32_e32 v107, v109
	v_lshl_add_u64 v[104:105], s[54:55], 0, v[180:181]
	global_store_dwordx4 v[104:105], v[126:129], off
	s_and_saveexec_b64 s[56:57], s[10:11]
	s_waitcnt lgkmcnt(0)
	v_pk_add_f32 v[106:107], v[106:107], v[108:109]
	v_add_co_u32_e32 v108, vcc, 0x2000, v124
	s_nop 1
	v_addc_co_u32_e32 v109, vcc, 0, v125, vcc
	global_store_dwordx2 v[108:109], v[106:107], off

; __device__ __forceinline__ u32x4 pack8f(f32x4 a, f32x4 b) { u32x4 w; w.x = cvt_pk_bf16(a[0], a[1]); w.y = cvt_pk_bf16(a[2], a[3]); w.z = cvt_pk_bf16(b[0], b[1]); w.w = cvt_pk_bf16(b[2], b[3]); return w; }
;     __device__ __forceinline__ void operator()(const f32x4 (&acc)[2][2][4][2], const Unit& u, int wr, int wc, int fr, int fq, const EpiCtx& X) const {
;     ...
;             for (int m = 0; m < 4; ++m) {
;                 const int rl = ai * HALF + m * 16; const unsigned off = lo + (unsigned)(rl * 64) * 2u;
;                 const f32x4 o0a = acc[ai][0][m][0], o0b = acc[ai][0][m][1], o1a = acc[ai][1][m][0], o1b = acc[ai][1][m][1];
;                 const f32x4 ra_ = dpp_swap1(odd ? o0a : o1a), rb_ = dpp_swap1(odd ? o0b : o1b);
;                 const f32x4 pa[2] = {odd ? ra_ : o0a, odd ? o1a : ra_}, pb[2] = {odd ? rb_ : o0b, odd ? o1b : rb_};
; #pragma unroll
;                 for (int q = 0; q < 2; ++q) {
;                     const u32x4 w0 = raw[2 * m + q];
;                     const f32x4 r0 = (f32x4){bf_lo(w0.x), bf_hi(w0.x), bf_lo(w0.y), bf_hi(w0.y)}, r1 = (f32x4){bf_lo(w0.z), bf_hi(w0.z), bf_lo(w0.w), bf_hi(w0.w)};
;                     f32x4 y0, y1;
;                     if (RESN) { const f32x2 t = tbl[rl + q]; const float mu = t.x, ra = t.y * ALPHA; y0 = (r0 - mu) * ra * g0 + b0 + pa[q]; y1 = (r1 - mu) * ra * g1 + b1 + pb[q]; }
;                     else { y0 = r0 * ALPHA + pa[q]; y1 = r1 * ALPHA + pb[q]; }
;                     { const u32x4 w = pack8f(y0, y1); *(u32x4*)(xb + off + q * 128) = w;
;                         y0 = (f32x4){bf_lo(w.x), bf_hi(w.x), bf_lo(w.y), bf_hi(w.y)}; y1 = (f32x4){bf_lo(w.z), bf_hi(w.z), bf_lo(w.w), bf_hi(w.w)}; }
;                     float sa = ((y0[0] + y0[1]) + (y0[2] + y0[3])) + ((y1[0] + y1[1]) + (y1[2] + y1[3]));
;                     float sb = ((y0[0] * y0[0] + y0[1] * y0[1]) + (y0[2] * y0[2] + y0[3] * y0[3])) + ((y1[0] * y1[0] + y1[1] * y1[1]) + (y1[2] * y1[2] + y1[3] * y1[3]));
;                     sa += dpp_x1(sa);
;                     sb += dpp_x1(sb);
;                     sa += __shfl_xor(sa, 16); sa += __shfl_xor(sa, 32); sb += __shfl_xor(sb, 16); sb += __shfl_xor(sb, 32);
;                     if (fq == 0 && !odd) ps[(size_t)(rl + q) * 64] = (f32x2){sa, sb};
.LBB0_590:
	s_or_b64 exec, exec, s[56:57]
	s_waitcnt lgkmcnt(0)
	v_cndmask_b32_e64 v98, v92, v84, s[8:9]
	s_nop 0
	v_cndmask_b32_e64 v97, v93, v85, s[8:9]
	s_waitcnt lgkmcnt(0)
	v_cndmask_b32_e64 v99, v94, v86, s[8:9]
	v_mov_b32_dpp v96, v98 quad_perm:[1,0,3,2] row_mask:0xf bank_mask:0xf
	s_nop 0
	v_cndmask_b32_e64 v100, v95, v87, s[8:9]
	v_cndmask_b32_e64 v102, v88, v80, s[8:9]
	v_mov_b32_dpp v98, v97 quad_perm:[1,0,3,2] row_mask:0xf bank_mask:0xf
	s_nop 0
	v_cndmask_b32_e64 v101, v89, v81, s[8:9]
	v_cndmask_b32_e64 v103, v90, v82, s[8:9]
	v_mov_b32_dpp v97, v99 quad_perm:[1,0,3,2] row_mask:0xf bank_mask:0xf
	s_nop 0
	v_cndmask_b32_e64 v104, v91, v83, s[8:9]
	v_cndmask_b32_e64 v93, v98, v93, s[8:9]
	v_mov_b32_dpp v99, v100 quad_perm:[1,0,3,2] row_mask:0xf bank_mask:0xf
	s_nop 0
	v_cndmask_b32_e64 v92, v96, v92, s[8:9]
	v_cndmask_b32_e64 v95, v99, v95, s[8:9]
	v_mov_b32_dpp v100, v102 quad_perm:[1,0,3,2] row_mask:0xf bank_mask:0xf
	s_nop 0
	v_cndmask_b32_e64 v94, v97, v94, s[8:9]
	v_cndmask_b32_e64 v88, v100, v88, s[8:9]
	v_mov_b32_dpp v102, v101 quad_perm:[1,0,3,2] row_mask:0xf bank_mask:0xf
	s_nop 0
	v_cndmask_b32_e64 v89, v102, v89, s[8:9]
	s_waitcnt vmcnt(15)
	v_and_b32_e32 v105, 0xffff0000, v140
	v_mov_b32_dpp v101, v103 quad_perm:[1,0,3,2] row_mask:0xf bank_mask:0xf
	s_nop 0
	v_cndmask_b32_e64 v90, v101, v90, s[8:9]
	v_lshlrev_b32_e32 v106, 16, v141
	v_mov_b32_dpp v103, v104 quad_perm:[1,0,3,2] row_mask:0xf bank_mask:0xf
	v_cndmask_b32_e64 v91, v103, v91, s[8:9]
	v_lshlrev_b32_e32 v104, 16, v140
	v_and_b32_e32 v107, 0xffff0000, v141
	v_lshlrev_b32_e32 v108, 16, v142
	v_and_b32_e32 v109, 0xffff0000, v142
	v_lshlrev_b32_e32 v110, 16, v143
	v_and_b32_e32 v111, 0xffff0000, v143
	v_pk_fma_f32 v[94:95], v[106:107], s[18:19], v[94:95] op_sel_hi:[1,0,1]
	v_pk_fma_f32 v[92:93], v[104:105], s[18:19], v[92:93] op_sel_hi:[1,0,1]
	v_pk_fma_f32 v[90:91], v[110:111], s[18:19], v[90:91] op_sel_hi:[1,0,1]
	v_pk_fma_f32 v[88:89], v[108:109], s[18:19], v[88:89] op_sel_hi:[1,0,1]
	v_cvt_pk_bf16_f32 v104, v92, v93
	v_cvt_pk_bf16_f32 v105, v94, v95
	v_mov_b32_e32 v179, v165
	v_cvt_pk_bf16_f32 v106, v88, v89
	v_cvt_pk_bf16_f32 v107, v90, v91
	v_lshlrev_b32_e32 v88, 16, v104
	v_and_b32_e32 v90, 0xffff0000, v104
	v_lshlrev_b32_e32 v92, 16, v105
	v_and_b32_e32 v94, 0xffff0000, v105
	v_lshlrev_b32_e32 v108, 16, v106
	v_and_b32_e32 v110, 0xffff0000, v106
	v_lshlrev_b32_e32 v112, 16, v107
	v_and_b32_e32 v114, 0xffff0000, v107
	v_mul_f32_e32 v89, v88, v88
	v_mul_f32_e32 v91, v90, v90
	v_mul_f32_e32 v93, v92, v92
	v_mul_f32_e32 v95, v94, v94
	v_mul_f32_e32 v109, v108, v108
	v_mul_f32_e32 v111, v110, v110
	v_mul_f32_e32 v113, v112, v112
	v_mul_f32_e32 v115, v114, v114
	v_pk_add_f32 v[88:89], v[88:89], v[90:91]
	v_pk_add_f32 v[90:91], v[92:93], v[94:95]
	v_pk_add_f32 v[92:93], v[112:113], v[114:115]
	v_pk_add_f32 v[88:89], v[88:89], v[90:91]
	v_pk_add_f32 v[90:91], v[108:109], v[110:111]
	s_nop 0
	v_pk_add_f32 v[90:91], v[90:91], v[92:93]
	s_nop 0
	v_pk_add_f32 v[88:89], v[88:89], v[90:91]
	v_mov_b32_e32 v90, v165
	v_mov_b32_e32 v91, v165
	s_nop 0
	v_mov_b32_dpp v90, v88 quad_perm:[1,0,3,2] row_mask:0xf bank_mask:0xf
	v_mov_b32_dpp v91, v89 quad_perm:[1,0,3,2] row_mask:0xf bank_mask:0xf
	v_pk_add_f32 v[88:89], v[88:89], v[90:91]
	v_mov_b32_e32 v90, v88
	v_mov_b32_e32 v91, v89
	s_nop 1
	v_permlane16_swap_b32_e32 v88, v90
	v_permlane16_swap_b32_e32 v89, v91
	s_waitcnt lgkmcnt(0)
	v_pk_add_f32 v[90:91], v[88:89], v[90:91]
	v_mov_b32_e32 v92, v90
	v_mov_b32_e32 v93, v91
	s_nop 1
	v_permlane32_swap_b32_e32 v90, v92
	v_permlane32_swap_b32_e32 v91, v93
	v_lshl_add_u64 v[88:89], s[54:55], 0, v[178:179]
	global_store_dwordx4 v[88:89], v[104:107], off
	s_and_saveexec_b64 s[56:57], s[10:11]
	s_waitcnt lgkmcnt(0)
	v_pk_add_f32 v[90:91], v[90:91], v[92:93]
	v_add_co_u32_e32 v92, vcc, 0x4000, v124
	s_nop 1
	v_addc_co_u32_e32 v93, vcc, 0, v125, vcc
	global_store_dwordx2 v[92:93], v[90:91], off

; __device__ __forceinline__ u32x4 pack8f(f32x4 a, f32x4 b) { u32x4 w; w.x = cvt_pk_bf16(a[0], a[1]); w.y = cvt_pk_bf16(a[2], a[3]); w.z = cvt_pk_bf16(b[0], b[1]); w.w = cvt_pk_bf16(b[2], b[3]); return w; }
;     __device__ __forceinline__ void operator()(const f32x4 (&acc)[2][2][4][2], const Unit& u, int wr, int wc, int fr, int fq, const EpiCtx& X) const {
;     ...
;             for (int m = 0; m < 4; ++m) {
;                 const int rl = ai * HALF + m * 16; const unsigned off = lo + (unsigned)(rl * 64) * 2u;
;                 const f32x4 o0a = acc[ai][0][m][0], o0b = acc[ai][0][m][1], o1a = acc[ai][1][m][0], o1b = acc[ai][1][m][1];
;                 const f32x4 ra_ = dpp_swap1(odd ? o0a : o1a), rb_ = dpp_swap1(odd ? o0b : o1b);
;                 const f32x4 pa[2] = {odd ? ra_ : o0a, odd ? o1a : ra_}, pb[2] = {odd ? rb_ : o0b, odd ? o1b : rb_};
; #pragma unroll
;                 for (int q = 0; q < 2; ++q) {
;                     const u32x4 w0 = raw[2 * m + q];
;                     const f32x4 r0 = (f32x4){bf_lo(w0.x), bf_hi(w0.x), bf_lo(w0.y), bf_hi(w0.y)}, r1 = (f32x4){bf_lo(w0.z), bf_hi(w0.z), bf_lo(w0.w), bf_hi(w0.w)};
;                     f32x4 y0, y1;
;                     if (RESN) { const f32x2 t = tbl[rl + q]; const float mu = t.x, ra = t.y * ALPHA; y0 = (r0 - mu) * ra * g0 + b0 + pa[q]; y1 = (r1 - mu) * ra * g1 + b1 + pb[q]; }
;                     else { y0 = r0 * ALPHA + pa[q]; y1 = r1 * ALPHA + pb[q]; }
;                     { const u32x4 w = pack8f(y0, y1); *(u32x4*)(xb + off + q * 128) = w;
;                         y0 = (f32x4){bf_lo(w.x), bf_hi(w.x), bf_lo(w.y), bf_hi(w.y)}; y1 = (f32x4){bf_lo(w.z), bf_hi(w.z), bf_lo(w.w), bf_hi(w.w)}; }
;                     float sa = ((y0[0] + y0[1]) + (y0[2] + y0[3])) + ((y1[0] + y1[1]) + (y1[2] + y1[3]));
;                     float sb = ((y0[0] * y0[0] + y0[1] * y0[1]) + (y0[2] * y0[2] + y0[3] * y0[3])) + ((y1[0] * y1[0] + y1[1] * y1[1]) + (y1[2] * y1[2] + y1[3] * y1[3]));
;                     sa += dpp_x1(sa);
;                     sb += dpp_x1(sb);
;                     sa += __shfl_xor(sa, 16); sa += __shfl_xor(sa, 32); sb += __shfl_xor(sb, 16); sb += __shfl_xor(sb, 32);
;                     if (fq == 0 && !odd) ps[(size_t)(rl + q) * 64] = (f32x2){sa, sb};
.LBB0_594:
	s_or_b64 exec, exec, s[56:57]
	s_waitcnt lgkmcnt(0)
	v_cndmask_b32_e64 v82, v76, v68, s[8:9]
	s_nop 0
	v_cndmask_b32_e64 v81, v77, v69, s[8:9]
	s_waitcnt lgkmcnt(0)
	v_cndmask_b32_e64 v83, v78, v70, s[8:9]
	v_mov_b32_dpp v80, v82 quad_perm:[1,0,3,2] row_mask:0xf bank_mask:0xf
	s_nop 0
	v_cndmask_b32_e64 v84, v79, v71, s[8:9]
	v_cndmask_b32_e64 v86, v72, v64, s[8:9]
	v_mov_b32_dpp v82, v81 quad_perm:[1,0,3,2] row_mask:0xf bank_mask:0xf
	s_nop 0
	v_cndmask_b32_e64 v85, v73, v65, s[8:9]
	v_cndmask_b32_e64 v87, v74, v66, s[8:9]
	v_mov_b32_dpp v81, v83 quad_perm:[1,0,3,2] row_mask:0xf bank_mask:0xf
	s_nop 0
	v_cndmask_b32_e64 v88, v75, v67, s[8:9]
	v_cndmask_b32_e64 v77, v82, v77, s[8:9]
	v_mov_b32_dpp v83, v84 quad_perm:[1,0,3,2] row_mask:0xf bank_mask:0xf
	s_nop 0
	v_cndmask_b32_e64 v76, v80, v76, s[8:9]
	v_cndmask_b32_e64 v79, v83, v79, s[8:9]
	v_mov_b32_dpp v84, v86 quad_perm:[1,0,3,2] row_mask:0xf bank_mask:0xf
	s_nop 0
	v_cndmask_b32_e64 v78, v81, v78, s[8:9]
	v_cndmask_b32_e64 v72, v84, v72, s[8:9]
	v_mov_b32_dpp v86, v85 quad_perm:[1,0,3,2] row_mask:0xf bank_mask:0xf
	s_nop 0
	v_cndmask_b32_e64 v73, v86, v73, s[8:9]
	s_waitcnt vmcnt(17)
	v_and_b32_e32 v89, 0xffff0000, v132
	v_mov_b32_dpp v85, v87 quad_perm:[1,0,3,2] row_mask:0xf bank_mask:0xf
	s_nop 0
	v_cndmask_b32_e64 v74, v85, v74, s[8:9]
	v_lshlrev_b32_e32 v90, 16, v133
	v_mov_b32_dpp v87, v88 quad_perm:[1,0,3,2] row_mask:0xf bank_mask:0xf
	v_cndmask_b32_e64 v75, v87, v75, s[8:9]
	v_lshlrev_b32_e32 v88, 16, v132
	v_and_b32_e32 v91, 0xffff0000, v133
	v_lshlrev_b32_e32 v92, 16, v134
	v_and_b32_e32 v93, 0xffff0000, v134
	v_lshlrev_b32_e32 v94, 16, v135
	v_and_b32_e32 v95, 0xffff0000, v135
	v_pk_fma_f32 v[78:79], v[90:91], s[18:19], v[78:79] op_sel_hi:[1,0,1]
	v_pk_fma_f32 v[76:77], v[88:89], s[18:19], v[76:77] op_sel_hi:[1,0,1]
	v_pk_fma_f32 v[74:75], v[94:95], s[18:19], v[74:75] op_sel_hi:[1,0,1]
	v_pk_fma_f32 v[72:73], v[92:93], s[18:19], v[72:73] op_sel_hi:[1,0,1]
	v_cvt_pk_bf16_f32 v88, v76, v77
	v_cvt_pk_bf16_f32 v89, v78, v79
	v_mov_b32_e32 v177, v165
	v_cvt_pk_bf16_f32 v90, v72, v73
	v_cvt_pk_bf16_f32 v91, v74, v75
	v_lshlrev_b32_e32 v72, 16, v88
	v_and_b32_e32 v74, 0xffff0000, v88
	v_lshlrev_b32_e32 v76, 16, v89
	v_and_b32_e32 v78, 0xffff0000, v89
	v_lshlrev_b32_e32 v92, 16, v90
	v_and_b32_e32 v94, 0xffff0000, v90
	v_lshlrev_b32_e32 v96, 16, v91
	v_and_b32_e32 v98, 0xffff0000, v91
	v_mul_f32_e32 v73, v72, v72
	v_mul_f32_e32 v75, v74, v74
	v_mul_f32_e32 v77, v76, v76
	v_mul_f32_e32 v79, v78, v78
	v_mul_f32_e32 v93, v92, v92
	v_mul_f32_e32 v95, v94, v94
	v_mul_f32_e32 v97, v96, v96
	v_mul_f32_e32 v99, v98, v98
	v_pk_add_f32 v[72:73], v[72:73], v[74:75]
	v_pk_add_f32 v[74:75], v[76:77], v[78:79]
	v_pk_add_f32 v[76:77], v[96:97], v[98:99]
	v_pk_add_f32 v[72:73], v[72:73], v[74:75]
	v_pk_add_f32 v[74:75], v[92:93], v[94:95]
	s_nop 0
	v_pk_add_f32 v[74:75], v[74:75], v[76:77]
	s_nop 0
	v_pk_add_f32 v[72:73], v[72:73], v[74:75]
	v_mov_b32_e32 v74, v165
	v_mov_b32_e32 v75, v165
	s_nop 0
	v_mov_b32_dpp v74, v72 quad_perm:[1,0,3,2] row_mask:0xf bank_mask:0xf
	v_mov_b32_dpp v75, v73 quad_perm:[1,0,3,2] row_mask:0xf bank_mask:0xf
	v_pk_add_f32 v[72:73], v[72:73], v[74:75]
	v_mov_b32_e32 v74, v72
	v_mov_b32_e32 v75, v73
	s_nop 1
	v_permlane16_swap_b32_e32 v72, v74
	v_permlane16_swap_b32_e32 v73, v75
	s_waitcnt lgkmcnt(0)
	v_pk_add_f32 v[74:75], v[72:73], v[74:75]
	v_mov_b32_e32 v76, v74
	v_mov_b32_e32 v77, v75
	s_nop 1
	v_permlane32_swap_b32_e32 v74, v76
	v_permlane32_swap_b32_e32 v75, v77
	v_lshl_add_u64 v[72:73], s[54:55], 0, v[176:177]
	global_store_dwordx4 v[72:73], v[88:91], off
	s_and_saveexec_b64 s[56:57], s[10:11]
	s_waitcnt lgkmcnt(0)
	v_pk_add_f32 v[74:75], v[74:75], v[76:77]
	v_add_co_u32_e32 v76, vcc, 0x6000, v124
	s_nop 1
	v_addc_co_u32_e32 v77, vcc, 0, v125, vcc
	global_store_dwordx2 v[76:77], v[74:75], off

;     __device__ __forceinline__ void operator()(const f32x4 (&acc)[2][2][4][2], const Unit& u, int wr, int wc, int fr, int fq, const EpiCtx& X) const {
;     ...
;             for (int m = 0; m < 4; ++m) { const unsigned off = lo + (unsigned)((ai * HALF + m * 16) * 64) * 2u; raw[2 * m] = *(const u32x4*)(xb + off); raw[2 * m + 1] = *(const u32x4*)(xb + off + 128); }
; #pragma unroll
;             for (int m = 0; m < 4; ++m) {
;                 const int rl = ai * HALF + m * 16; const unsigned off = lo + (unsigned)(rl * 64) * 2u;
;                 const f32x4 o0a = acc[ai][0][m][0], o0b = acc[ai][0][m][1], o1a = acc[ai][1][m][0], o1b = acc[ai][1][m][1];
;                 const f32x4 ra_ = dpp_swap1(odd ? o0a : o1a), rb_ = dpp_swap1(odd ? o0b : o1b);
;                 const f32x4 pa[2] = {odd ? ra_ : o0a, odd ? o1a : ra_}, pb[2] = {odd ? rb_ : o0b, odd ? o1b : rb_};
; #pragma unroll
;                 for (int q = 0; q < 2; ++q) {
;                     const u32x4 w0 = raw[2 * m + q];
;                     const f32x4 r0 = (f32x4){bf_lo(w0.x), bf_hi(w0.x), bf_lo(w0.y), bf_hi(w0.y)}, r1 = (f32x4){bf_lo(w0.z), bf_hi(w0.z), bf_lo(w0.w), bf_hi(w0.w)};
;                     f32x4 y0, y1;
;                     if (RESN) { const f32x2 t = tbl[rl + q]; const float mu = t.x, ra = t.y * ALPHA; y0 = (r0 - mu) * ra * g0 + b0 + pa[q]; y1 = (r1 - mu) * ra * g1 + b1 + pb[q]; }
;                     else { y0 = r0 * ALPHA + pa[q]; y1 = r1 * ALPHA + pb[q]; }
;                     { const u32x4 w = pack8f(y0, y1); *(u32x4*)(xb + off + q * 128) = w;
;                         y0 = (f32x4){bf_lo(w.x), bf_hi(w.x), bf_lo(w.y), bf_hi(w.y)}; y1 = (f32x4){bf_lo(w.z), bf_hi(w.z), bf_lo(w.w), bf_hi(w.w)}; }
;                     float sa = ((y0[0] + y0[1]) + (y0[2] + y0[3])) + ((y1[0] + y1[1]) + (y1[2] + y1[3]));
;                     float sb = ((y0[0] * y0[0] + y0[1] * y0[1]) + (y0[2] * y0[2] + y0[3] * y0[3])) + ((y1[0] * y1[0] + y1[1] * y1[1]) + (y1[2] * y1[2] + y1[3] * y1[3]));
;                     sa += dpp_x1(sa);
;                     sb += dpp_x1(sb);
;                     sa += __shfl_xor(sa, 16); sa += __shfl_xor(sa, 32); sb += __shfl_xor(sb, 16); sb += __shfl_xor(sb, 32);
;                     if (fq == 0 && !odd) ps[(size_t)(rl + q) * 64] = (f32x2){sa, sb};
.LBB0_598:
	s_or_b64 exec, exec, s[56:57]
	v_add_u32_e32 v96, 0x4000, v164
	s_waitcnt vmcnt(16)
	v_mov_b32_e32 v104, v230
	v_mov_b32_e32 v105, v231
	v_mov_b32_e32 v106, v232
	v_mov_b32_e32 v107, v233
	v_add_u32_e32 v94, 0x4800, v164
	v_add_u32_e32 v92, 0x5000, v164
	v_add_u32_e32 v164, 0x5800, v164
	v_mov_b32_e32 v88, v234
	v_mov_b32_e32 v89, v235
	v_mov_b32_e32 v90, v236
	v_mov_b32_e32 v91, v237
	v_mov_b32_e32 v84, v238
	v_mov_b32_e32 v85, v239
	v_mov_b32_e32 v86, v240
	v_mov_b32_e32 v87, v241
	v_mov_b32_e32 v80, v242
	v_mov_b32_e32 v81, v243
	v_mov_b32_e32 v82, v244
	v_mov_b32_e32 v83, v245
	global_load_dwordx4 v[76:79], v92, s[54:55]
	global_load_dwordx4 v[72:75], v92, s[54:55] offset:128
	global_load_dwordx4 v[68:71], v164, s[54:55]
	s_waitcnt lgkmcnt(0)
	global_load_dwordx4 v[64:67], v164, s[54:55] offset:128
	v_cndmask_b32_e64 v103, v63, v55, s[8:9]
	v_cndmask_b32_e64 v110, v62, v54, s[8:9]
	v_cndmask_b32_e64 v111, v61, v53, s[8:9]
	v_cndmask_b32_e64 v112, v60, v52, s[8:9]
	s_nop 0
	s_nop 0
	s_nop 0
	s_nop 0
	v_cndmask_b32_e64 v113, v59, v51, s[8:9]
	v_cndmask_b32_e64 v114, v58, v50, s[8:9]
	v_cndmask_b32_e64 v115, v57, v49, s[8:9]
	v_cndmask_b32_e64 v116, v56, v48, s[8:9]
	s_nop 0
	s_nop 0
	s_nop 0
	s_nop 0
	v_mov_b32_dpp v93, v112 quad_perm:[1,0,3,2] row_mask:0xf bank_mask:0xf
	v_mov_b32_dpp v97, v111 quad_perm:[1,0,3,2] row_mask:0xf bank_mask:0xf
	v_mov_b32_dpp v95, v110 quad_perm:[1,0,3,2] row_mask:0xf bank_mask:0xf
	v_mov_b32_dpp v98, v103 quad_perm:[1,0,3,2] row_mask:0xf bank_mask:0xf
	v_mov_b32_dpp v99, v116 quad_perm:[1,0,3,2] row_mask:0xf bank_mask:0xf
	v_mov_b32_dpp v101, v115 quad_perm:[1,0,3,2] row_mask:0xf bank_mask:0xf
	v_mov_b32_dpp v100, v114 quad_perm:[1,0,3,2] row_mask:0xf bank_mask:0xf
	v_mov_b32_dpp v102, v113 quad_perm:[1,0,3,2] row_mask:0xf bank_mask:0xf
	v_cndmask_b32_e64 v61, v97, v61, s[8:9]
	v_cndmask_b32_e64 v60, v93, v60, s[8:9]
	v_cndmask_b32_e64 v63, v98, v63, s[8:9]
	v_cndmask_b32_e64 v62, v95, v62, s[8:9]
	v_cndmask_b32_e64 v57, v101, v57, s[8:9]
	v_cndmask_b32_e64 v56, v99, v56, s[8:9]
	v_cndmask_b32_e64 v59, v102, v59, s[8:9]
	v_cndmask_b32_e64 v58, v100, v58, s[8:9]
	v_mov_b32_e32 v108, v165
	v_mov_b32_e32 v109, v165
	v_lshlrev_b32_e32 v110, 16, v104
	v_and_b32_e32 v111, 0xffff0000, v104
	v_lshlrev_b32_e32 v104, 16, v105
	v_and_b32_e32 v105, 0xffff0000, v105
	v_lshlrev_b32_e32 v112, 16, v106
	v_and_b32_e32 v113, 0xffff0000, v106
	v_lshlrev_b32_e32 v106, 16, v107
	v_and_b32_e32 v107, 0xffff0000, v107
	v_pk_fma_f32 v[62:63], v[104:105], s[18:19], v[62:63] op_sel_hi:[1,0,1]
	v_pk_fma_f32 v[60:61], v[110:111], s[18:19], v[60:61] op_sel_hi:[1,0,1]
	v_pk_fma_f32 v[58:59], v[106:107], s[18:19], v[58:59] op_sel_hi:[1,0,1]
	v_pk_fma_f32 v[56:57], v[112:113], s[18:19], v[56:57] op_sel_hi:[1,0,1]
	v_cvt_pk_bf16_f32 v60, v60, v61
	v_cvt_pk_bf16_f32 v61, v62, v63
	s_nop 0
	v_cvt_pk_bf16_f32 v62, v56, v57
	v_cvt_pk_bf16_f32 v63, v58, v59
	v_lshlrev_b32_e32 v56, 16, v60
	v_and_b32_e32 v58, 0xffff0000, v60
	v_lshlrev_b32_e32 v104, 16, v61
	v_and_b32_e32 v106, 0xffff0000, v61
	v_lshlrev_b32_e32 v110, 16, v62
	v_and_b32_e32 v112, 0xffff0000, v62
	v_lshlrev_b32_e32 v114, 16, v63
	v_and_b32_e32 v116, 0xffff0000, v63
	v_mul_f32_e32 v57, v56, v56
	v_mul_f32_e32 v59, v58, v58
	v_mul_f32_e32 v105, v104, v104
	v_mul_f32_e32 v107, v106, v106
	v_mul_f32_e32 v111, v110, v110
	v_mul_f32_e32 v113, v112, v112
	v_mul_f32_e32 v115, v114, v114
	v_mul_f32_e32 v117, v116, v116
	v_pk_add_f32 v[56:57], v[56:57], v[58:59]
	v_pk_add_f32 v[58:59], v[104:105], v[106:107]
	v_pk_add_f32 v[104:105], v[110:111], v[112:113]
	v_pk_add_f32 v[106:107], v[114:115], v[116:117]
	v_pk_add_f32 v[56:57], v[56:57], v[58:59]
	v_pk_add_f32 v[58:59], v[104:105], v[106:107]
	global_store_dwordx4 v96, v[60:63], s[54:55]
	v_pk_add_f32 v[56:57], v[56:57], v[58:59]
	s_nop 1
	v_mov_b32_dpp v108, v56 quad_perm:[1,0,3,2] row_mask:0xf bank_mask:0xf
	v_mov_b32_dpp v109, v57 quad_perm:[1,0,3,2] row_mask:0xf bank_mask:0xf
	v_pk_add_f32 v[56:57], v[56:57], v[108:109]
	v_mov_b32_e32 v58, v56
	v_mov_b32_e32 v59, v57
	s_nop 1
	v_permlane16_swap_b32_e32 v56, v58
	v_permlane16_swap_b32_e32 v57, v59
	s_waitcnt lgkmcnt(0)
	v_pk_add_f32 v[56:57], v[56:57], v[58:59]
	v_mov_b32_e32 v58, v56
	v_mov_b32_e32 v59, v57
	s_nop 1
	v_permlane32_swap_b32_e32 v56, v58
	v_permlane32_swap_b32_e32 v57, v59
	s_and_saveexec_b64 s[56:57], s[10:11]
	s_cbranch_execz .LBB0_600
	s_waitcnt lgkmcnt(0)
	v_pk_add_f32 v[56:57], v[56:57], v[58:59]
	v_add_co_u32_e32 v58, vcc, 0x10000, v124
	s_nop 1
	v_addc_co_u32_e32 v59, vcc, 0, v125, vcc
	global_store_dwordx2 v[58:59], v[56:57], off

; __device__ __forceinline__ u32x4 pack8f(f32x4 a, f32x4 b) { u32x4 w; w.x = cvt_pk_bf16(a[0], a[1]); w.y = cvt_pk_bf16(a[2], a[3]); w.z = cvt_pk_bf16(b[0], b[1]); w.w = cvt_pk_bf16(b[2], b[3]); return w; }
;     __device__ __forceinline__ void operator()(const f32x4 (&acc)[2][2][4][2], const Unit& u, int wr, int wc, int fr, int fq, const EpiCtx& X) const {
;     ...
;             for (int m = 0; m < 4; ++m) {
;                 const int rl = ai * HALF + m * 16; const unsigned off = lo + (unsigned)(rl * 64) * 2u;
;                 const f32x4 o0a = acc[ai][0][m][0], o0b = acc[ai][0][m][1], o1a = acc[ai][1][m][0], o1b = acc[ai][1][m][1];
;                 const f32x4 ra_ = dpp_swap1(odd ? o0a : o1a), rb_ = dpp_swap1(odd ? o0b : o1b);
;                 const f32x4 pa[2] = {odd ? ra_ : o0a, odd ? o1a : ra_}, pb[2] = {odd ? rb_ : o0b, odd ? o1b : rb_};
; #pragma unroll
;                 for (int q = 0; q < 2; ++q) {
;                     const u32x4 w0 = raw[2 * m + q];
;                     const f32x4 r0 = (f32x4){bf_lo(w0.x), bf_hi(w0.x), bf_lo(w0.y), bf_hi(w0.y)}, r1 = (f32x4){bf_lo(w0.z), bf_hi(w0.z), bf_lo(w0.w), bf_hi(w0.w)};
;                     f32x4 y0, y1;
;                     if (RESN) { const f32x2 t = tbl[rl + q]; const float mu = t.x, ra = t.y * ALPHA; y0 = (r0 - mu) * ra * g0 + b0 + pa[q]; y1 = (r1 - mu) * ra * g1 + b1 + pb[q]; }
;                     else { y0 = r0 * ALPHA + pa[q]; y1 = r1 * ALPHA + pb[q]; }
;                     { const u32x4 w = pack8f(y0, y1); *(u32x4*)(xb + off + q * 128) = w;
;                         y0 = (f32x4){bf_lo(w.x), bf_hi(w.x), bf_lo(w.y), bf_hi(w.y)}; y1 = (f32x4){bf_lo(w.z), bf_hi(w.z), bf_lo(w.w), bf_hi(w.w)}; }
;                     float sa = ((y0[0] + y0[1]) + (y0[2] + y0[3])) + ((y1[0] + y1[1]) + (y1[2] + y1[3]));
;                     float sb = ((y0[0] * y0[0] + y0[1] * y0[1]) + (y0[2] * y0[2] + y0[3] * y0[3])) + ((y1[0] * y1[0] + y1[1] * y1[1]) + (y1[2] * y1[2] + y1[3] * y1[3]));
;                     sa += dpp_x1(sa);
;                     sb += dpp_x1(sb);
;                     sa += __shfl_xor(sa, 16); sa += __shfl_xor(sa, 32); sb += __shfl_xor(sb, 16); sb += __shfl_xor(sb, 32);
;                     if (fq == 0 && !odd) ps[(size_t)(rl + q) * 64] = (f32x2){sa, sb};
.LBB0_602:
	s_or_b64 exec, exec, s[56:57]
	s_waitcnt lgkmcnt(0)
	v_cndmask_b32_e64 v50, v44, v36, s[8:9]
	s_nop 0
	v_cndmask_b32_e64 v49, v45, v37, s[8:9]
	s_waitcnt lgkmcnt(0)
	v_cndmask_b32_e64 v51, v46, v38, s[8:9]
	v_mov_b32_dpp v48, v50 quad_perm:[1,0,3,2] row_mask:0xf bank_mask:0xf
	s_nop 0
	v_cndmask_b32_e64 v52, v47, v39, s[8:9]
	v_cndmask_b32_e64 v54, v40, v32, s[8:9]
	v_mov_b32_dpp v50, v49 quad_perm:[1,0,3,2] row_mask:0xf bank_mask:0xf
	s_nop 0
	v_cndmask_b32_e64 v53, v41, v33, s[8:9]
	v_cndmask_b32_e64 v55, v42, v34, s[8:9]
	v_mov_b32_dpp v49, v51 quad_perm:[1,0,3,2] row_mask:0xf bank_mask:0xf
	s_nop 0
	v_cndmask_b32_e64 v56, v43, v35, s[8:9]
	v_cndmask_b32_e64 v45, v50, v45, s[8:9]
	v_mov_b32_dpp v51, v52 quad_perm:[1,0,3,2] row_mask:0xf bank_mask:0xf
	s_nop 0
	v_cndmask_b32_e64 v44, v48, v44, s[8:9]
	v_cndmask_b32_e64 v47, v51, v47, s[8:9]
	v_mov_b32_dpp v52, v54 quad_perm:[1,0,3,2] row_mask:0xf bank_mask:0xf
	s_nop 0
	v_cndmask_b32_e64 v46, v49, v46, s[8:9]
	v_cndmask_b32_e64 v40, v52, v40, s[8:9]
	v_mov_b32_dpp v54, v53 quad_perm:[1,0,3,2] row_mask:0xf bank_mask:0xf
	s_nop 0
	v_cndmask_b32_e64 v41, v54, v41, s[8:9]
	v_and_b32_e32 v57, 0xffff0000, v84
	v_mov_b32_dpp v53, v55 quad_perm:[1,0,3,2] row_mask:0xf bank_mask:0xf
	s_nop 0
	v_cndmask_b32_e64 v42, v53, v42, s[8:9]
	v_lshlrev_b32_e32 v58, 16, v85
	v_mov_b32_dpp v55, v56 quad_perm:[1,0,3,2] row_mask:0xf bank_mask:0xf
	v_cndmask_b32_e64 v43, v55, v43, s[8:9]
	v_lshlrev_b32_e32 v56, 16, v84
	v_and_b32_e32 v59, 0xffff0000, v85
	v_lshlrev_b32_e32 v60, 16, v86
	v_and_b32_e32 v61, 0xffff0000, v86
	v_lshlrev_b32_e32 v62, 16, v87
	v_and_b32_e32 v63, 0xffff0000, v87
	v_pk_fma_f32 v[46:47], v[58:59], s[18:19], v[46:47] op_sel_hi:[1,0,1]
	v_pk_fma_f32 v[44:45], v[56:57], s[18:19], v[44:45] op_sel_hi:[1,0,1]
	v_pk_fma_f32 v[42:43], v[62:63], s[18:19], v[42:43] op_sel_hi:[1,0,1]
	v_pk_fma_f32 v[40:41], v[60:61], s[18:19], v[40:41] op_sel_hi:[1,0,1]
	v_cvt_pk_bf16_f32 v56, v44, v45
	v_cvt_pk_bf16_f32 v57, v46, v47
	v_mov_b32_e32 v95, v165
	v_cvt_pk_bf16_f32 v58, v40, v41
	v_cvt_pk_bf16_f32 v59, v42, v43
	v_lshlrev_b32_e32 v40, 16, v56
	v_and_b32_e32 v42, 0xffff0000, v56
	v_lshlrev_b32_e32 v44, 16, v57
	v_and_b32_e32 v46, 0xffff0000, v57
	v_lshlrev_b32_e32 v60, 16, v58
	v_and_b32_e32 v62, 0xffff0000, v58
	v_lshlrev_b32_e32 v84, 16, v59
	v_and_b32_e32 v86, 0xffff0000, v59
	v_mul_f32_e32 v41, v40, v40
	v_mul_f32_e32 v43, v42, v42
	v_mul_f32_e32 v45, v44, v44
	v_mul_f32_e32 v47, v46, v46
	v_mul_f32_e32 v61, v60, v60
	v_mul_f32_e32 v63, v62, v62
	v_mul_f32_e32 v85, v84, v84
	v_mul_f32_e32 v87, v86, v86
	v_pk_add_f32 v[40:41], v[40:41], v[42:43]
	v_pk_add_f32 v[42:43], v[44:45], v[46:47]
	v_pk_add_f32 v[44:45], v[84:85], v[86:87]
	v_pk_add_f32 v[40:41], v[40:41], v[42:43]
	v_pk_add_f32 v[42:43], v[60:61], v[62:63]
	s_nop 0
	v_pk_add_f32 v[42:43], v[42:43], v[44:45]
	s_nop 0
	v_pk_add_f32 v[40:41], v[40:41], v[42:43]
	v_mov_b32_e32 v42, v165
	v_mov_b32_e32 v43, v165
	s_nop 0
	v_mov_b32_dpp v42, v40 quad_perm:[1,0,3,2] row_mask:0xf bank_mask:0xf
	v_mov_b32_dpp v43, v41 quad_perm:[1,0,3,2] row_mask:0xf bank_mask:0xf
	v_pk_add_f32 v[40:41], v[40:41], v[42:43]
	v_mov_b32_e32 v42, v40
	v_mov_b32_e32 v43, v41
	s_nop 1
	v_permlane16_swap_b32_e32 v40, v42
	v_permlane16_swap_b32_e32 v41, v43
	s_waitcnt lgkmcnt(0)
	v_pk_add_f32 v[42:43], v[40:41], v[42:43]
	v_mov_b32_e32 v44, v42
	v_mov_b32_e32 v45, v43
	s_nop 1
	v_permlane32_swap_b32_e32 v42, v44
	v_permlane32_swap_b32_e32 v43, v45
	v_lshl_add_u64 v[40:41], s[54:55], 0, v[94:95]
	global_store_dwordx4 v[40:41], v[56:59], off
	s_and_saveexec_b64 s[56:57], s[10:11]
	s_cbranch_execz .LBB0_604
	s_waitcnt lgkmcnt(0)
	v_pk_add_f32 v[42:43], v[42:43], v[44:45]
	v_add_co_u32_e32 v44, vcc, 0x12000, v124
	s_nop 1
	v_addc_co_u32_e32 v45, vcc, 0, v125, vcc
	global_store_dwordx2 v[44:45], v[42:43], off

; __device__ __forceinline__ u32x4 pack8f(f32x4 a, f32x4 b) { u32x4 w; w.x = cvt_pk_bf16(a[0], a[1]); w.y = cvt_pk_bf16(a[2], a[3]); w.z = cvt_pk_bf16(b[0], b[1]); w.w = cvt_pk_bf16(b[2], b[3]); return w; }
;     __device__ __forceinline__ void operator()(const f32x4 (&acc)[2][2][4][2], const Unit& u, int wr, int wc, int fr, int fq, const EpiCtx& X) const {
;     ...
;             for (int m = 0; m < 4; ++m) {
;                 const int rl = ai * HALF + m * 16; const unsigned off = lo + (unsigned)(rl * 64) * 2u;
;                 const f32x4 o0a = acc[ai][0][m][0], o0b = acc[ai][0][m][1], o1a = acc[ai][1][m][0], o1b = acc[ai][1][m][1];
;                 const f32x4 ra_ = dpp_swap1(odd ? o0a : o1a), rb_ = dpp_swap1(odd ? o0b : o1b);
;                 const f32x4 pa[2] = {odd ? ra_ : o0a, odd ? o1a : ra_}, pb[2] = {odd ? rb_ : o0b, odd ? o1b : rb_};
; #pragma unroll
;                 for (int q = 0; q < 2; ++q) {
;                     const u32x4 w0 = raw[2 * m + q];
;                     const f32x4 r0 = (f32x4){bf_lo(w0.x), bf_hi(w0.x), bf_lo(w0.y), bf_hi(w0.y)}, r1 = (f32x4){bf_lo(w0.z), bf_hi(w0.z), bf_lo(w0.w), bf_hi(w0.w)};
;                     f32x4 y0, y1;
;                     if (RESN) { const f32x2 t = tbl[rl + q]; const float mu = t.x, ra = t.y * ALPHA; y0 = (r0 - mu) * ra * g0 + b0 + pa[q]; y1 = (r1 - mu) * ra * g1 + b1 + pb[q]; }
;                     else { y0 = r0 * ALPHA + pa[q]; y1 = r1 * ALPHA + pb[q]; }
;                     { const u32x4 w = pack8f(y0, y1); *(u32x4*)(xb + off + q * 128) = w;
;                         y0 = (f32x4){bf_lo(w.x), bf_hi(w.x), bf_lo(w.y), bf_hi(w.y)}; y1 = (f32x4){bf_lo(w.z), bf_hi(w.z), bf_lo(w.w), bf_hi(w.w)}; }
;                     float sa = ((y0[0] + y0[1]) + (y0[2] + y0[3])) + ((y1[0] + y1[1]) + (y1[2] + y1[3]));
;                     float sb = ((y0[0] * y0[0] + y0[1] * y0[1]) + (y0[2] * y0[2] + y0[3] * y0[3])) + ((y1[0] * y1[0] + y1[1] * y1[1]) + (y1[2] * y1[2] + y1[3] * y1[3]));
;                     sa += dpp_x1(sa);
;                     sb += dpp_x1(sb);
;                     sa += __shfl_xor(sa, 16); sa += __shfl_xor(sa, 32); sb += __shfl_xor(sb, 16); sb += __shfl_xor(sb, 32);
;                     if (fq == 0 && !odd) ps[(size_t)(rl + q) * 64] = (f32x2){sa, sb};
.LBB0_606:
	s_or_b64 exec, exec, s[56:57]
	s_waitcnt lgkmcnt(0)
	v_cndmask_b32_e64 v34, v28, v20, s[8:9]
	s_nop 0
	v_cndmask_b32_e64 v33, v29, v21, s[8:9]
	s_waitcnt lgkmcnt(0)
	v_cndmask_b32_e64 v35, v30, v22, s[8:9]
	v_mov_b32_dpp v32, v34 quad_perm:[1,0,3,2] row_mask:0xf bank_mask:0xf
	s_nop 0
	v_cndmask_b32_e64 v36, v31, v23, s[8:9]
	v_cndmask_b32_e64 v38, v24, v16, s[8:9]
	v_mov_b32_dpp v34, v33 quad_perm:[1,0,3,2] row_mask:0xf bank_mask:0xf
	s_nop 0
	v_cndmask_b32_e64 v37, v25, v17, s[8:9]
	v_cndmask_b32_e64 v39, v26, v18, s[8:9]
	v_mov_b32_dpp v33, v35 quad_perm:[1,0,3,2] row_mask:0xf bank_mask:0xf
	s_nop 0
	v_cndmask_b32_e64 v40, v27, v19, s[8:9]
	v_cndmask_b32_e64 v29, v34, v29, s[8:9]
	v_mov_b32_dpp v35, v36 quad_perm:[1,0,3,2] row_mask:0xf bank_mask:0xf
	s_nop 0
	v_cndmask_b32_e64 v28, v32, v28, s[8:9]
	v_cndmask_b32_e64 v31, v35, v31, s[8:9]
	v_mov_b32_dpp v36, v38 quad_perm:[1,0,3,2] row_mask:0xf bank_mask:0xf
	s_nop 0
	v_cndmask_b32_e64 v30, v33, v30, s[8:9]
	v_cndmask_b32_e64 v24, v36, v24, s[8:9]
	v_mov_b32_dpp v38, v37 quad_perm:[1,0,3,2] row_mask:0xf bank_mask:0xf
	s_nop 0
	v_cndmask_b32_e64 v25, v38, v25, s[8:9]
	s_waitcnt vmcnt(11)
	v_and_b32_e32 v41, 0xffff0000, v76
	v_mov_b32_dpp v37, v39 quad_perm:[1,0,3,2] row_mask:0xf bank_mask:0xf
	s_nop 0
	v_cndmask_b32_e64 v26, v37, v26, s[8:9]
	v_lshlrev_b32_e32 v42, 16, v77
	v_mov_b32_dpp v39, v40 quad_perm:[1,0,3,2] row_mask:0xf bank_mask:0xf
	v_cndmask_b32_e64 v27, v39, v27, s[8:9]
	v_lshlrev_b32_e32 v40, 16, v76
	v_and_b32_e32 v43, 0xffff0000, v77
	v_lshlrev_b32_e32 v44, 16, v78
	v_and_b32_e32 v45, 0xffff0000, v78
	v_lshlrev_b32_e32 v46, 16, v79
	v_and_b32_e32 v47, 0xffff0000, v79
	v_pk_fma_f32 v[30:31], v[42:43], s[18:19], v[30:31] op_sel_hi:[1,0,1]
	v_pk_fma_f32 v[28:29], v[40:41], s[18:19], v[28:29] op_sel_hi:[1,0,1]
	v_pk_fma_f32 v[26:27], v[46:47], s[18:19], v[26:27] op_sel_hi:[1,0,1]
	v_pk_fma_f32 v[24:25], v[44:45], s[18:19], v[24:25] op_sel_hi:[1,0,1]
	v_cvt_pk_bf16_f32 v40, v28, v29
	v_cvt_pk_bf16_f32 v41, v30, v31
	v_mov_b32_e32 v93, v165
	v_cvt_pk_bf16_f32 v42, v24, v25
	v_cvt_pk_bf16_f32 v43, v26, v27
	v_lshlrev_b32_e32 v24, 16, v40
	v_and_b32_e32 v26, 0xffff0000, v40
	v_lshlrev_b32_e32 v28, 16, v41
	v_and_b32_e32 v30, 0xffff0000, v41
	v_lshlrev_b32_e32 v44, 16, v42
	v_and_b32_e32 v46, 0xffff0000, v42
	v_lshlrev_b32_e32 v48, 16, v43
	v_and_b32_e32 v50, 0xffff0000, v43
	v_mul_f32_e32 v25, v24, v24
	v_mul_f32_e32 v27, v26, v26
	v_mul_f32_e32 v29, v28, v28
	v_mul_f32_e32 v31, v30, v30
	v_mul_f32_e32 v45, v44, v44
	v_mul_f32_e32 v47, v46, v46
	v_mul_f32_e32 v49, v48, v48
	v_mul_f32_e32 v51, v50, v50
	v_pk_add_f32 v[24:25], v[24:25], v[26:27]
	v_pk_add_f32 v[26:27], v[28:29], v[30:31]
	v_pk_add_f32 v[28:29], v[48:49], v[50:51]
	v_pk_add_f32 v[24:25], v[24:25], v[26:27]
	v_pk_add_f32 v[26:27], v[44:45], v[46:47]
	s_nop 0
	v_pk_add_f32 v[26:27], v[26:27], v[28:29]
	s_nop 0
	v_pk_add_f32 v[24:25], v[24:25], v[26:27]
	v_mov_b32_e32 v26, v165
	v_mov_b32_e32 v27, v165
	s_nop 0
	v_mov_b32_dpp v26, v24 quad_perm:[1,0,3,2] row_mask:0xf bank_mask:0xf
	v_mov_b32_dpp v27, v25 quad_perm:[1,0,3,2] row_mask:0xf bank_mask:0xf
	v_pk_add_f32 v[24:25], v[24:25], v[26:27]
	v_mov_b32_e32 v26, v24
	v_mov_b32_e32 v27, v25
	s_nop 1
	v_permlane16_swap_b32_e32 v24, v26
	v_permlane16_swap_b32_e32 v25, v27
	s_waitcnt lgkmcnt(0)
	v_pk_add_f32 v[26:27], v[24:25], v[26:27]
	v_mov_b32_e32 v28, v26
	v_mov_b32_e32 v29, v27
	s_nop 1
	v_permlane32_swap_b32_e32 v26, v28
	v_permlane32_swap_b32_e32 v27, v29
	v_lshl_add_u64 v[24:25], s[54:55], 0, v[92:93]
	global_store_dwordx4 v[24:25], v[40:43], off
	s_and_saveexec_b64 s[56:57], s[10:11]
	s_cbranch_execz .LBB0_608
	s_waitcnt lgkmcnt(0)
	v_pk_add_f32 v[26:27], v[26:27], v[28:29]
	v_add_co_u32_e32 v28, vcc, 0x14000, v124
	s_nop 1
	v_addc_co_u32_e32 v29, vcc, 0, v125, vcc
	global_store_dwordx2 v[28:29], v[26:27], off

; __device__ __forceinline__ u32x4 pack8f(f32x4 a, f32x4 b) { u32x4 w; w.x = cvt_pk_bf16(a[0], a[1]); w.y = cvt_pk_bf16(a[2], a[3]); w.z = cvt_pk_bf16(b[0], b[1]); w.w = cvt_pk_bf16(b[2], b[3]); return w; }
;     __device__ __forceinline__ void operator()(const f32x4 (&acc)[2][2][4][2], const Unit& u, int wr, int wc, int fr, int fq, const EpiCtx& X) const {
;     ...
;             for (int m = 0; m < 4; ++m) {
;                 const int rl = ai * HALF + m * 16; const unsigned off = lo + (unsigned)(rl * 64) * 2u;
;                 const f32x4 o0a = acc[ai][0][m][0], o0b = acc[ai][0][m][1], o1a = acc[ai][1][m][0], o1b = acc[ai][1][m][1];
;                 const f32x4 ra_ = dpp_swap1(odd ? o0a : o1a), rb_ = dpp_swap1(odd ? o0b : o1b);
;                 const f32x4 pa[2] = {odd ? ra_ : o0a, odd ? o1a : ra_}, pb[2] = {odd ? rb_ : o0b, odd ? o1b : rb_};
; #pragma unroll
;                 for (int q = 0; q < 2; ++q) {
;                     const u32x4 w0 = raw[2 * m + q];
;                     const f32x4 r0 = (f32x4){bf_lo(w0.x), bf_hi(w0.x), bf_lo(w0.y), bf_hi(w0.y)}, r1 = (f32x4){bf_lo(w0.z), bf_hi(w0.z), bf_lo(w0.w), bf_hi(w0.w)};
;                     f32x4 y0, y1;
;                     if (RESN) { const f32x2 t = tbl[rl + q]; const float mu = t.x, ra = t.y * ALPHA; y0 = (r0 - mu) * ra * g0 + b0 + pa[q]; y1 = (r1 - mu) * ra * g1 + b1 + pb[q]; }
;                     else { y0 = r0 * ALPHA + pa[q]; y1 = r1 * ALPHA + pb[q]; }
;                     { const u32x4 w = pack8f(y0, y1); *(u32x4*)(xb + off + q * 128) = w;
;                         y0 = (f32x4){bf_lo(w.x), bf_hi(w.x), bf_lo(w.y), bf_hi(w.y)}; y1 = (f32x4){bf_lo(w.z), bf_hi(w.z), bf_lo(w.w), bf_hi(w.w)}; }
;                     float sa = ((y0[0] + y0[1]) + (y0[2] + y0[3])) + ((y1[0] + y1[1]) + (y1[2] + y1[3]));
;                     float sb = ((y0[0] * y0[0] + y0[1] * y0[1]) + (y0[2] * y0[2] + y0[3] * y0[3])) + ((y1[0] * y1[0] + y1[1] * y1[1]) + (y1[2] * y1[2] + y1[3] * y1[3]));
;                     sa += dpp_x1(sa);
;                     sb += dpp_x1(sb);
;                     sa += __shfl_xor(sa, 16); sa += __shfl_xor(sa, 32); sb += __shfl_xor(sb, 16); sb += __shfl_xor(sb, 32);
;                     if (fq == 0 && !odd) ps[(size_t)(rl + q) * 64] = (f32x2){sa, sb};
.LBB0_610:
	s_or_b64 exec, exec, s[56:57]
	s_waitcnt lgkmcnt(0)
	v_cndmask_b32_e64 v18, v12, v4, s[8:9]
	s_nop 0
	v_cndmask_b32_e64 v17, v13, v5, s[8:9]
	s_waitcnt lgkmcnt(0)
	v_cndmask_b32_e64 v19, v14, v6, s[8:9]
	v_mov_b32_dpp v16, v18 quad_perm:[1,0,3,2] row_mask:0xf bank_mask:0xf
	s_nop 0
	v_cndmask_b32_e64 v20, v15, v7, s[8:9]
	v_cndmask_b32_e64 v22, v8, v0, s[8:9]
	v_mov_b32_dpp v18, v17 quad_perm:[1,0,3,2] row_mask:0xf bank_mask:0xf
	s_nop 0
	v_cndmask_b32_e64 v21, v9, v1, s[8:9]
	v_cndmask_b32_e64 v23, v10, v2, s[8:9]
	v_mov_b32_dpp v17, v19 quad_perm:[1,0,3,2] row_mask:0xf bank_mask:0xf
	s_nop 0
	v_cndmask_b32_e64 v24, v11, v3, s[8:9]
	v_cndmask_b32_e64 v13, v18, v13, s[8:9]
	v_mov_b32_dpp v19, v20 quad_perm:[1,0,3,2] row_mask:0xf bank_mask:0xf
	s_nop 0
	v_cndmask_b32_e64 v12, v16, v12, s[8:9]
	v_cndmask_b32_e64 v15, v19, v15, s[8:9]
	v_mov_b32_dpp v20, v22 quad_perm:[1,0,3,2] row_mask:0xf bank_mask:0xf
	s_nop 0
	v_cndmask_b32_e64 v14, v17, v14, s[8:9]
	v_cndmask_b32_e64 v8, v20, v8, s[8:9]
	v_mov_b32_dpp v22, v21 quad_perm:[1,0,3,2] row_mask:0xf bank_mask:0xf
	s_nop 0
	v_cndmask_b32_e64 v9, v22, v9, s[8:9]
	s_waitcnt vmcnt(13)
	v_and_b32_e32 v25, 0xffff0000, v68
	v_mov_b32_dpp v21, v23 quad_perm:[1,0,3,2] row_mask:0xf bank_mask:0xf
	s_nop 0
	v_cndmask_b32_e64 v10, v21, v10, s[8:9]
	v_lshlrev_b32_e32 v26, 16, v69
	v_mov_b32_dpp v23, v24 quad_perm:[1,0,3,2] row_mask:0xf bank_mask:0xf
	v_cndmask_b32_e64 v11, v23, v11, s[8:9]
	v_lshlrev_b32_e32 v24, 16, v68
	v_and_b32_e32 v27, 0xffff0000, v69
	v_lshlrev_b32_e32 v28, 16, v70
	v_and_b32_e32 v29, 0xffff0000, v70
	v_lshlrev_b32_e32 v30, 16, v71
	v_and_b32_e32 v31, 0xffff0000, v71
	v_pk_fma_f32 v[14:15], v[26:27], s[18:19], v[14:15] op_sel_hi:[1,0,1]
	v_pk_fma_f32 v[12:13], v[24:25], s[18:19], v[12:13] op_sel_hi:[1,0,1]
	v_pk_fma_f32 v[10:11], v[30:31], s[18:19], v[10:11] op_sel_hi:[1,0,1]
	v_pk_fma_f32 v[8:9], v[28:29], s[18:19], v[8:9] op_sel_hi:[1,0,1]
	v_cvt_pk_bf16_f32 v24, v12, v13
	v_cvt_pk_bf16_f32 v25, v14, v15
	s_nop 0
	v_cvt_pk_bf16_f32 v26, v8, v9
	v_cvt_pk_bf16_f32 v27, v10, v11
	v_lshlrev_b32_e32 v8, 16, v24
	v_and_b32_e32 v10, 0xffff0000, v24
	v_lshlrev_b32_e32 v12, 16, v25
	v_and_b32_e32 v14, 0xffff0000, v25
	v_lshlrev_b32_e32 v28, 16, v26
	v_and_b32_e32 v30, 0xffff0000, v26
	v_lshlrev_b32_e32 v32, 16, v27
	v_and_b32_e32 v34, 0xffff0000, v27
	v_mul_f32_e32 v9, v8, v8
	v_mul_f32_e32 v11, v10, v10
	v_mul_f32_e32 v13, v12, v12
	v_mul_f32_e32 v15, v14, v14
	v_mul_f32_e32 v29, v28, v28
	v_mul_f32_e32 v31, v30, v30
	v_mul_f32_e32 v33, v32, v32
	v_mul_f32_e32 v35, v34, v34
	v_pk_add_f32 v[8:9], v[8:9], v[10:11]
	v_pk_add_f32 v[10:11], v[12:13], v[14:15]
	v_pk_add_f32 v[12:13], v[32:33], v[34:35]
	v_pk_add_f32 v[8:9], v[8:9], v[10:11]
	v_pk_add_f32 v[10:11], v[28:29], v[30:31]
	s_nop 0
	v_pk_add_f32 v[10:11], v[10:11], v[12:13]
	s_nop 0
	v_pk_add_f32 v[8:9], v[8:9], v[10:11]
	v_mov_b32_e32 v10, v165
	v_mov_b32_e32 v11, v165
	s_nop 0
	v_mov_b32_dpp v10, v8 quad_perm:[1,0,3,2] row_mask:0xf bank_mask:0xf
	v_mov_b32_dpp v11, v9 quad_perm:[1,0,3,2] row_mask:0xf bank_mask:0xf
	v_pk_add_f32 v[8:9], v[8:9], v[10:11]
	v_mov_b32_e32 v10, v8
	v_mov_b32_e32 v11, v9
	s_nop 1
	v_permlane16_swap_b32_e32 v8, v10
	v_permlane16_swap_b32_e32 v9, v11
	s_waitcnt lgkmcnt(0)
	v_pk_add_f32 v[10:11], v[8:9], v[10:11]
	v_mov_b32_e32 v12, v10
	v_mov_b32_e32 v13, v11
	s_nop 1
	v_permlane32_swap_b32_e32 v10, v12
	v_permlane32_swap_b32_e32 v11, v13
	v_lshl_add_u64 v[8:9], s[54:55], 0, v[164:165]
	global_store_dwordx4 v[8:9], v[24:27], off
	s_and_saveexec_b64 s[54:55], s[10:11]
	s_cbranch_execz .LBB0_612
	s_waitcnt lgkmcnt(0)
	v_pk_add_f32 v[10:11], v[10:11], v[12:13]
	v_add_co_u32_e32 v12, vcc, 0x16000, v124
	s_nop 1
	v_addc_co_u32_e32 v13, vcc, 0, v125, vcc
	global_store_dwordx2 v[12:13], v[10:11], off

; #define LAS __attribute__((address_space(3)))
;     __device__ __forceinline__ void operator()(const f32x4 (&acc)[2][2][4][2], const Unit& u, int wr, int wc, int fr, int fq, const EpiCtx& X) const {
;     ...
;         char* yb = nullptr; char* xb = (char*)(XB + (size_t)u.pm * BM * DM + (size_t)(u.pn * 4 + wc) * (BM * 64));
;         unsigned lo = (unsigned)((wr * 64 + fe) * 64 + o32 + 8 * fq) * 2u; EPI_OPAQUE(lo);
;         const int col = u.pn * BM + wc * 64 + o32 + 8 * fq;
;         f32x4 g0, g1, b0, b1;
;         if (RESN) { ensure_tbl(PSp, sidp, u.pm, X);
;             g0 = *(const f32x4*)(gp + col); g1 = *(const f32x4*)(gp + col + 4); b0 = *(const f32x4*)(bp + col) * ALPHA; b1 = *(const f32x4*)(bp + col + 4) * ALPHA; }
;         const LAS f32x2* tbl = (const LAS f32x2*)(X.lds + TBL_OFF) + wr * 64 + fe;
;         f32x2* ps = PSn + ((size_t)u.pm * BM + wr * 64 + fe) * 64 + u.pn * 4 + wc;
; #pragma unroll
;         for (int ai = 0; ai < 2; ++ai) {
;             u32x4 raw[8];
; #pragma unroll
;             for (int m = 0; m < 4; ++m) { const unsigned off = lo + (unsigned)((ai * HALF + m * 16) * 64) * 2u; raw[2 * m] = *(const u32x4*)(xb + off); raw[2 * m + 1] = *(const u32x4*)(xb + off + 128); }
; #pragma unroll
;             for (int m = 0; m < 4; ++m) {
;                 const int rl = ai * HALF + m * 16; const unsigned off = lo + (unsigned)(rl * 64) * 2u;
;                 const f32x4 o0a = acc[ai][0][m][0], o0b = acc[ai][0][m][1], o1a = acc[ai][1][m][0], o1b = acc[ai][1][m][1];
;                 const f32x4 ra_ = dpp_swap1(odd ? o0a : o1a), rb_ = dpp_swap1(odd ? o0b : o1b);
;                 const f32x4 pa[2] = {odd ? ra_ : o0a, odd ? o1a : ra_}, pb[2] = {odd ? rb_ : o0b, odd ? o1b : rb_};
; #pragma unroll
;                 for (int q = 0; q < 2; ++q) {
;                     const u32x4 w0 = raw[2 * m + q];
;                     const f32x4 r0 = (f32x4){bf_lo(w0.x), bf_hi(w0.x), bf_lo(w0.y), bf_hi(w0.y)}, r1 = (f32x4){bf_lo(w0.z), bf_hi(w0.z), bf_lo(w0.w), bf_hi(w0.w)};
;                     f32x4 y0, y1;
;                     if (RESN) { const f32x2 t = tbl[rl + q]; const float mu = t.x, ra = t.y * ALPHA; y0 = (r0 - mu) * ra * g0 + b0 + pa[q]; y1 = (r1 - mu) * ra * g1 + b1 + pb[q]; }
;                     else { y0 = r0 * ALPHA + pa[q]; y1 = r1 * ALPHA + pb[q]; }
;                     { const u32x4 w = pack8f(y0, y1); *(u32x4*)(xb + off + q * 128) = w;
.LBB0_816:
	s_lshl_b64 s[4:5], s[70:71], 21
	s_add_u32 s20, s57, s4
	s_addc_u32 s21, s59, s5
	s_lshl_b32 s70, s68, 2
	s_or_b32 s4, s70, s41
	s_ashr_i32 s5, s4, 31
	v_lshl_add_u32 v72, s68, 8, v200
	v_ashrrev_i32_e32 v73, 31, v72
	s_lshl_b64 s[4:5], s[4:5], 15
	v_lshlrev_b64 v[72:73], 2, v[72:73]
	s_add_u32 s20, s20, s4
	v_lshl_add_u64 v[74:75], s[26:27], 0, v[72:73]
	s_addc_u32 s21, s21, s5
	global_load_dwordx4 v[194:197], v[74:75], off offset:16
	global_load_dwordx4 v[178:181], v[74:75], off
	global_load_dwordx4 v[214:217], v164, s[20:21]
	v_lshl_add_u64 v[72:73], s[24:25], 0, v[72:73]
	s_waitcnt lgkmcnt(0)
	global_load_dwordx4 v[76:79], v[72:73], off
	s_nop 0
	global_load_dwordx4 v[72:75], v[72:73], off offset:16
	v_cndmask_b32_e64 v136, v135, v127, s[10:11]
	v_cndmask_b32_e64 v137, v134, v126, s[10:11]
	v_cndmask_b32_e64 v138, v133, v125, s[10:11]
	v_cndmask_b32_e64 v139, v132, v124, s[10:11]
	s_nop 0
	s_nop 0
	s_nop 0
	s_nop 0
	v_cndmask_b32_e64 v140, v131, v123, s[10:11]
	v_cndmask_b32_e64 v141, v130, v122, s[10:11]
	v_cndmask_b32_e64 v142, v129, v121, s[10:11]
	v_cndmask_b32_e64 v143, v128, v120, s[10:11]
	s_nop 0
	s_nop 0
	s_nop 0
	s_nop 0
	v_mov_b32_dpp v189, v139 quad_perm:[1,0,3,2] row_mask:0xf bank_mask:0xf
	v_mov_b32_dpp v193, v138 quad_perm:[1,0,3,2] row_mask:0xf bank_mask:0xf
	v_mov_b32_dpp v191, v137 quad_perm:[1,0,3,2] row_mask:0xf bank_mask:0xf
	v_mov_b32_dpp v209, v136 quad_perm:[1,0,3,2] row_mask:0xf bank_mask:0xf
	v_mov_b32_dpp v210, v143 quad_perm:[1,0,3,2] row_mask:0xf bank_mask:0xf
	v_mov_b32_dpp v212, v142 quad_perm:[1,0,3,2] row_mask:0xf bank_mask:0xf
	v_mov_b32_dpp v211, v141 quad_perm:[1,0,3,2] row_mask:0xf bank_mask:0xf
	v_mov_b32_dpp v213, v140 quad_perm:[1,0,3,2] row_mask:0xf bank_mask:0xf
	v_add_u32_e32 v192, 0x800, v164
	v_add_u32_e32 v190, 0x1000, v164
	v_add_u32_e32 v188, 0x1800, v164
	ds_read_b64 v[218:219], v201
	v_cndmask_b32_e64 v221, v193, v133, s[10:11]
	v_cndmask_b32_e64 v220, v189, v132, s[10:11]
	v_cndmask_b32_e64 v223, v209, v135, s[10:11]
	v_cndmask_b32_e64 v222, v191, v134, s[10:11]
	v_cndmask_b32_e64 v225, v212, v129, s[10:11]
	v_cndmask_b32_e64 v224, v210, v128, s[10:11]
	v_cndmask_b32_e64 v227, v213, v131, s[10:11]
	v_cndmask_b32_e64 v226, v211, v130, s[10:11]
	global_load_dwordx4 v[152:155], v164, s[20:21] offset:128
	global_load_dwordx4 v[148:151], v192, s[20:21]
	global_load_dwordx4 v[144:147], v192, s[20:21] offset:128
	global_load_dwordx4 v[140:143], v190, s[20:21]
	global_load_dwordx4 v[136:139], v190, s[20:21] offset:128
	global_load_dwordx4 v[132:135], v188, s[20:21]
	global_load_dwordx4 v[128:131], v188, s[20:21] offset:128
	s_waitcnt lgkmcnt(0)
	v_mul_f32_e32 v208, 0x3fb504f3, v219
	v_lshl_add_u64 v[186:187], v[166:167], 0, s[72:73]
	s_ashr_i32 s71, s70, 31
	v_lshl_add_u64 v[186:187], s[70:71], 3, v[186:187]
	v_lshl_add_u64 v[186:187], v[186:187], 0, s[22:23]
	v_add_u32_e32 v246, 0x4000, v164
	v_add_u32_e32 v247, 0x4800, v164
	global_load_dwordx4 v[230:233], v246, s[20:21]
	global_load_dwordx4 v[234:237], v246, s[20:21] offset:128
	global_load_dwordx4 v[238:241], v247, s[20:21]
	global_load_dwordx4 v[242:245], v247, s[20:21] offset:128
	s_waitcnt vmcnt(14)
	v_pk_mul_f32 v[182:183], v[180:181], s[58:59] op_sel_hi:[1,0]
	v_pk_mul_f32 v[184:185], v[178:179], s[58:59] op_sel_hi:[1,0]
	v_pk_mul_f32 v[178:179], v[196:197], s[58:59] op_sel_hi:[1,0]
	v_pk_mul_f32 v[180:181], v[194:195], s[58:59] op_sel_hi:[1,0]
	s_waitcnt vmcnt(13)
	v_lshlrev_b32_e32 v194, 16, v214
	v_and_b32_e32 v195, 0xffff0000, v214
	v_lshlrev_b32_e32 v196, 16, v215
	v_and_b32_e32 v197, 0xffff0000, v215
	v_lshlrev_b32_e32 v207, 16, v216
	v_and_b32_e32 v214, 0xffff0000, v216
	v_lshlrev_b32_e32 v216, 16, v217
	v_and_b32_e32 v217, 0xffff0000, v217
	v_sub_f32_e32 v195, v195, v218
	v_sub_f32_e32 v194, v194, v218
	v_sub_f32_e32 v197, v197, v218
	v_sub_f32_e32 v196, v196, v218
	v_sub_f32_e32 v215, v214, v218
	v_sub_f32_e32 v214, v207, v218
	v_sub_f32_e32 v217, v217, v218
	v_sub_f32_e32 v216, v216, v218
	v_pk_mul_f32 v[196:197], v[196:197], v[208:209] op_sel_hi:[1,0]
	v_pk_mul_f32 v[194:195], v[194:195], v[208:209] op_sel_hi:[1,0]
	v_pk_mul_f32 v[216:217], v[216:217], v[208:209] op_sel_hi:[1,0]
	v_pk_mul_f32 v[214:215], v[214:215], v[208:209] op_sel_hi:[1,0]
	s_waitcnt vmcnt(12)
	v_pk_fma_f32 v[194:195], v[76:77], v[194:195], v[184:185]
	v_pk_fma_f32 v[196:197], v[78:79], v[196:197], v[182:183]
	s_waitcnt vmcnt(11)
	v_pk_fma_f32 v[214:215], v[72:73], v[214:215], v[180:181]
	v_pk_fma_f32 v[216:217], v[74:75], v[216:217], v[178:179]
	v_pk_add_f32 v[196:197], v[222:223], v[196:197]
	v_pk_add_f32 v[194:195], v[220:221], v[194:195]
	v_pk_add_f32 v[218:219], v[226:227], v[216:217]
	v_pk_add_f32 v[216:217], v[224:225], v[214:215]
	v_cvt_pk_bf16_f32 v214, v194, v195
	v_cvt_pk_bf16_f32 v215, v196, v197
	v_and_b32_e32 v208, 64, v206
	v_cvt_pk_bf16_f32 v216, v216, v217
	v_cvt_pk_bf16_f32 v217, v218, v219
	v_lshlrev_b32_e32 v194, 16, v214
	v_and_b32_e32 v196, 0xffff0000, v214
	v_lshlrev_b32_e32 v218, 16, v215
	v_and_b32_e32 v220, 0xffff0000, v215
	v_lshlrev_b32_e32 v222, 16, v216
	v_and_b32_e32 v224, 0xffff0000, v216
	v_lshlrev_b32_e32 v226, 16, v217
	v_and_b32_e32 v228, 0xffff0000, v217
	v_mul_f32_e32 v195, v194, v194
	v_mul_f32_e32 v197, v196, v196
	v_mul_f32_e32 v219, v218, v218
	v_mul_f32_e32 v221, v220, v220
	v_mul_f32_e32 v223, v222, v222
	v_mul_f32_e32 v225, v224, v224
	v_mul_f32_e32 v227, v226, v226
	v_mul_f32_e32 v229, v228, v228
	v_pk_add_f32 v[194:195], v[194:195], v[196:197]
	v_pk_add_f32 v[196:197], v[218:219], v[220:221]
	v_pk_add_f32 v[218:219], v[226:227], v[228:229]
	v_pk_add_f32 v[194:195], v[194:195], v[196:197]
	v_pk_add_f32 v[196:197], v[222:223], v[224:225]
	v_xor_b32_e32 v207, 16, v206
	v_add_u32_e32 v208, 64, v208
	v_pk_add_f32 v[196:197], v[196:197], v[218:219]
	v_cmp_lt_i32_e32 vcc, v207, v208
	v_pk_add_f32 v[194:195], v[194:195], v[196:197]
	s_nop 0
	s_nop 0
	v_cndmask_b32_e32 v207, v206, v207, vcc
	v_mov_b32_dpp v196, v194 quad_perm:[1,0,3,2] row_mask:0xf bank_mask:0xf
	v_mov_b32_dpp v197, v195 quad_perm:[1,0,3,2] row_mask:0xf bank_mask:0xf
	v_lshlrev_b32_e32 v207, 2, v207
	v_pk_add_f32 v[194:195], v[194:195], v[196:197]
	v_mov_b32_e32 v196, v194
	v_mov_b32_e32 v197, v195
	s_nop 1
	v_permlane16_swap_b32_e32 v194, v196
	v_permlane16_swap_b32_e32 v195, v197
	v_xor_b32_e32 v218, 32, v206
	v_cmp_lt_i32_e32 vcc, v218, v208
	global_store_dwordx4 v164, v[214:217], s[20:21]
	s_waitcnt lgkmcnt(0)
	v_pk_add_f32 v[194:195], v[194:195], v[196:197]
	v_cndmask_b32_e32 v208, v206, v218, vcc
	v_lshlrev_b32_e32 v208, 2, v208
	v_mov_b32_e32 v196, v194
	v_mov_b32_e32 v197, v195
	s_nop 1
	v_permlane32_swap_b32_e32 v194, v196
	v_permlane32_swap_b32_e32 v195, v197
	s_and_saveexec_b64 s[52:53], s[16:17]
	s_waitcnt lgkmcnt(0)
	v_pk_add_f32 v[194:195], v[194:195], v[196:197]
	global_store_dwordx2 v[186:187], v[194:195], off

; __device__ __forceinline__ u32x4 pack8f(f32x4 a, f32x4 b) { u32x4 w; w.x = cvt_pk_bf16(a[0], a[1]); w.y = cvt_pk_bf16(a[2], a[3]); w.z = cvt_pk_bf16(b[0], b[1]); w.w = cvt_pk_bf16(b[2], b[3]); return w; }
; __device__ __forceinline__ float dpp_x1(float x) { return __builtin_bit_cast(float, __builtin_amdgcn_update_dpp(0, __builtin_bit_cast(int, x), 0xB1, 0xF, 0xF, false)); }
;     __device__ __forceinline__ void operator()(const f32x4 (&acc)[2][2][4][2], const Unit& u, int wr, int wc, int fr, int fq, const EpiCtx& X) const {
;     ...
;                 const f32x4 o0a = acc[ai][0][m][0], o0b = acc[ai][0][m][1], o1a = acc[ai][1][m][0], o1b = acc[ai][1][m][1];
;                 const f32x4 ra_ = dpp_swap1(odd ? o0a : o1a), rb_ = dpp_swap1(odd ? o0b : o1b);
;                 const f32x4 pa[2] = {odd ? ra_ : o0a, odd ? o1a : ra_}, pb[2] = {odd ? rb_ : o0b, odd ? o1b : rb_};
; #pragma unroll
;                 for (int q = 0; q < 2; ++q) {
;                     const u32x4 w0 = raw[2 * m + q];
;                     const f32x4 r0 = (f32x4){bf_lo(w0.x), bf_hi(w0.x), bf_lo(w0.y), bf_hi(w0.y)}, r1 = (f32x4){bf_lo(w0.z), bf_hi(w0.z), bf_lo(w0.w), bf_hi(w0.w)};
;                     f32x4 y0, y1;
;                     if (RESN) { const f32x2 t = tbl[rl + q]; const float mu = t.x, ra = t.y * ALPHA; y0 = (r0 - mu) * ra * g0 + b0 + pa[q]; y1 = (r1 - mu) * ra * g1 + b1 + pb[q]; }
;                     else { y0 = r0 * ALPHA + pa[q]; y1 = r1 * ALPHA + pb[q]; }
;                     { const u32x4 w = pack8f(y0, y1); *(u32x4*)(xb + off + q * 128) = w;
;                         y0 = (f32x4){bf_lo(w.x), bf_hi(w.x), bf_lo(w.y), bf_hi(w.y)}; y1 = (f32x4){bf_lo(w.z), bf_hi(w.z), bf_lo(w.w), bf_hi(w.w)}; }
;                     float sa = ((y0[0] + y0[1]) + (y0[2] + y0[3])) + ((y1[0] + y1[1]) + (y1[2] + y1[3]));
;                     float sb = ((y0[0] * y0[0] + y0[1] * y0[1]) + (y0[2] * y0[2] + y0[3] * y0[3])) + ((y1[0] * y1[0] + y1[1] * y1[1]) + (y1[2] * y1[2] + y1[3] * y1[3]));
;                     sa += dpp_x1(sa);
;                     sb += dpp_x1(sb);
;                     sa += __shfl_xor(sa, 16); sa += __shfl_xor(sa, 32); sb += __shfl_xor(sb, 16); sb += __shfl_xor(sb, 32);
;                     if (fq == 0 && !odd) ps[(size_t)(rl + q) * 64] = (f32x2){sa, sb};
.LBB0_820:
	s_or_b64 exec, exec, s[52:53]
	s_waitcnt lgkmcnt(0)
	v_cndmask_b32_e64 v122, v116, v108, s[10:11]
	s_nop 0
	v_cndmask_b32_e64 v121, v117, v109, s[10:11]
	s_waitcnt lgkmcnt(0)
	v_cndmask_b32_e64 v123, v118, v110, s[10:11]
	v_mov_b32_dpp v120, v122 quad_perm:[1,0,3,2] row_mask:0xf bank_mask:0xf
	s_nop 0
	v_cndmask_b32_e64 v124, v119, v111, s[10:11]
	v_cndmask_b32_e64 v126, v112, v104, s[10:11]
	v_mov_b32_dpp v122, v121 quad_perm:[1,0,3,2] row_mask:0xf bank_mask:0xf
	s_nop 0
	v_cndmask_b32_e64 v125, v113, v105, s[10:11]
	v_cndmask_b32_e64 v127, v114, v106, s[10:11]
	v_mov_b32_dpp v121, v123 quad_perm:[1,0,3,2] row_mask:0xf bank_mask:0xf
	s_nop 0
	v_cndmask_b32_e64 v152, v115, v107, s[10:11]
	s_waitcnt vmcnt(13)
	v_and_b32_e32 v153, 0xffff0000, v148
	v_mov_b32_dpp v123, v124 quad_perm:[1,0,3,2] row_mask:0xf bank_mask:0xf
	s_nop 0
	v_lshlrev_b32_e32 v154, 16, v149
	v_and_b32_e32 v155, 0xffff0000, v149
	v_mov_b32_dpp v124, v126 quad_perm:[1,0,3,2] row_mask:0xf bank_mask:0xf
	s_nop 0
	v_lshlrev_b32_e32 v189, 16, v150
	v_and_b32_e32 v191, 0xffff0000, v150
	v_mov_b32_dpp v126, v125 quad_perm:[1,0,3,2] row_mask:0xf bank_mask:0xf
	s_nop 0
	v_lshlrev_b32_e32 v193, 16, v151
	v_and_b32_e32 v151, 0xffff0000, v151
	v_mov_b32_dpp v125, v127 quad_perm:[1,0,3,2] row_mask:0xf bank_mask:0xf
	s_nop 0
	v_cndmask_b32_e64 v117, v122, v117, s[10:11]
	v_cndmask_b32_e64 v116, v120, v116, s[10:11]
	v_mov_b32_dpp v127, v152 quad_perm:[1,0,3,2] row_mask:0xf bank_mask:0xf
	v_lshlrev_b32_e32 v152, 16, v148
	ds_read_b64 v[148:149], v201 offset:128
	v_cndmask_b32_e64 v119, v123, v119, s[10:11]
	v_cndmask_b32_e64 v118, v121, v118, s[10:11]
	v_cndmask_b32_e64 v113, v126, v113, s[10:11]
	v_cndmask_b32_e64 v112, v124, v112, s[10:11]
	s_waitcnt lgkmcnt(0)
	v_mul_f32_e32 v150, 0x3fb504f3, v149
	v_sub_f32_e32 v153, v153, v148
	v_sub_f32_e32 v152, v152, v148
	v_pk_mul_f32 v[152:153], v[152:153], v[150:151] op_sel_hi:[1,0]
	v_sub_f32_e32 v155, v155, v148
	v_pk_fma_f32 v[152:153], v[76:77], v[152:153], v[184:185]
	v_sub_f32_e32 v154, v154, v148
	v_pk_add_f32 v[116:117], v[116:117], v[152:153]
	v_sub_f32_e32 v153, v191, v148
	v_sub_f32_e32 v152, v189, v148
	v_sub_f32_e32 v149, v151, v148
	v_sub_f32_e32 v148, v193, v148
	v_pk_mul_f32 v[154:155], v[154:155], v[150:151] op_sel_hi:[1,0]
	v_pk_mul_f32 v[148:149], v[148:149], v[150:151] op_sel_hi:[1,0]
	v_pk_mul_f32 v[150:151], v[152:153], v[150:151] op_sel_hi:[1,0]
	v_cndmask_b32_e64 v115, v127, v115, s[10:11]
	v_cndmask_b32_e64 v114, v125, v114, s[10:11]
	v_pk_fma_f32 v[154:155], v[78:79], v[154:155], v[182:183]
	v_pk_fma_f32 v[150:151], v[72:73], v[150:151], v[180:181]
	v_pk_fma_f32 v[148:149], v[74:75], v[148:149], v[178:179]
	v_pk_add_f32 v[118:119], v[118:119], v[154:155]
	v_pk_add_f32 v[114:115], v[114:115], v[148:149]
	v_pk_add_f32 v[112:113], v[112:113], v[150:151]
	v_cvt_pk_bf16_f32 v148, v116, v117
	v_cvt_pk_bf16_f32 v149, v118, v119
	v_mov_b32_e32 v193, v165
	v_cvt_pk_bf16_f32 v150, v112, v113
	v_cvt_pk_bf16_f32 v151, v114, v115
	v_lshlrev_b32_e32 v112, 16, v148
	v_and_b32_e32 v114, 0xffff0000, v148
	v_lshlrev_b32_e32 v116, 16, v149
	v_and_b32_e32 v118, 0xffff0000, v149
	v_lshlrev_b32_e32 v152, 16, v150
	v_and_b32_e32 v154, 0xffff0000, v150
	v_lshlrev_b32_e32 v194, 16, v151
	v_and_b32_e32 v196, 0xffff0000, v151
	v_mul_f32_e32 v113, v112, v112
	v_mul_f32_e32 v115, v114, v114
	v_mul_f32_e32 v117, v116, v116
	v_mul_f32_e32 v119, v118, v118
	v_mul_f32_e32 v153, v152, v152
	v_mul_f32_e32 v155, v154, v154
	v_mul_f32_e32 v195, v194, v194
	v_mul_f32_e32 v197, v196, v196
	v_pk_add_f32 v[112:113], v[112:113], v[114:115]
	v_pk_add_f32 v[114:115], v[116:117], v[118:119]
	v_pk_add_f32 v[116:117], v[194:195], v[196:197]
	v_pk_add_f32 v[112:113], v[112:113], v[114:115]
	v_pk_add_f32 v[114:115], v[152:153], v[154:155]
	s_nop 0
	v_pk_add_f32 v[114:115], v[114:115], v[116:117]
	s_nop 0
	v_pk_add_f32 v[112:113], v[112:113], v[114:115]
	v_mov_b32_e32 v114, v165
	v_mov_b32_e32 v115, v165
	s_nop 0
	v_mov_b32_dpp v114, v112 quad_perm:[1,0,3,2] row_mask:0xf bank_mask:0xf
	v_mov_b32_dpp v115, v113 quad_perm:[1,0,3,2] row_mask:0xf bank_mask:0xf
	v_pk_add_f32 v[112:113], v[112:113], v[114:115]
	v_mov_b32_e32 v114, v112
	v_mov_b32_e32 v115, v113
	s_nop 1
	v_permlane16_swap_b32_e32 v112, v114
	v_permlane16_swap_b32_e32 v113, v115
	s_waitcnt lgkmcnt(0)
	v_pk_add_f32 v[114:115], v[112:113], v[114:115]
	v_mov_b32_e32 v116, v114
	v_mov_b32_e32 v117, v115
	s_nop 1
	v_permlane32_swap_b32_e32 v114, v116
	v_permlane32_swap_b32_e32 v115, v117
	v_lshl_add_u64 v[112:113], s[20:21], 0, v[192:193]
	global_store_dwordx4 v[112:113], v[148:151], off
	s_and_saveexec_b64 s[68:69], s[16:17]
	s_waitcnt lgkmcnt(0)
	v_pk_add_f32 v[114:115], v[114:115], v[116:117]
	v_add_co_u32_e32 v116, vcc, 0x2000, v186
	s_nop 1
	v_addc_co_u32_e32 v117, vcc, 0, v187, vcc
	global_store_dwordx2 v[116:117], v[114:115], off

; __device__ __forceinline__ u32x4 pack8f(f32x4 a, f32x4 b) { u32x4 w; w.x = cvt_pk_bf16(a[0], a[1]); w.y = cvt_pk_bf16(a[2], a[3]); w.z = cvt_pk_bf16(b[0], b[1]); w.w = cvt_pk_bf16(b[2], b[3]); return w; }
; __device__ __forceinline__ float dpp_x1(float x) { return __builtin_bit_cast(float, __builtin_amdgcn_update_dpp(0, __builtin_bit_cast(int, x), 0xB1, 0xF, 0xF, false)); }
;     __device__ __forceinline__ void operator()(const f32x4 (&acc)[2][2][4][2], const Unit& u, int wr, int wc, int fr, int fq, const EpiCtx& X) const {
;     ...
;                 const f32x4 o0a = acc[ai][0][m][0], o0b = acc[ai][0][m][1], o1a = acc[ai][1][m][0], o1b = acc[ai][1][m][1];
;                 const f32x4 ra_ = dpp_swap1(odd ? o0a : o1a), rb_ = dpp_swap1(odd ? o0b : o1b);
;                 const f32x4 pa[2] = {odd ? ra_ : o0a, odd ? o1a : ra_}, pb[2] = {odd ? rb_ : o0b, odd ? o1b : rb_};
; #pragma unroll
;                 for (int q = 0; q < 2; ++q) {
;                     const u32x4 w0 = raw[2 * m + q];
;                     const f32x4 r0 = (f32x4){bf_lo(w0.x), bf_hi(w0.x), bf_lo(w0.y), bf_hi(w0.y)}, r1 = (f32x4){bf_lo(w0.z), bf_hi(w0.z), bf_lo(w0.w), bf_hi(w0.w)};
;                     f32x4 y0, y1;
;                     if (RESN) { const f32x2 t = tbl[rl + q]; const float mu = t.x, ra = t.y * ALPHA; y0 = (r0 - mu) * ra * g0 + b0 + pa[q]; y1 = (r1 - mu) * ra * g1 + b1 + pb[q]; }
;                     else { y0 = r0 * ALPHA + pa[q]; y1 = r1 * ALPHA + pb[q]; }
;                     { const u32x4 w = pack8f(y0, y1); *(u32x4*)(xb + off + q * 128) = w;
;                         y0 = (f32x4){bf_lo(w.x), bf_hi(w.x), bf_lo(w.y), bf_hi(w.y)}; y1 = (f32x4){bf_lo(w.z), bf_hi(w.z), bf_lo(w.w), bf_hi(w.w)}; }
;                     float sa = ((y0[0] + y0[1]) + (y0[2] + y0[3])) + ((y1[0] + y1[1]) + (y1[2] + y1[3]));
;                     float sb = ((y0[0] * y0[0] + y0[1] * y0[1]) + (y0[2] * y0[2] + y0[3] * y0[3])) + ((y1[0] * y1[0] + y1[1] * y1[1]) + (y1[2] * y1[2] + y1[3] * y1[3]));
;                     sa += dpp_x1(sa);
;                     sb += dpp_x1(sb);
;                     sa += __shfl_xor(sa, 16); sa += __shfl_xor(sa, 32); sb += __shfl_xor(sb, 16); sb += __shfl_xor(sb, 32);
;                     if (fq == 0 && !odd) ps[(size_t)(rl + q) * 64] = (f32x2){sa, sb};
.LBB0_824:
	s_or_b64 exec, exec, s[68:69]
	s_waitcnt lgkmcnt(0)
	v_cndmask_b32_e64 v106, v100, v92, s[10:11]
	s_nop 0
	v_cndmask_b32_e64 v105, v101, v93, s[10:11]
	s_waitcnt lgkmcnt(0)
	v_cndmask_b32_e64 v107, v102, v94, s[10:11]
	v_mov_b32_dpp v104, v106 quad_perm:[1,0,3,2] row_mask:0xf bank_mask:0xf
	s_nop 0
	v_cndmask_b32_e64 v108, v103, v95, s[10:11]
	v_cndmask_b32_e64 v110, v96, v88, s[10:11]
	v_mov_b32_dpp v106, v105 quad_perm:[1,0,3,2] row_mask:0xf bank_mask:0xf
	s_nop 0
	v_cndmask_b32_e64 v109, v97, v89, s[10:11]
	v_cndmask_b32_e64 v111, v98, v90, s[10:11]
	v_mov_b32_dpp v105, v107 quad_perm:[1,0,3,2] row_mask:0xf bank_mask:0xf
	s_nop 0
	v_cndmask_b32_e64 v112, v99, v91, s[10:11]
	s_waitcnt vmcnt(15)
	v_lshlrev_b32_e32 v115, 16, v140
	v_mov_b32_dpp v107, v108 quad_perm:[1,0,3,2] row_mask:0xf bank_mask:0xf
	s_nop 0
	v_and_b32_e32 v116, 0xffff0000, v140
	v_cndmask_b32_e64 v101, v106, v101, s[10:11]
	v_mov_b32_dpp v108, v110 quad_perm:[1,0,3,2] row_mask:0xf bank_mask:0xf
	s_nop 0
	v_cndmask_b32_e64 v100, v104, v100, s[10:11]
	v_lshlrev_b32_e32 v118, 16, v141
	v_mov_b32_dpp v110, v109 quad_perm:[1,0,3,2] row_mask:0xf bank_mask:0xf
	s_nop 0
	v_and_b32_e32 v119, 0xffff0000, v141
	v_lshlrev_b32_e32 v120, 16, v142
	v_mov_b32_dpp v109, v111 quad_perm:[1,0,3,2] row_mask:0xf bank_mask:0xf
	s_nop 0
	v_and_b32_e32 v121, 0xffff0000, v142
	v_lshlrev_b32_e32 v122, 16, v143
	v_mov_b32_dpp v111, v112 quad_perm:[1,0,3,2] row_mask:0xf bank_mask:0xf
	ds_read_b64 v[112:113], v201 offset:256
	v_and_b32_e32 v123, 0xffff0000, v143
	v_cndmask_b32_e64 v103, v107, v103, s[10:11]
	v_cndmask_b32_e64 v102, v105, v102, s[10:11]
	v_cndmask_b32_e64 v97, v110, v97, s[10:11]
	s_waitcnt lgkmcnt(0)
	v_mul_f32_e32 v114, 0x3fb504f3, v113
	v_sub_f32_e32 v117, v116, v112
	v_sub_f32_e32 v116, v115, v112
	v_pk_mul_f32 v[116:117], v[116:117], v[114:115] op_sel_hi:[1,0]
	v_sub_f32_e32 v119, v119, v112
	v_pk_fma_f32 v[116:117], v[76:77], v[116:117], v[184:185]
	v_sub_f32_e32 v118, v118, v112
	v_pk_add_f32 v[100:101], v[100:101], v[116:117]
	v_sub_f32_e32 v117, v121, v112
	v_sub_f32_e32 v116, v120, v112
	v_sub_f32_e32 v113, v123, v112
	v_sub_f32_e32 v112, v122, v112
	v_pk_mul_f32 v[118:119], v[118:119], v[114:115] op_sel_hi:[1,0]
	v_pk_mul_f32 v[112:113], v[112:113], v[114:115] op_sel_hi:[1,0]
	v_pk_mul_f32 v[114:115], v[116:117], v[114:115] op_sel_hi:[1,0]
	v_cndmask_b32_e64 v96, v108, v96, s[10:11]
	v_cndmask_b32_e64 v99, v111, v99, s[10:11]
	v_cndmask_b32_e64 v98, v109, v98, s[10:11]
	v_pk_fma_f32 v[118:119], v[78:79], v[118:119], v[182:183]
	v_pk_fma_f32 v[114:115], v[72:73], v[114:115], v[180:181]
	v_pk_fma_f32 v[112:113], v[74:75], v[112:113], v[178:179]
	v_pk_add_f32 v[102:103], v[102:103], v[118:119]
	v_pk_add_f32 v[98:99], v[98:99], v[112:113]
	v_pk_add_f32 v[96:97], v[96:97], v[114:115]
	v_cvt_pk_bf16_f32 v112, v100, v101
	v_cvt_pk_bf16_f32 v113, v102, v103
	v_mov_b32_e32 v191, v165
	v_cvt_pk_bf16_f32 v114, v96, v97
	v_cvt_pk_bf16_f32 v115, v98, v99
	v_lshlrev_b32_e32 v96, 16, v112
	v_and_b32_e32 v98, 0xffff0000, v112
	v_lshlrev_b32_e32 v100, 16, v113
	v_and_b32_e32 v102, 0xffff0000, v113
	v_lshlrev_b32_e32 v116, 16, v114
	v_and_b32_e32 v118, 0xffff0000, v114
	v_lshlrev_b32_e32 v120, 16, v115
	v_and_b32_e32 v122, 0xffff0000, v115
	v_mul_f32_e32 v97, v96, v96
	v_mul_f32_e32 v99, v98, v98
	v_mul_f32_e32 v101, v100, v100
	v_mul_f32_e32 v103, v102, v102
	v_mul_f32_e32 v117, v116, v116
	v_mul_f32_e32 v119, v118, v118
	v_mul_f32_e32 v121, v120, v120
	v_mul_f32_e32 v123, v122, v122
	v_pk_add_f32 v[96:97], v[96:97], v[98:99]
	v_pk_add_f32 v[98:99], v[100:101], v[102:103]
	v_pk_add_f32 v[100:101], v[120:121], v[122:123]
	v_pk_add_f32 v[96:97], v[96:97], v[98:99]
	v_pk_add_f32 v[98:99], v[116:117], v[118:119]
	s_nop 0
	v_pk_add_f32 v[98:99], v[98:99], v[100:101]
	s_nop 0
	v_pk_add_f32 v[96:97], v[96:97], v[98:99]
	v_mov_b32_e32 v98, v165
	v_mov_b32_e32 v99, v165
	s_nop 0
	v_mov_b32_dpp v98, v96 quad_perm:[1,0,3,2] row_mask:0xf bank_mask:0xf
	v_mov_b32_dpp v99, v97 quad_perm:[1,0,3,2] row_mask:0xf bank_mask:0xf
	v_pk_add_f32 v[96:97], v[96:97], v[98:99]
	v_mov_b32_e32 v98, v96
	v_mov_b32_e32 v99, v97
	s_nop 1
	v_permlane16_swap_b32_e32 v96, v98
	v_permlane16_swap_b32_e32 v97, v99
	s_waitcnt lgkmcnt(0)
	v_pk_add_f32 v[98:99], v[96:97], v[98:99]
	v_mov_b32_e32 v100, v98
	v_mov_b32_e32 v101, v99
	s_nop 1
	v_permlane32_swap_b32_e32 v98, v100
	v_permlane32_swap_b32_e32 v99, v101
	v_lshl_add_u64 v[96:97], s[20:21], 0, v[190:191]
	global_store_dwordx4 v[96:97], v[112:115], off
	s_and_saveexec_b64 s[68:69], s[16:17]
	s_waitcnt lgkmcnt(0)
	v_pk_add_f32 v[98:99], v[98:99], v[100:101]
	v_add_co_u32_e32 v100, vcc, 0x4000, v186
	s_nop 1
	v_addc_co_u32_e32 v101, vcc, 0, v187, vcc
	global_store_dwordx2 v[100:101], v[98:99], off

; __device__ __forceinline__ u32x4 pack8f(f32x4 a, f32x4 b) { u32x4 w; w.x = cvt_pk_bf16(a[0], a[1]); w.y = cvt_pk_bf16(a[2], a[3]); w.z = cvt_pk_bf16(b[0], b[1]); w.w = cvt_pk_bf16(b[2], b[3]); return w; }
; __device__ __forceinline__ float dpp_x1(float x) { return __builtin_bit_cast(float, __builtin_amdgcn_update_dpp(0, __builtin_bit_cast(int, x), 0xB1, 0xF, 0xF, false)); }
;     __device__ __forceinline__ void operator()(const f32x4 (&acc)[2][2][4][2], const Unit& u, int wr, int wc, int fr, int fq, const EpiCtx& X) const {
;     ...
;                 const f32x4 o0a = acc[ai][0][m][0], o0b = acc[ai][0][m][1], o1a = acc[ai][1][m][0], o1b = acc[ai][1][m][1];
;                 const f32x4 ra_ = dpp_swap1(odd ? o0a : o1a), rb_ = dpp_swap1(odd ? o0b : o1b);
;                 const f32x4 pa[2] = {odd ? ra_ : o0a, odd ? o1a : ra_}, pb[2] = {odd ? rb_ : o0b, odd ? o1b : rb_};
; #pragma unroll
;                 for (int q = 0; q < 2; ++q) {
;                     const u32x4 w0 = raw[2 * m + q];
;                     const f32x4 r0 = (f32x4){bf_lo(w0.x), bf_hi(w0.x), bf_lo(w0.y), bf_hi(w0.y)}, r1 = (f32x4){bf_lo(w0.z), bf_hi(w0.z), bf_lo(w0.w), bf_hi(w0.w)};
;                     f32x4 y0, y1;
;                     if (RESN) { const f32x2 t = tbl[rl + q]; const float mu = t.x, ra = t.y * ALPHA; y0 = (r0 - mu) * ra * g0 + b0 + pa[q]; y1 = (r1 - mu) * ra * g1 + b1 + pb[q]; }
;                     else { y0 = r0 * ALPHA + pa[q]; y1 = r1 * ALPHA + pb[q]; }
;                     { const u32x4 w = pack8f(y0, y1); *(u32x4*)(xb + off + q * 128) = w;
;                         y0 = (f32x4){bf_lo(w.x), bf_hi(w.x), bf_lo(w.y), bf_hi(w.y)}; y1 = (f32x4){bf_lo(w.z), bf_hi(w.z), bf_lo(w.w), bf_hi(w.w)}; }
;                     float sa = ((y0[0] + y0[1]) + (y0[2] + y0[3])) + ((y1[0] + y1[1]) + (y1[2] + y1[3]));
;                     float sb = ((y0[0] * y0[0] + y0[1] * y0[1]) + (y0[2] * y0[2] + y0[3] * y0[3])) + ((y1[0] * y1[0] + y1[1] * y1[1]) + (y1[2] * y1[2] + y1[3] * y1[3]));
;                     sa += dpp_x1(sa);
;                     sb += dpp_x1(sb);
;                     sa += __shfl_xor(sa, 16); sa += __shfl_xor(sa, 32); sb += __shfl_xor(sb, 16); sb += __shfl_xor(sb, 32);
;                     if (fq == 0 && !odd) ps[(size_t)(rl + q) * 64] = (f32x2){sa, sb};
.LBB0_828:
	s_or_b64 exec, exec, s[68:69]
	s_waitcnt lgkmcnt(0)
	v_cndmask_b32_e64 v90, v84, v68, s[10:11]
	s_nop 0
	v_cndmask_b32_e64 v89, v85, v69, s[10:11]
	s_waitcnt lgkmcnt(0)
	v_cndmask_b32_e64 v91, v86, v70, s[10:11]
	v_mov_b32_dpp v88, v90 quad_perm:[1,0,3,2] row_mask:0xf bank_mask:0xf
	s_nop 0
	v_cndmask_b32_e64 v92, v87, v71, s[10:11]
	v_cndmask_b32_e64 v94, v80, v64, s[10:11]
	v_mov_b32_dpp v90, v89 quad_perm:[1,0,3,2] row_mask:0xf bank_mask:0xf
	s_nop 0
	v_cndmask_b32_e64 v93, v81, v65, s[10:11]
	v_cndmask_b32_e64 v95, v82, v66, s[10:11]
	v_mov_b32_dpp v89, v91 quad_perm:[1,0,3,2] row_mask:0xf bank_mask:0xf
	s_nop 0
	v_cndmask_b32_e64 v96, v83, v67, s[10:11]
	s_waitcnt vmcnt(17)
	v_lshlrev_b32_e32 v99, 16, v132
	v_mov_b32_dpp v91, v92 quad_perm:[1,0,3,2] row_mask:0xf bank_mask:0xf
	s_nop 0
	v_and_b32_e32 v100, 0xffff0000, v132
	v_cndmask_b32_e64 v85, v90, v85, s[10:11]
	v_mov_b32_dpp v92, v94 quad_perm:[1,0,3,2] row_mask:0xf bank_mask:0xf
	s_nop 0
	v_cndmask_b32_e64 v84, v88, v84, s[10:11]
	v_lshlrev_b32_e32 v102, 16, v133
	v_mov_b32_dpp v94, v93 quad_perm:[1,0,3,2] row_mask:0xf bank_mask:0xf
	s_nop 0
	v_and_b32_e32 v103, 0xffff0000, v133
	v_lshlrev_b32_e32 v104, 16, v134
	v_mov_b32_dpp v93, v95 quad_perm:[1,0,3,2] row_mask:0xf bank_mask:0xf
	s_nop 0
	v_and_b32_e32 v105, 0xffff0000, v134
	v_lshlrev_b32_e32 v106, 16, v135
	v_mov_b32_dpp v95, v96 quad_perm:[1,0,3,2] row_mask:0xf bank_mask:0xf
	ds_read_b64 v[96:97], v201 offset:384
	v_and_b32_e32 v107, 0xffff0000, v135
	v_cndmask_b32_e64 v87, v91, v87, s[10:11]
	v_cndmask_b32_e64 v86, v89, v86, s[10:11]
	v_cndmask_b32_e64 v81, v94, v81, s[10:11]
	s_waitcnt lgkmcnt(0)
	v_mul_f32_e32 v98, 0x3fb504f3, v97
	v_sub_f32_e32 v101, v100, v96
	v_sub_f32_e32 v100, v99, v96
	v_pk_mul_f32 v[100:101], v[100:101], v[98:99] op_sel_hi:[1,0]
	v_sub_f32_e32 v103, v103, v96
	v_pk_fma_f32 v[100:101], v[76:77], v[100:101], v[184:185]
	v_sub_f32_e32 v102, v102, v96
	v_pk_add_f32 v[84:85], v[84:85], v[100:101]
	v_sub_f32_e32 v101, v105, v96
	v_sub_f32_e32 v100, v104, v96
	v_sub_f32_e32 v97, v107, v96
	v_sub_f32_e32 v96, v106, v96
	v_pk_mul_f32 v[102:103], v[102:103], v[98:99] op_sel_hi:[1,0]
	v_pk_mul_f32 v[96:97], v[96:97], v[98:99] op_sel_hi:[1,0]
	v_pk_mul_f32 v[98:99], v[100:101], v[98:99] op_sel_hi:[1,0]
	v_cndmask_b32_e64 v80, v92, v80, s[10:11]
	v_cndmask_b32_e64 v83, v95, v83, s[10:11]
	v_cndmask_b32_e64 v82, v93, v82, s[10:11]
	v_pk_fma_f32 v[102:103], v[78:79], v[102:103], v[182:183]
	v_pk_fma_f32 v[98:99], v[72:73], v[98:99], v[180:181]
	v_pk_fma_f32 v[96:97], v[74:75], v[96:97], v[178:179]
	v_pk_add_f32 v[86:87], v[86:87], v[102:103]
	v_pk_add_f32 v[82:83], v[82:83], v[96:97]
	v_pk_add_f32 v[80:81], v[80:81], v[98:99]
	v_cvt_pk_bf16_f32 v96, v84, v85
	v_cvt_pk_bf16_f32 v97, v86, v87
	v_mov_b32_e32 v189, v165
	v_cvt_pk_bf16_f32 v98, v80, v81
	v_cvt_pk_bf16_f32 v99, v82, v83
	v_lshlrev_b32_e32 v80, 16, v96
	v_and_b32_e32 v82, 0xffff0000, v96
	v_lshlrev_b32_e32 v84, 16, v97
	v_and_b32_e32 v86, 0xffff0000, v97
	v_lshlrev_b32_e32 v100, 16, v98
	v_and_b32_e32 v102, 0xffff0000, v98
	v_lshlrev_b32_e32 v104, 16, v99
	v_and_b32_e32 v106, 0xffff0000, v99
	v_mul_f32_e32 v81, v80, v80
	v_mul_f32_e32 v83, v82, v82
	v_mul_f32_e32 v85, v84, v84
	v_mul_f32_e32 v87, v86, v86
	v_mul_f32_e32 v101, v100, v100
	v_mul_f32_e32 v103, v102, v102
	v_mul_f32_e32 v105, v104, v104
	v_mul_f32_e32 v107, v106, v106
	v_pk_add_f32 v[80:81], v[80:81], v[82:83]
	v_pk_add_f32 v[82:83], v[84:85], v[86:87]
	v_pk_add_f32 v[84:85], v[104:105], v[106:107]
	v_pk_add_f32 v[80:81], v[80:81], v[82:83]
	v_pk_add_f32 v[82:83], v[100:101], v[102:103]
	s_nop 0
	v_pk_add_f32 v[82:83], v[82:83], v[84:85]
	s_nop 0
	v_pk_add_f32 v[80:81], v[80:81], v[82:83]
	v_mov_b32_e32 v82, v165
	v_mov_b32_e32 v83, v165
	s_nop 0
	v_mov_b32_dpp v82, v80 quad_perm:[1,0,3,2] row_mask:0xf bank_mask:0xf
	v_mov_b32_dpp v83, v81 quad_perm:[1,0,3,2] row_mask:0xf bank_mask:0xf
	v_pk_add_f32 v[80:81], v[80:81], v[82:83]
	v_mov_b32_e32 v82, v80
	v_mov_b32_e32 v83, v81
	s_nop 1
	v_permlane16_swap_b32_e32 v80, v82
	v_permlane16_swap_b32_e32 v81, v83
	s_waitcnt lgkmcnt(0)
	v_pk_add_f32 v[82:83], v[80:81], v[82:83]
	v_mov_b32_e32 v84, v82
	v_mov_b32_e32 v85, v83
	s_nop 1
	v_permlane32_swap_b32_e32 v82, v84
	v_permlane32_swap_b32_e32 v83, v85
	v_lshl_add_u64 v[80:81], s[20:21], 0, v[188:189]
	global_store_dwordx4 v[80:81], v[96:99], off
	s_and_saveexec_b64 s[68:69], s[16:17]
	s_waitcnt lgkmcnt(0)
	v_pk_add_f32 v[82:83], v[82:83], v[84:85]
	v_add_co_u32_e32 v84, vcc, 0x6000, v186
	s_nop 1
	v_addc_co_u32_e32 v85, vcc, 0, v187, vcc
	global_store_dwordx2 v[84:85], v[82:83], off

;     __device__ __forceinline__ void operator()(const f32x4 (&acc)[2][2][4][2], const Unit& u, int wr, int wc, int fr, int fq, const EpiCtx& X) const {
;     ...
;             for (int m = 0; m < 4; ++m) { const unsigned off = lo + (unsigned)((ai * HALF + m * 16) * 64) * 2u; raw[2 * m] = *(const u32x4*)(xb + off); raw[2 * m + 1] = *(const u32x4*)(xb + off + 128); }
; #pragma unroll
;             for (int m = 0; m < 4; ++m) {
;                 const int rl = ai * HALF + m * 16; const unsigned off = lo + (unsigned)(rl * 64) * 2u;
;                 const f32x4 o0a = acc[ai][0][m][0], o0b = acc[ai][0][m][1], o1a = acc[ai][1][m][0], o1b = acc[ai][1][m][1];
;                 const f32x4 ra_ = dpp_swap1(odd ? o0a : o1a), rb_ = dpp_swap1(odd ? o0b : o1b);
;                 const f32x4 pa[2] = {odd ? ra_ : o0a, odd ? o1a : ra_}, pb[2] = {odd ? rb_ : o0b, odd ? o1b : rb_};
; #pragma unroll
;                 for (int q = 0; q < 2; ++q) {
;                     const u32x4 w0 = raw[2 * m + q];
;                     const f32x4 r0 = (f32x4){bf_lo(w0.x), bf_hi(w0.x), bf_lo(w0.y), bf_hi(w0.y)}, r1 = (f32x4){bf_lo(w0.z), bf_hi(w0.z), bf_lo(w0.w), bf_hi(w0.w)};
;                     f32x4 y0, y1;
;                     if (RESN) { const f32x2 t = tbl[rl + q]; const float mu = t.x, ra = t.y * ALPHA; y0 = (r0 - mu) * ra * g0 + b0 + pa[q]; y1 = (r1 - mu) * ra * g1 + b1 + pb[q]; }
;                     else { y0 = r0 * ALPHA + pa[q]; y1 = r1 * ALPHA + pb[q]; }
;                     { const u32x4 w = pack8f(y0, y1); *(u32x4*)(xb + off + q * 128) = w;
;                         y0 = (f32x4){bf_lo(w.x), bf_hi(w.x), bf_lo(w.y), bf_hi(w.y)}; y1 = (f32x4){bf_lo(w.z), bf_hi(w.z), bf_lo(w.w), bf_hi(w.w)}; }
;                     float sa = ((y0[0] + y0[1]) + (y0[2] + y0[3])) + ((y1[0] + y1[1]) + (y1[2] + y1[3]));
;                     float sb = ((y0[0] * y0[0] + y0[1] * y0[1]) + (y0[2] * y0[2] + y0[3] * y0[3])) + ((y1[0] * y1[0] + y1[1] * y1[1]) + (y1[2] * y1[2] + y1[3] * y1[3]));
;                     sa += dpp_x1(sa);
;                     sb += dpp_x1(sb);
;                     sa += __shfl_xor(sa, 16); sa += __shfl_xor(sa, 32); sb += __shfl_xor(sb, 16); sb += __shfl_xor(sb, 32);
;                     if (fq == 0 && !odd) ps[(size_t)(rl + q) * 64] = (f32x2){sa, sb};
.LBB0_832:
	s_or_b64 exec, exec, s[68:69]
	v_add_u32_e32 v104, 0x4000, v164
	s_waitcnt vmcnt(16)
	v_mov_b32_e32 v112, v230
	v_mov_b32_e32 v113, v231
	v_mov_b32_e32 v114, v232
	v_mov_b32_e32 v115, v233
	v_add_u32_e32 v102, 0x4800, v164
	v_add_u32_e32 v100, 0x5000, v164
	v_add_u32_e32 v164, 0x5800, v164
	v_mov_b32_e32 v96, v234
	v_mov_b32_e32 v97, v235
	v_mov_b32_e32 v98, v236
	v_mov_b32_e32 v99, v237
	v_mov_b32_e32 v92, v238
	v_mov_b32_e32 v93, v239
	v_mov_b32_e32 v94, v240
	v_mov_b32_e32 v95, v241
	v_mov_b32_e32 v88, v242
	v_mov_b32_e32 v89, v243
	v_mov_b32_e32 v90, v244
	v_mov_b32_e32 v91, v245
	global_load_dwordx4 v[84:87], v100, s[20:21]
	global_load_dwordx4 v[80:83], v100, s[20:21] offset:128
	global_load_dwordx4 v[68:71], v164, s[20:21]
	s_waitcnt lgkmcnt(0)
	global_load_dwordx4 v[64:67], v164, s[20:21] offset:128
	v_cndmask_b32_e64 v116, v62, v54, s[10:11]
	v_cndmask_b32_e64 v117, v61, v53, s[10:11]
	s_nop 0
	s_nop 0
	v_cndmask_b32_e64 v111, v63, v55, s[10:11]
	v_mov_b32_dpp v105, v117 quad_perm:[1,0,3,2] row_mask:0xf bank_mask:0xf
	v_mov_b32_dpp v103, v116 quad_perm:[1,0,3,2] row_mask:0xf bank_mask:0xf
	ds_read_b64 v[116:117], v201 offset:1024
	v_cndmask_b32_e64 v118, v60, v52, s[10:11]
	s_nop 0
	s_nop 0
	v_cndmask_b32_e64 v119, v59, v51, s[10:11]
	v_cndmask_b32_e64 v120, v58, v50, s[10:11]
	v_cndmask_b32_e64 v121, v57, v49, s[10:11]
	v_cndmask_b32_e64 v122, v56, v48, s[10:11]
	s_nop 0
	s_nop 0
	s_nop 0
	s_nop 0
	v_mov_b32_dpp v101, v118 quad_perm:[1,0,3,2] row_mask:0xf bank_mask:0xf
	v_mov_b32_dpp v106, v111 quad_perm:[1,0,3,2] row_mask:0xf bank_mask:0xf
	v_mov_b32_dpp v107, v122 quad_perm:[1,0,3,2] row_mask:0xf bank_mask:0xf
	v_mov_b32_dpp v109, v121 quad_perm:[1,0,3,2] row_mask:0xf bank_mask:0xf
	v_mov_b32_dpp v108, v120 quad_perm:[1,0,3,2] row_mask:0xf bank_mask:0xf
	v_mov_b32_dpp v110, v119 quad_perm:[1,0,3,2] row_mask:0xf bank_mask:0xf
	s_waitcnt lgkmcnt(0)
	v_mul_f32_e32 v118, 0x3fb504f3, v117
	v_cndmask_b32_e64 v61, v105, v61, s[10:11]
	v_cndmask_b32_e64 v60, v101, v60, s[10:11]
	v_cndmask_b32_e64 v63, v106, v63, s[10:11]
	v_cndmask_b32_e64 v62, v103, v62, s[10:11]
	v_cndmask_b32_e64 v57, v109, v57, s[10:11]
	v_cndmask_b32_e64 v56, v107, v56, s[10:11]
	v_cndmask_b32_e64 v59, v110, v59, s[10:11]
	v_cndmask_b32_e64 v58, v108, v58, s[10:11]
	v_lshlrev_b32_e32 v111, 16, v112
	v_and_b32_e32 v112, 0xffff0000, v112
	v_lshlrev_b32_e32 v117, 16, v113
	v_and_b32_e32 v119, 0xffff0000, v113
	v_lshlrev_b32_e32 v120, 16, v114
	v_and_b32_e32 v121, 0xffff0000, v114
	v_lshlrev_b32_e32 v122, 16, v115
	v_and_b32_e32 v123, 0xffff0000, v115
	v_sub_f32_e32 v113, v112, v116
	v_sub_f32_e32 v112, v111, v116
	v_sub_f32_e32 v115, v119, v116
	v_sub_f32_e32 v114, v117, v116
	v_sub_f32_e32 v121, v121, v116
	v_sub_f32_e32 v120, v120, v116
	v_sub_f32_e32 v117, v123, v116
	v_sub_f32_e32 v116, v122, v116
	v_pk_mul_f32 v[114:115], v[114:115], v[118:119] op_sel_hi:[1,0]
	v_pk_mul_f32 v[112:113], v[112:113], v[118:119] op_sel_hi:[1,0]
	v_pk_mul_f32 v[116:117], v[116:117], v[118:119] op_sel_hi:[1,0]
	v_pk_mul_f32 v[118:119], v[120:121], v[118:119] op_sel_hi:[1,0]
	v_pk_fma_f32 v[112:113], v[76:77], v[112:113], v[184:185]
	v_pk_fma_f32 v[114:115], v[78:79], v[114:115], v[182:183]
	v_pk_fma_f32 v[118:119], v[72:73], v[118:119], v[180:181]
	v_pk_fma_f32 v[116:117], v[74:75], v[116:117], v[178:179]
	v_pk_add_f32 v[62:63], v[62:63], v[114:115]
	v_pk_add_f32 v[60:61], v[60:61], v[112:113]
	v_pk_add_f32 v[58:59], v[58:59], v[116:117]
	v_pk_add_f32 v[56:57], v[56:57], v[118:119]
	v_cvt_pk_bf16_f32 v60, v60, v61
	v_cvt_pk_bf16_f32 v61, v62, v63
	s_nop 0
	v_cvt_pk_bf16_f32 v62, v56, v57
	v_cvt_pk_bf16_f32 v63, v58, v59
	v_lshlrev_b32_e32 v56, 16, v60
	v_and_b32_e32 v58, 0xffff0000, v60
	v_lshlrev_b32_e32 v112, 16, v61
	v_and_b32_e32 v114, 0xffff0000, v61
	v_lshlrev_b32_e32 v116, 16, v62
	v_and_b32_e32 v118, 0xffff0000, v62
	v_lshlrev_b32_e32 v120, 16, v63
	v_and_b32_e32 v122, 0xffff0000, v63
	v_mul_f32_e32 v57, v56, v56
	v_mul_f32_e32 v59, v58, v58
	v_mul_f32_e32 v113, v112, v112
	v_mul_f32_e32 v115, v114, v114
	v_mul_f32_e32 v117, v116, v116
	v_mul_f32_e32 v119, v118, v118
	v_mul_f32_e32 v121, v120, v120
	v_mul_f32_e32 v123, v122, v122
	v_pk_add_f32 v[56:57], v[56:57], v[58:59]
	v_pk_add_f32 v[58:59], v[112:113], v[114:115]
	v_pk_add_f32 v[112:113], v[120:121], v[122:123]
	v_pk_add_f32 v[56:57], v[56:57], v[58:59]
	v_pk_add_f32 v[58:59], v[116:117], v[118:119]
	global_store_dwordx4 v104, v[60:63], s[20:21]
	v_pk_add_f32 v[58:59], v[58:59], v[112:113]
	s_nop 0
	v_pk_add_f32 v[56:57], v[56:57], v[58:59]
	v_mov_b32_e32 v58, v165
	v_mov_b32_e32 v59, v165
	s_nop 0
	v_mov_b32_dpp v58, v56 quad_perm:[1,0,3,2] row_mask:0xf bank_mask:0xf
	v_mov_b32_dpp v59, v57 quad_perm:[1,0,3,2] row_mask:0xf bank_mask:0xf
	v_pk_add_f32 v[56:57], v[56:57], v[58:59]
	v_mov_b32_e32 v58, v56
	v_mov_b32_e32 v59, v57
	s_nop 1
	v_permlane16_swap_b32_e32 v56, v58
	v_permlane16_swap_b32_e32 v57, v59
	s_waitcnt lgkmcnt(0)
	v_pk_add_f32 v[56:57], v[56:57], v[58:59]
	v_mov_b32_e32 v58, v56
	v_mov_b32_e32 v59, v57
	s_nop 1
	v_permlane32_swap_b32_e32 v56, v58
	v_permlane32_swap_b32_e32 v57, v59
	s_and_saveexec_b64 s[68:69], s[16:17]
	s_cbranch_execz .LBB0_834
	s_waitcnt lgkmcnt(0)
	v_pk_add_f32 v[56:57], v[56:57], v[58:59]
	v_add_co_u32_e32 v58, vcc, 0x10000, v186
	s_nop 1
	v_addc_co_u32_e32 v59, vcc, 0, v187, vcc
	global_store_dwordx2 v[58:59], v[56:57], off

; __device__ __forceinline__ u32x4 pack8f(f32x4 a, f32x4 b) { u32x4 w; w.x = cvt_pk_bf16(a[0], a[1]); w.y = cvt_pk_bf16(a[2], a[3]); w.z = cvt_pk_bf16(b[0], b[1]); w.w = cvt_pk_bf16(b[2], b[3]); return w; }
; __device__ __forceinline__ float dpp_x1(float x) { return __builtin_bit_cast(float, __builtin_amdgcn_update_dpp(0, __builtin_bit_cast(int, x), 0xB1, 0xF, 0xF, false)); }
;     __device__ __forceinline__ void operator()(const f32x4 (&acc)[2][2][4][2], const Unit& u, int wr, int wc, int fr, int fq, const EpiCtx& X) const {
;     ...
;                 const f32x4 o0a = acc[ai][0][m][0], o0b = acc[ai][0][m][1], o1a = acc[ai][1][m][0], o1b = acc[ai][1][m][1];
;                 const f32x4 ra_ = dpp_swap1(odd ? o0a : o1a), rb_ = dpp_swap1(odd ? o0b : o1b);
;                 const f32x4 pa[2] = {odd ? ra_ : o0a, odd ? o1a : ra_}, pb[2] = {odd ? rb_ : o0b, odd ? o1b : rb_};
; #pragma unroll
;                 for (int q = 0; q < 2; ++q) {
;                     const u32x4 w0 = raw[2 * m + q];
;                     const f32x4 r0 = (f32x4){bf_lo(w0.x), bf_hi(w0.x), bf_lo(w0.y), bf_hi(w0.y)}, r1 = (f32x4){bf_lo(w0.z), bf_hi(w0.z), bf_lo(w0.w), bf_hi(w0.w)};
;                     f32x4 y0, y1;
;                     if (RESN) { const f32x2 t = tbl[rl + q]; const float mu = t.x, ra = t.y * ALPHA; y0 = (r0 - mu) * ra * g0 + b0 + pa[q]; y1 = (r1 - mu) * ra * g1 + b1 + pb[q]; }
;                     else { y0 = r0 * ALPHA + pa[q]; y1 = r1 * ALPHA + pb[q]; }
;                     { const u32x4 w = pack8f(y0, y1); *(u32x4*)(xb + off + q * 128) = w;
;                         y0 = (f32x4){bf_lo(w.x), bf_hi(w.x), bf_lo(w.y), bf_hi(w.y)}; y1 = (f32x4){bf_lo(w.z), bf_hi(w.z), bf_lo(w.w), bf_hi(w.w)}; }
;                     float sa = ((y0[0] + y0[1]) + (y0[2] + y0[3])) + ((y1[0] + y1[1]) + (y1[2] + y1[3]));
;                     float sb = ((y0[0] * y0[0] + y0[1] * y0[1]) + (y0[2] * y0[2] + y0[3] * y0[3])) + ((y1[0] * y1[0] + y1[1] * y1[1]) + (y1[2] * y1[2] + y1[3] * y1[3]));
;                     sa += dpp_x1(sa);
;                     sb += dpp_x1(sb);
;                     sa += __shfl_xor(sa, 16); sa += __shfl_xor(sa, 32); sb += __shfl_xor(sb, 16); sb += __shfl_xor(sb, 32);
;                     if (fq == 0 && !odd) ps[(size_t)(rl + q) * 64] = (f32x2){sa, sb};
.LBB0_836:
	s_or_b64 exec, exec, s[68:69]
	s_waitcnt lgkmcnt(0)
	v_cndmask_b32_e64 v50, v44, v36, s[10:11]
	s_nop 0
	v_cndmask_b32_e64 v49, v45, v37, s[10:11]
	s_waitcnt lgkmcnt(0)
	v_cndmask_b32_e64 v51, v46, v38, s[10:11]
	v_mov_b32_dpp v48, v50 quad_perm:[1,0,3,2] row_mask:0xf bank_mask:0xf
	s_nop 0
	v_cndmask_b32_e64 v52, v47, v39, s[10:11]
	v_cndmask_b32_e64 v54, v40, v32, s[10:11]
	v_mov_b32_dpp v50, v49 quad_perm:[1,0,3,2] row_mask:0xf bank_mask:0xf
	s_nop 0
	v_cndmask_b32_e64 v53, v41, v33, s[10:11]
	v_cndmask_b32_e64 v55, v42, v34, s[10:11]
	v_mov_b32_dpp v49, v51 quad_perm:[1,0,3,2] row_mask:0xf bank_mask:0xf
	s_nop 0
	v_cndmask_b32_e64 v56, v43, v35, s[10:11]
	v_lshlrev_b32_e32 v59, 16, v92
	v_mov_b32_dpp v51, v52 quad_perm:[1,0,3,2] row_mask:0xf bank_mask:0xf
	s_nop 0
	v_and_b32_e32 v60, 0xffff0000, v92
	v_cndmask_b32_e64 v45, v50, v45, s[10:11]
	v_mov_b32_dpp v52, v54 quad_perm:[1,0,3,2] row_mask:0xf bank_mask:0xf
	s_nop 0
	v_cndmask_b32_e64 v44, v48, v44, s[10:11]
	v_lshlrev_b32_e32 v62, 16, v93
	v_mov_b32_dpp v54, v53 quad_perm:[1,0,3,2] row_mask:0xf bank_mask:0xf
	s_nop 0
	v_and_b32_e32 v63, 0xffff0000, v93
	v_lshlrev_b32_e32 v92, 16, v94
	v_mov_b32_dpp v53, v55 quad_perm:[1,0,3,2] row_mask:0xf bank_mask:0xf
	s_nop 0
	v_and_b32_e32 v93, 0xffff0000, v94
	v_lshlrev_b32_e32 v94, 16, v95
	v_mov_b32_dpp v55, v56 quad_perm:[1,0,3,2] row_mask:0xf bank_mask:0xf
	ds_read_b64 v[56:57], v201 offset:1152
	v_and_b32_e32 v95, 0xffff0000, v95
	v_cndmask_b32_e64 v47, v51, v47, s[10:11]
	v_cndmask_b32_e64 v46, v49, v46, s[10:11]
	v_cndmask_b32_e64 v41, v54, v41, s[10:11]
	s_waitcnt lgkmcnt(0)
	v_mul_f32_e32 v58, 0x3fb504f3, v57
	v_sub_f32_e32 v61, v60, v56
	v_sub_f32_e32 v60, v59, v56
	v_pk_mul_f32 v[60:61], v[60:61], v[58:59] op_sel_hi:[1,0]
	v_sub_f32_e32 v63, v63, v56
	v_pk_fma_f32 v[60:61], v[76:77], v[60:61], v[184:185]
	v_sub_f32_e32 v62, v62, v56
	v_pk_add_f32 v[44:45], v[44:45], v[60:61]
	v_sub_f32_e32 v61, v93, v56
	v_sub_f32_e32 v60, v92, v56
	v_sub_f32_e32 v57, v95, v56
	v_sub_f32_e32 v56, v94, v56
	v_pk_mul_f32 v[62:63], v[62:63], v[58:59] op_sel_hi:[1,0]
	v_pk_mul_f32 v[56:57], v[56:57], v[58:59] op_sel_hi:[1,0]
	v_pk_mul_f32 v[58:59], v[60:61], v[58:59] op_sel_hi:[1,0]
	v_cndmask_b32_e64 v40, v52, v40, s[10:11]
	v_cndmask_b32_e64 v43, v55, v43, s[10:11]
	v_cndmask_b32_e64 v42, v53, v42, s[10:11]
	v_pk_fma_f32 v[62:63], v[78:79], v[62:63], v[182:183]
	v_pk_fma_f32 v[58:59], v[72:73], v[58:59], v[180:181]
	v_pk_fma_f32 v[56:57], v[74:75], v[56:57], v[178:179]
	v_pk_add_f32 v[46:47], v[46:47], v[62:63]
	v_pk_add_f32 v[42:43], v[42:43], v[56:57]
	v_pk_add_f32 v[40:41], v[40:41], v[58:59]
	v_cvt_pk_bf16_f32 v56, v44, v45
	v_cvt_pk_bf16_f32 v57, v46, v47
	v_mov_b32_e32 v103, v165
	v_cvt_pk_bf16_f32 v58, v40, v41
	v_cvt_pk_bf16_f32 v59, v42, v43
	v_lshlrev_b32_e32 v40, 16, v56
	v_and_b32_e32 v42, 0xffff0000, v56
	v_lshlrev_b32_e32 v44, 16, v57
	v_and_b32_e32 v46, 0xffff0000, v57
	v_lshlrev_b32_e32 v60, 16, v58
	v_and_b32_e32 v62, 0xffff0000, v58
	v_lshlrev_b32_e32 v92, 16, v59
	v_and_b32_e32 v94, 0xffff0000, v59
	v_mul_f32_e32 v41, v40, v40
	v_mul_f32_e32 v43, v42, v42
	v_mul_f32_e32 v45, v44, v44
	v_mul_f32_e32 v47, v46, v46
	v_mul_f32_e32 v61, v60, v60
	v_mul_f32_e32 v63, v62, v62
	v_mul_f32_e32 v93, v92, v92
	v_mul_f32_e32 v95, v94, v94
	v_pk_add_f32 v[40:41], v[40:41], v[42:43]
	v_pk_add_f32 v[42:43], v[44:45], v[46:47]
	v_pk_add_f32 v[44:45], v[92:93], v[94:95]
	v_pk_add_f32 v[40:41], v[40:41], v[42:43]
	v_pk_add_f32 v[42:43], v[60:61], v[62:63]
	s_nop 0
	v_pk_add_f32 v[42:43], v[42:43], v[44:45]
	s_nop 0
	v_pk_add_f32 v[40:41], v[40:41], v[42:43]
	v_mov_b32_e32 v42, v165
	v_mov_b32_e32 v43, v165
	s_nop 0
	v_mov_b32_dpp v42, v40 quad_perm:[1,0,3,2] row_mask:0xf bank_mask:0xf
	v_mov_b32_dpp v43, v41 quad_perm:[1,0,3,2] row_mask:0xf bank_mask:0xf
	v_pk_add_f32 v[40:41], v[40:41], v[42:43]
	v_mov_b32_e32 v42, v40
	v_mov_b32_e32 v43, v41
	s_nop 1
	v_permlane16_swap_b32_e32 v40, v42
	v_permlane16_swap_b32_e32 v41, v43
	s_waitcnt lgkmcnt(0)
	v_pk_add_f32 v[42:43], v[40:41], v[42:43]
	v_mov_b32_e32 v44, v42
	v_mov_b32_e32 v45, v43
	s_nop 1
	v_permlane32_swap_b32_e32 v42, v44
	v_permlane32_swap_b32_e32 v43, v45
	v_lshl_add_u64 v[40:41], s[20:21], 0, v[102:103]
	global_store_dwordx4 v[40:41], v[56:59], off
	s_and_saveexec_b64 s[68:69], s[16:17]
	s_cbranch_execz .LBB0_838
	s_waitcnt lgkmcnt(0)
	v_pk_add_f32 v[42:43], v[42:43], v[44:45]
	v_add_co_u32_e32 v44, vcc, 0x12000, v186
	s_nop 1
	v_addc_co_u32_e32 v45, vcc, 0, v187, vcc
	global_store_dwordx2 v[44:45], v[42:43], off

; __device__ __forceinline__ u32x4 pack8f(f32x4 a, f32x4 b) { u32x4 w; w.x = cvt_pk_bf16(a[0], a[1]); w.y = cvt_pk_bf16(a[2], a[3]); w.z = cvt_pk_bf16(b[0], b[1]); w.w = cvt_pk_bf16(b[2], b[3]); return w; }
; __device__ __forceinline__ float dpp_x1(float x) { return __builtin_bit_cast(float, __builtin_amdgcn_update_dpp(0, __builtin_bit_cast(int, x), 0xB1, 0xF, 0xF, false)); }
;     __device__ __forceinline__ void operator()(const f32x4 (&acc)[2][2][4][2], const Unit& u, int wr, int wc, int fr, int fq, const EpiCtx& X) const {
;     ...
;                 const f32x4 o0a = acc[ai][0][m][0], o0b = acc[ai][0][m][1], o1a = acc[ai][1][m][0], o1b = acc[ai][1][m][1];
;                 const f32x4 ra_ = dpp_swap1(odd ? o0a : o1a), rb_ = dpp_swap1(odd ? o0b : o1b);
;                 const f32x4 pa[2] = {odd ? ra_ : o0a, odd ? o1a : ra_}, pb[2] = {odd ? rb_ : o0b, odd ? o1b : rb_};
; #pragma unroll
;                 for (int q = 0; q < 2; ++q) {
;                     const u32x4 w0 = raw[2 * m + q];
;                     const f32x4 r0 = (f32x4){bf_lo(w0.x), bf_hi(w0.x), bf_lo(w0.y), bf_hi(w0.y)}, r1 = (f32x4){bf_lo(w0.z), bf_hi(w0.z), bf_lo(w0.w), bf_hi(w0.w)};
;                     f32x4 y0, y1;
;                     if (RESN) { const f32x2 t = tbl[rl + q]; const float mu = t.x, ra = t.y * ALPHA; y0 = (r0 - mu) * ra * g0 + b0 + pa[q]; y1 = (r1 - mu) * ra * g1 + b1 + pb[q]; }
;                     else { y0 = r0 * ALPHA + pa[q]; y1 = r1 * ALPHA + pb[q]; }
;                     { const u32x4 w = pack8f(y0, y1); *(u32x4*)(xb + off + q * 128) = w;
;                         y0 = (f32x4){bf_lo(w.x), bf_hi(w.x), bf_lo(w.y), bf_hi(w.y)}; y1 = (f32x4){bf_lo(w.z), bf_hi(w.z), bf_lo(w.w), bf_hi(w.w)}; }
;                     float sa = ((y0[0] + y0[1]) + (y0[2] + y0[3])) + ((y1[0] + y1[1]) + (y1[2] + y1[3]));
;                     float sb = ((y0[0] * y0[0] + y0[1] * y0[1]) + (y0[2] * y0[2] + y0[3] * y0[3])) + ((y1[0] * y1[0] + y1[1] * y1[1]) + (y1[2] * y1[2] + y1[3] * y1[3]));
;                     sa += dpp_x1(sa);
;                     sb += dpp_x1(sb);
;                     sa += __shfl_xor(sa, 16); sa += __shfl_xor(sa, 32); sb += __shfl_xor(sb, 16); sb += __shfl_xor(sb, 32);
;                     if (fq == 0 && !odd) ps[(size_t)(rl + q) * 64] = (f32x2){sa, sb};
.LBB0_840:
	s_or_b64 exec, exec, s[68:69]
	s_waitcnt lgkmcnt(0)
	v_cndmask_b32_e64 v34, v28, v20, s[10:11]
	s_nop 0
	v_cndmask_b32_e64 v33, v29, v21, s[10:11]
	s_waitcnt lgkmcnt(0)
	v_cndmask_b32_e64 v35, v30, v22, s[10:11]
	v_mov_b32_dpp v32, v34 quad_perm:[1,0,3,2] row_mask:0xf bank_mask:0xf
	s_nop 0
	v_cndmask_b32_e64 v36, v31, v23, s[10:11]
	v_cndmask_b32_e64 v38, v24, v16, s[10:11]
	v_mov_b32_dpp v34, v33 quad_perm:[1,0,3,2] row_mask:0xf bank_mask:0xf
	s_nop 0
	v_cndmask_b32_e64 v37, v25, v17, s[10:11]
	v_cndmask_b32_e64 v39, v26, v18, s[10:11]
	v_mov_b32_dpp v33, v35 quad_perm:[1,0,3,2] row_mask:0xf bank_mask:0xf
	s_nop 0
	v_cndmask_b32_e64 v40, v27, v19, s[10:11]
	s_waitcnt vmcnt(11)
	v_lshlrev_b32_e32 v43, 16, v84
	v_mov_b32_dpp v35, v36 quad_perm:[1,0,3,2] row_mask:0xf bank_mask:0xf
	s_nop 0
	v_and_b32_e32 v44, 0xffff0000, v84
	v_cndmask_b32_e64 v29, v34, v29, s[10:11]
	v_mov_b32_dpp v36, v38 quad_perm:[1,0,3,2] row_mask:0xf bank_mask:0xf
	s_nop 0
	v_cndmask_b32_e64 v28, v32, v28, s[10:11]
	v_lshlrev_b32_e32 v46, 16, v85
	v_mov_b32_dpp v38, v37 quad_perm:[1,0,3,2] row_mask:0xf bank_mask:0xf
	s_nop 0
	v_and_b32_e32 v47, 0xffff0000, v85
	v_lshlrev_b32_e32 v48, 16, v86
	v_mov_b32_dpp v37, v39 quad_perm:[1,0,3,2] row_mask:0xf bank_mask:0xf
	s_nop 0
	v_and_b32_e32 v49, 0xffff0000, v86
	v_lshlrev_b32_e32 v50, 16, v87
	v_mov_b32_dpp v39, v40 quad_perm:[1,0,3,2] row_mask:0xf bank_mask:0xf
	ds_read_b64 v[40:41], v201 offset:1280
	v_and_b32_e32 v51, 0xffff0000, v87
	v_cndmask_b32_e64 v31, v35, v31, s[10:11]
	v_cndmask_b32_e64 v30, v33, v30, s[10:11]
	v_cndmask_b32_e64 v25, v38, v25, s[10:11]
	s_waitcnt lgkmcnt(0)
	v_mul_f32_e32 v42, 0x3fb504f3, v41
	v_sub_f32_e32 v45, v44, v40
	v_sub_f32_e32 v44, v43, v40
	v_pk_mul_f32 v[44:45], v[44:45], v[42:43] op_sel_hi:[1,0]
	v_sub_f32_e32 v47, v47, v40
	v_pk_fma_f32 v[44:45], v[76:77], v[44:45], v[184:185]
	v_sub_f32_e32 v46, v46, v40
	v_pk_add_f32 v[28:29], v[28:29], v[44:45]
	v_sub_f32_e32 v45, v49, v40
	v_sub_f32_e32 v44, v48, v40
	v_sub_f32_e32 v41, v51, v40
	v_sub_f32_e32 v40, v50, v40
	v_pk_mul_f32 v[46:47], v[46:47], v[42:43] op_sel_hi:[1,0]
	v_pk_mul_f32 v[40:41], v[40:41], v[42:43] op_sel_hi:[1,0]
	v_pk_mul_f32 v[42:43], v[44:45], v[42:43] op_sel_hi:[1,0]
	v_cndmask_b32_e64 v24, v36, v24, s[10:11]
	v_cndmask_b32_e64 v27, v39, v27, s[10:11]
	v_cndmask_b32_e64 v26, v37, v26, s[10:11]
	v_pk_fma_f32 v[46:47], v[78:79], v[46:47], v[182:183]
	v_pk_fma_f32 v[42:43], v[72:73], v[42:43], v[180:181]
	v_pk_fma_f32 v[40:41], v[74:75], v[40:41], v[178:179]
	v_pk_add_f32 v[30:31], v[30:31], v[46:47]
	v_pk_add_f32 v[26:27], v[26:27], v[40:41]
	v_pk_add_f32 v[24:25], v[24:25], v[42:43]
	v_cvt_pk_bf16_f32 v40, v28, v29
	v_cvt_pk_bf16_f32 v41, v30, v31
	v_mov_b32_e32 v101, v165
	v_cvt_pk_bf16_f32 v42, v24, v25
	v_cvt_pk_bf16_f32 v43, v26, v27
	v_lshlrev_b32_e32 v24, 16, v40
	v_and_b32_e32 v26, 0xffff0000, v40
	v_lshlrev_b32_e32 v28, 16, v41
	v_and_b32_e32 v30, 0xffff0000, v41
	v_lshlrev_b32_e32 v44, 16, v42
	v_and_b32_e32 v46, 0xffff0000, v42
	v_lshlrev_b32_e32 v48, 16, v43
	v_and_b32_e32 v50, 0xffff0000, v43
	v_mul_f32_e32 v25, v24, v24
	v_mul_f32_e32 v27, v26, v26
	v_mul_f32_e32 v29, v28, v28
	v_mul_f32_e32 v31, v30, v30
	v_mul_f32_e32 v45, v44, v44
	v_mul_f32_e32 v47, v46, v46
	v_mul_f32_e32 v49, v48, v48
	v_mul_f32_e32 v51, v50, v50
	v_pk_add_f32 v[24:25], v[24:25], v[26:27]
	v_pk_add_f32 v[26:27], v[28:29], v[30:31]
	v_pk_add_f32 v[28:29], v[48:49], v[50:51]
	v_pk_add_f32 v[24:25], v[24:25], v[26:27]
	v_pk_add_f32 v[26:27], v[44:45], v[46:47]
	s_nop 0
	v_pk_add_f32 v[26:27], v[26:27], v[28:29]
	s_nop 0
	v_pk_add_f32 v[24:25], v[24:25], v[26:27]
	v_mov_b32_e32 v26, v165
	v_mov_b32_e32 v27, v165
	s_nop 0
	v_mov_b32_dpp v26, v24 quad_perm:[1,0,3,2] row_mask:0xf bank_mask:0xf
	v_mov_b32_dpp v27, v25 quad_perm:[1,0,3,2] row_mask:0xf bank_mask:0xf
	v_pk_add_f32 v[24:25], v[24:25], v[26:27]
	v_mov_b32_e32 v26, v24
	v_mov_b32_e32 v27, v25
	s_nop 1
	v_permlane16_swap_b32_e32 v24, v26
	v_permlane16_swap_b32_e32 v25, v27
	s_waitcnt lgkmcnt(0)
	v_pk_add_f32 v[26:27], v[24:25], v[26:27]
	v_mov_b32_e32 v28, v26
	v_mov_b32_e32 v29, v27
	s_nop 1
	v_permlane32_swap_b32_e32 v26, v28
	v_permlane32_swap_b32_e32 v27, v29
	v_lshl_add_u64 v[24:25], s[20:21], 0, v[100:101]
	global_store_dwordx4 v[24:25], v[40:43], off
	s_and_saveexec_b64 s[68:69], s[16:17]
	s_cbranch_execz .LBB0_842
	s_waitcnt lgkmcnt(0)
	v_pk_add_f32 v[26:27], v[26:27], v[28:29]
	v_add_co_u32_e32 v28, vcc, 0x14000, v186
	s_nop 1
	v_addc_co_u32_e32 v29, vcc, 0, v187, vcc
	global_store_dwordx2 v[28:29], v[26:27], off

; __device__ __forceinline__ u32x4 pack8f(f32x4 a, f32x4 b) { u32x4 w; w.x = cvt_pk_bf16(a[0], a[1]); w.y = cvt_pk_bf16(a[2], a[3]); w.z = cvt_pk_bf16(b[0], b[1]); w.w = cvt_pk_bf16(b[2], b[3]); return w; }
; __device__ __forceinline__ float dpp_x1(float x) { return __builtin_bit_cast(float, __builtin_amdgcn_update_dpp(0, __builtin_bit_cast(int, x), 0xB1, 0xF, 0xF, false)); }
;     __device__ __forceinline__ void operator()(const f32x4 (&acc)[2][2][4][2], const Unit& u, int wr, int wc, int fr, int fq, const EpiCtx& X) const {
;     ...
;                 const f32x4 o0a = acc[ai][0][m][0], o0b = acc[ai][0][m][1], o1a = acc[ai][1][m][0], o1b = acc[ai][1][m][1];
;                 const f32x4 ra_ = dpp_swap1(odd ? o0a : o1a), rb_ = dpp_swap1(odd ? o0b : o1b);
;                 const f32x4 pa[2] = {odd ? ra_ : o0a, odd ? o1a : ra_}, pb[2] = {odd ? rb_ : o0b, odd ? o1b : rb_};
; #pragma unroll
;                 for (int q = 0; q < 2; ++q) {
;                     const u32x4 w0 = raw[2 * m + q];
;                     const f32x4 r0 = (f32x4){bf_lo(w0.x), bf_hi(w0.x), bf_lo(w0.y), bf_hi(w0.y)}, r1 = (f32x4){bf_lo(w0.z), bf_hi(w0.z), bf_lo(w0.w), bf_hi(w0.w)};
;                     f32x4 y0, y1;
;                     if (RESN) { const f32x2 t = tbl[rl + q]; const float mu = t.x, ra = t.y * ALPHA; y0 = (r0 - mu) * ra * g0 + b0 + pa[q]; y1 = (r1 - mu) * ra * g1 + b1 + pb[q]; }
;                     else { y0 = r0 * ALPHA + pa[q]; y1 = r1 * ALPHA + pb[q]; }
;                     { const u32x4 w = pack8f(y0, y1); *(u32x4*)(xb + off + q * 128) = w;
;                         y0 = (f32x4){bf_lo(w.x), bf_hi(w.x), bf_lo(w.y), bf_hi(w.y)}; y1 = (f32x4){bf_lo(w.z), bf_hi(w.z), bf_lo(w.w), bf_hi(w.w)}; }
;                     float sa = ((y0[0] + y0[1]) + (y0[2] + y0[3])) + ((y1[0] + y1[1]) + (y1[2] + y1[3]));
;                     float sb = ((y0[0] * y0[0] + y0[1] * y0[1]) + (y0[2] * y0[2] + y0[3] * y0[3])) + ((y1[0] * y1[0] + y1[1] * y1[1]) + (y1[2] * y1[2] + y1[3] * y1[3]));
;                     sa += dpp_x1(sa);
;                     sb += dpp_x1(sb);
;                     sa += __shfl_xor(sa, 16); sa += __shfl_xor(sa, 32); sb += __shfl_xor(sb, 16); sb += __shfl_xor(sb, 32);
;                     if (fq == 0 && !odd) ps[(size_t)(rl + q) * 64] = (f32x2){sa, sb};
.LBB0_844:
	s_or_b64 exec, exec, s[68:69]
	s_waitcnt lgkmcnt(0)
	v_cndmask_b32_e64 v18, v12, v4, s[10:11]
	s_nop 0
	v_cndmask_b32_e64 v17, v13, v5, s[10:11]
	s_waitcnt lgkmcnt(0)
	v_cndmask_b32_e64 v19, v14, v6, s[10:11]
	v_mov_b32_dpp v16, v18 quad_perm:[1,0,3,2] row_mask:0xf bank_mask:0xf
	s_nop 0
	v_cndmask_b32_e64 v20, v15, v7, s[10:11]
	v_cndmask_b32_e64 v22, v8, v0, s[10:11]
	v_mov_b32_dpp v18, v17 quad_perm:[1,0,3,2] row_mask:0xf bank_mask:0xf
	s_nop 0
	v_cndmask_b32_e64 v21, v9, v1, s[10:11]
	v_cndmask_b32_e64 v23, v10, v2, s[10:11]
	v_mov_b32_dpp v17, v19 quad_perm:[1,0,3,2] row_mask:0xf bank_mask:0xf
	s_nop 0
	v_cndmask_b32_e64 v24, v11, v3, s[10:11]
	s_waitcnt vmcnt(13)
	v_lshlrev_b32_e32 v27, 16, v68
	v_mov_b32_dpp v19, v20 quad_perm:[1,0,3,2] row_mask:0xf bank_mask:0xf
	s_nop 0
	v_and_b32_e32 v28, 0xffff0000, v68
	v_cndmask_b32_e64 v13, v18, v13, s[10:11]
	v_mov_b32_dpp v20, v22 quad_perm:[1,0,3,2] row_mask:0xf bank_mask:0xf
	s_nop 0
	v_cndmask_b32_e64 v12, v16, v12, s[10:11]
	v_lshlrev_b32_e32 v30, 16, v69
	v_mov_b32_dpp v22, v21 quad_perm:[1,0,3,2] row_mask:0xf bank_mask:0xf
	s_nop 0
	v_and_b32_e32 v31, 0xffff0000, v69
	v_lshlrev_b32_e32 v32, 16, v70
	v_mov_b32_dpp v21, v23 quad_perm:[1,0,3,2] row_mask:0xf bank_mask:0xf
	s_nop 0
	v_and_b32_e32 v33, 0xffff0000, v70
	v_lshlrev_b32_e32 v34, 16, v71
	v_mov_b32_dpp v23, v24 quad_perm:[1,0,3,2] row_mask:0xf bank_mask:0xf
	ds_read_b64 v[24:25], v201 offset:1408
	v_and_b32_e32 v35, 0xffff0000, v71
	v_cndmask_b32_e64 v15, v19, v15, s[10:11]
	v_cndmask_b32_e64 v14, v17, v14, s[10:11]
	v_cndmask_b32_e64 v9, v22, v9, s[10:11]
	s_waitcnt lgkmcnt(0)
	v_mul_f32_e32 v26, 0x3fb504f3, v25
	v_sub_f32_e32 v29, v28, v24
	v_sub_f32_e32 v28, v27, v24
	v_pk_mul_f32 v[28:29], v[28:29], v[26:27] op_sel_hi:[1,0]
	v_sub_f32_e32 v31, v31, v24
	v_pk_fma_f32 v[28:29], v[76:77], v[28:29], v[184:185]
	v_sub_f32_e32 v30, v30, v24
	v_pk_add_f32 v[12:13], v[12:13], v[28:29]
	v_sub_f32_e32 v29, v33, v24
	v_sub_f32_e32 v28, v32, v24
	v_sub_f32_e32 v25, v35, v24
	v_sub_f32_e32 v24, v34, v24
	v_pk_mul_f32 v[30:31], v[30:31], v[26:27] op_sel_hi:[1,0]
	v_pk_mul_f32 v[24:25], v[24:25], v[26:27] op_sel_hi:[1,0]
	v_pk_mul_f32 v[26:27], v[28:29], v[26:27] op_sel_hi:[1,0]
	v_cndmask_b32_e64 v8, v20, v8, s[10:11]
	v_cndmask_b32_e64 v11, v23, v11, s[10:11]
	v_cndmask_b32_e64 v10, v21, v10, s[10:11]
	v_pk_fma_f32 v[30:31], v[78:79], v[30:31], v[182:183]
	v_pk_fma_f32 v[26:27], v[72:73], v[26:27], v[180:181]
	v_pk_fma_f32 v[24:25], v[74:75], v[24:25], v[178:179]
	v_pk_add_f32 v[14:15], v[14:15], v[30:31]
	v_pk_add_f32 v[10:11], v[10:11], v[24:25]
	v_pk_add_f32 v[8:9], v[8:9], v[26:27]
	v_cvt_pk_bf16_f32 v24, v12, v13
	v_cvt_pk_bf16_f32 v25, v14, v15
	s_nop 0
	v_cvt_pk_bf16_f32 v26, v8, v9
	v_cvt_pk_bf16_f32 v27, v10, v11
	v_lshlrev_b32_e32 v8, 16, v24
	v_and_b32_e32 v10, 0xffff0000, v24
	v_lshlrev_b32_e32 v12, 16, v25
	v_and_b32_e32 v14, 0xffff0000, v25
	v_lshlrev_b32_e32 v28, 16, v26
	v_and_b32_e32 v30, 0xffff0000, v26
	v_lshlrev_b32_e32 v32, 16, v27
	v_and_b32_e32 v34, 0xffff0000, v27
	v_mul_f32_e32 v9, v8, v8
	v_mul_f32_e32 v11, v10, v10
	v_mul_f32_e32 v13, v12, v12
	v_mul_f32_e32 v15, v14, v14
	v_mul_f32_e32 v29, v28, v28
	v_mul_f32_e32 v31, v30, v30
	v_mul_f32_e32 v33, v32, v32
	v_mul_f32_e32 v35, v34, v34
	v_pk_add_f32 v[8:9], v[8:9], v[10:11]
	v_pk_add_f32 v[10:11], v[12:13], v[14:15]
	v_pk_add_f32 v[12:13], v[32:33], v[34:35]
	v_pk_add_f32 v[8:9], v[8:9], v[10:11]
	v_pk_add_f32 v[10:11], v[28:29], v[30:31]
	s_nop 0
	v_pk_add_f32 v[10:11], v[10:11], v[12:13]
	s_nop 0
	v_pk_add_f32 v[8:9], v[8:9], v[10:11]
	v_mov_b32_e32 v10, v165
	v_mov_b32_e32 v11, v165
	s_nop 0
	v_mov_b32_dpp v10, v8 quad_perm:[1,0,3,2] row_mask:0xf bank_mask:0xf
	v_mov_b32_dpp v11, v9 quad_perm:[1,0,3,2] row_mask:0xf bank_mask:0xf
	v_pk_add_f32 v[8:9], v[8:9], v[10:11]
	v_mov_b32_e32 v10, v8
	v_mov_b32_e32 v11, v9
	s_nop 1
	v_permlane16_swap_b32_e32 v8, v10
	v_permlane16_swap_b32_e32 v9, v11
	s_waitcnt lgkmcnt(0)
	v_pk_add_f32 v[10:11], v[8:9], v[10:11]
	v_mov_b32_e32 v12, v10
	v_mov_b32_e32 v13, v11
	s_nop 1
	v_permlane32_swap_b32_e32 v10, v12
	v_permlane32_swap_b32_e32 v11, v13
	v_lshl_add_u64 v[8:9], s[20:21], 0, v[164:165]
	global_store_dwordx4 v[8:9], v[24:27], off
	s_and_saveexec_b64 s[20:21], s[16:17]
	s_cbranch_execz .LBB0_846
	s_waitcnt lgkmcnt(0)
	v_pk_add_f32 v[10:11], v[10:11], v[12:13]
	v_add_co_u32_e32 v12, vcc, 0x16000, v186
	s_nop 1
	v_addc_co_u32_e32 v13, vcc, 0, v187, vcc
	global_store_dwordx2 v[12:13], v[10:11], off

; #define LAS __attribute__((address_space(3)))
;     __device__ __forceinline__ void operator()(const f32x4 (&acc)[2][2][4][2], const Unit& u, int wr, int wc, int fr, int fq, const EpiCtx& X) const {
;     ...
;         char* yb = nullptr; char* xb = (char*)(XB + (size_t)u.pm * BM * DM + (size_t)(u.pn * 4 + wc) * (BM * 64));
;         unsigned lo = (unsigned)((wr * 64 + fe) * 64 + o32 + 8 * fq) * 2u; EPI_OPAQUE(lo);
;         const int col = u.pn * BM + wc * 64 + o32 + 8 * fq;
;         f32x4 g0, g1, b0, b1;
;         if (RESN) { ensure_tbl(PSp, sidp, u.pm, X);
;             g0 = *(const f32x4*)(gp + col); g1 = *(const f32x4*)(gp + col + 4); b0 = *(const f32x4*)(bp + col) * ALPHA; b1 = *(const f32x4*)(bp + col + 4) * ALPHA; }
;         const LAS f32x2* tbl = (const LAS f32x2*)(X.lds + TBL_OFF) + wr * 64 + fe;
;         f32x2* ps = PSn + ((size_t)u.pm * BM + wr * 64 + fe) * 64 + u.pn * 4 + wc;
; #pragma unroll
;         for (int ai = 0; ai < 2; ++ai) {
;             u32x4 raw[8];
; #pragma unroll
;             for (int m = 0; m < 4; ++m) { const unsigned off = lo + (unsigned)((ai * HALF + m * 16) * 64) * 2u; raw[2 * m] = *(const u32x4*)(xb + off); raw[2 * m + 1] = *(const u32x4*)(xb + off + 128); }
; #pragma unroll
;             for (int m = 0; m < 4; ++m) {
;                 const int rl = ai * HALF + m * 16; const unsigned off = lo + (unsigned)(rl * 64) * 2u;
;                 const f32x4 o0a = acc[ai][0][m][0], o0b = acc[ai][0][m][1], o1a = acc[ai][1][m][0], o1b = acc[ai][1][m][1];
;                 const f32x4 ra_ = dpp_swap1(odd ? o0a : o1a), rb_ = dpp_swap1(odd ? o0b : o1b);
;                 const f32x4 pa[2] = {odd ? ra_ : o0a, odd ? o1a : ra_}, pb[2] = {odd ? rb_ : o0b, odd ? o1b : rb_};
; #pragma unroll
;                 for (int q = 0; q < 2; ++q) {
;                     const u32x4 w0 = raw[2 * m + q];
;                     const f32x4 r0 = (f32x4){bf_lo(w0.x), bf_hi(w0.x), bf_lo(w0.y), bf_hi(w0.y)}, r1 = (f32x4){bf_lo(w0.z), bf_hi(w0.z), bf_lo(w0.w), bf_hi(w0.w)};
;                     f32x4 y0, y1;
;                     if (RESN) { const f32x2 t = tbl[rl + q]; const float mu = t.x, ra = t.y * ALPHA; y0 = (r0 - mu) * ra * g0 + b0 + pa[q]; y1 = (r1 - mu) * ra * g1 + b1 + pb[q]; }
;                     else { y0 = r0 * ALPHA + pa[q]; y1 = r1 * ALPHA + pb[q]; }
;                     { const u32x4 w = pack8f(y0, y1); *(u32x4*)(xb + off + q * 128) = w;
.LBB0_1463:
	s_lshl_b64 s[4:5], s[66:67], 21
	s_add_u32 s20, s51, s4
	s_addc_u32 s21, s53, s5
	s_lshl_b32 s66, s64, 2
	s_or_b32 s4, s66, s41
	s_ashr_i32 s5, s4, 31
	v_lshl_add_u32 v72, s64, 8, v200
	v_ashrrev_i32_e32 v73, 31, v72
	s_lshl_b64 s[4:5], s[4:5], 15
	v_lshlrev_b64 v[72:73], 2, v[72:73]
	s_add_u32 s20, s20, s4
	v_lshl_add_u64 v[74:75], s[26:27], 0, v[72:73]
	s_addc_u32 s21, s21, s5
	global_load_dwordx4 v[194:197], v[74:75], off offset:16
	global_load_dwordx4 v[178:181], v[74:75], off
	global_load_dwordx4 v[214:217], v164, s[20:21]
	v_lshl_add_u64 v[72:73], s[24:25], 0, v[72:73]
	s_waitcnt lgkmcnt(0)
	global_load_dwordx4 v[76:79], v[72:73], off
	s_nop 0
	global_load_dwordx4 v[72:75], v[72:73], off offset:16
	v_cndmask_b32_e64 v136, v135, v127, s[10:11]
	v_cndmask_b32_e64 v137, v134, v126, s[10:11]
	v_cndmask_b32_e64 v138, v133, v125, s[10:11]
	v_cndmask_b32_e64 v139, v132, v124, s[10:11]
	s_nop 0
	s_nop 0
	s_nop 0
	s_nop 0
	v_cndmask_b32_e64 v140, v131, v123, s[10:11]
	v_cndmask_b32_e64 v141, v130, v122, s[10:11]
	v_cndmask_b32_e64 v142, v129, v121, s[10:11]
	v_cndmask_b32_e64 v143, v128, v120, s[10:11]
	s_nop 0
	s_nop 0
	s_nop 0
	s_nop 0
	v_mov_b32_dpp v189, v139 quad_perm:[1,0,3,2] row_mask:0xf bank_mask:0xf
	v_mov_b32_dpp v193, v138 quad_perm:[1,0,3,2] row_mask:0xf bank_mask:0xf
	v_mov_b32_dpp v191, v137 quad_perm:[1,0,3,2] row_mask:0xf bank_mask:0xf
	v_mov_b32_dpp v209, v136 quad_perm:[1,0,3,2] row_mask:0xf bank_mask:0xf
	v_mov_b32_dpp v210, v143 quad_perm:[1,0,3,2] row_mask:0xf bank_mask:0xf
	v_mov_b32_dpp v212, v142 quad_perm:[1,0,3,2] row_mask:0xf bank_mask:0xf
	v_mov_b32_dpp v211, v141 quad_perm:[1,0,3,2] row_mask:0xf bank_mask:0xf
	v_mov_b32_dpp v213, v140 quad_perm:[1,0,3,2] row_mask:0xf bank_mask:0xf
	v_add_u32_e32 v192, 0x800, v164
	v_add_u32_e32 v190, 0x1000, v164
	v_add_u32_e32 v188, 0x1800, v164
	ds_read_b64 v[218:219], v201
	v_cndmask_b32_e64 v221, v193, v133, s[10:11]
	v_cndmask_b32_e64 v220, v189, v132, s[10:11]
	v_cndmask_b32_e64 v223, v209, v135, s[10:11]
	v_cndmask_b32_e64 v222, v191, v134, s[10:11]
	v_cndmask_b32_e64 v225, v212, v129, s[10:11]
	v_cndmask_b32_e64 v224, v210, v128, s[10:11]
	v_cndmask_b32_e64 v227, v213, v131, s[10:11]
	v_cndmask_b32_e64 v226, v211, v130, s[10:11]
	global_load_dwordx4 v[152:155], v164, s[20:21] offset:128
	global_load_dwordx4 v[148:151], v192, s[20:21]
	global_load_dwordx4 v[144:147], v192, s[20:21] offset:128
	global_load_dwordx4 v[140:143], v190, s[20:21]
	global_load_dwordx4 v[136:139], v190, s[20:21] offset:128
	global_load_dwordx4 v[132:135], v188, s[20:21]
	global_load_dwordx4 v[128:131], v188, s[20:21] offset:128
	s_waitcnt lgkmcnt(0)
	v_mul_f32_e32 v208, 0x3fb504f3, v219
	v_lshl_add_u64 v[186:187], v[166:167], 0, s[68:69]
	s_ashr_i32 s67, s66, 31
	v_lshl_add_u64 v[186:187], s[66:67], 3, v[186:187]
	v_lshl_add_u64 v[186:187], v[186:187], 0, s[22:23]
	v_add_u32_e32 v246, 0x4000, v164
	v_add_u32_e32 v247, 0x4800, v164
	global_load_dwordx4 v[230:233], v246, s[20:21]
	global_load_dwordx4 v[234:237], v246, s[20:21] offset:128
	global_load_dwordx4 v[238:241], v247, s[20:21]
	global_load_dwordx4 v[242:245], v247, s[20:21] offset:128
	s_waitcnt vmcnt(14)
	v_pk_mul_f32 v[182:183], v[180:181], s[52:53] op_sel_hi:[1,0]
	v_pk_mul_f32 v[184:185], v[178:179], s[52:53] op_sel_hi:[1,0]
	v_pk_mul_f32 v[178:179], v[196:197], s[52:53] op_sel_hi:[1,0]
	v_pk_mul_f32 v[180:181], v[194:195], s[52:53] op_sel_hi:[1,0]
	s_waitcnt vmcnt(13)
	v_lshlrev_b32_e32 v194, 16, v214
	v_and_b32_e32 v195, 0xffff0000, v214
	v_lshlrev_b32_e32 v196, 16, v215
	v_and_b32_e32 v197, 0xffff0000, v215
	v_lshlrev_b32_e32 v207, 16, v216
	v_and_b32_e32 v214, 0xffff0000, v216
	v_lshlrev_b32_e32 v216, 16, v217
	v_and_b32_e32 v217, 0xffff0000, v217
	v_sub_f32_e32 v195, v195, v218
	v_sub_f32_e32 v194, v194, v218
	v_sub_f32_e32 v197, v197, v218
	v_sub_f32_e32 v196, v196, v218
	v_sub_f32_e32 v215, v214, v218
	v_sub_f32_e32 v214, v207, v218
	v_sub_f32_e32 v217, v217, v218
	v_sub_f32_e32 v216, v216, v218
	v_pk_mul_f32 v[196:197], v[196:197], v[208:209] op_sel_hi:[1,0]
	v_pk_mul_f32 v[194:195], v[194:195], v[208:209] op_sel_hi:[1,0]
	v_pk_mul_f32 v[216:217], v[216:217], v[208:209] op_sel_hi:[1,0]
	v_pk_mul_f32 v[214:215], v[214:215], v[208:209] op_sel_hi:[1,0]
	s_waitcnt vmcnt(12)
	v_pk_fma_f32 v[194:195], v[76:77], v[194:195], v[184:185]
	v_pk_fma_f32 v[196:197], v[78:79], v[196:197], v[182:183]
	s_waitcnt vmcnt(11)
	v_pk_fma_f32 v[214:215], v[72:73], v[214:215], v[180:181]
	v_pk_fma_f32 v[216:217], v[74:75], v[216:217], v[178:179]
	v_pk_add_f32 v[196:197], v[222:223], v[196:197]
	v_pk_add_f32 v[194:195], v[220:221], v[194:195]
	v_pk_add_f32 v[218:219], v[226:227], v[216:217]
	v_pk_add_f32 v[216:217], v[224:225], v[214:215]
	v_cvt_pk_bf16_f32 v214, v194, v195
	v_cvt_pk_bf16_f32 v215, v196, v197
	v_and_b32_e32 v208, 64, v206
	v_cvt_pk_bf16_f32 v216, v216, v217
	v_cvt_pk_bf16_f32 v217, v218, v219
	v_lshlrev_b32_e32 v194, 16, v214
	v_and_b32_e32 v196, 0xffff0000, v214
	v_lshlrev_b32_e32 v218, 16, v215
	v_and_b32_e32 v220, 0xffff0000, v215
	v_lshlrev_b32_e32 v222, 16, v216
	v_and_b32_e32 v224, 0xffff0000, v216
	v_lshlrev_b32_e32 v226, 16, v217
	v_and_b32_e32 v228, 0xffff0000, v217
	v_mul_f32_e32 v195, v194, v194
	v_mul_f32_e32 v197, v196, v196
	v_mul_f32_e32 v219, v218, v218
	v_mul_f32_e32 v221, v220, v220
	v_mul_f32_e32 v223, v222, v222
	v_mul_f32_e32 v225, v224, v224
	v_mul_f32_e32 v227, v226, v226
	v_mul_f32_e32 v229, v228, v228
	v_pk_add_f32 v[194:195], v[194:195], v[196:197]
	v_pk_add_f32 v[196:197], v[218:219], v[220:221]
	v_pk_add_f32 v[218:219], v[226:227], v[228:229]
	v_pk_add_f32 v[194:195], v[194:195], v[196:197]
	v_pk_add_f32 v[196:197], v[222:223], v[224:225]
	v_xor_b32_e32 v207, 16, v206
	v_add_u32_e32 v208, 64, v208
	v_pk_add_f32 v[196:197], v[196:197], v[218:219]
	v_cmp_lt_i32_e32 vcc, v207, v208
	v_pk_add_f32 v[194:195], v[194:195], v[196:197]
	s_nop 0
	s_nop 0
	v_cndmask_b32_e32 v207, v206, v207, vcc
	v_mov_b32_dpp v196, v194 quad_perm:[1,0,3,2] row_mask:0xf bank_mask:0xf
	v_mov_b32_dpp v197, v195 quad_perm:[1,0,3,2] row_mask:0xf bank_mask:0xf
	v_lshlrev_b32_e32 v207, 2, v207
	v_pk_add_f32 v[194:195], v[194:195], v[196:197]
	v_mov_b32_e32 v196, v194
	v_mov_b32_e32 v197, v195
	s_nop 1
	v_permlane16_swap_b32_e32 v194, v196
	v_permlane16_swap_b32_e32 v195, v197
	v_xor_b32_e32 v218, 32, v206
	v_cmp_lt_i32_e32 vcc, v218, v208
	global_store_dwordx4 v164, v[214:217], s[20:21]
	s_waitcnt lgkmcnt(0)
	v_pk_add_f32 v[194:195], v[194:195], v[196:197]
	v_cndmask_b32_e32 v208, v206, v218, vcc
	v_lshlrev_b32_e32 v208, 2, v208
	v_mov_b32_e32 v196, v194
	v_mov_b32_e32 v197, v195
	s_nop 1
	v_permlane32_swap_b32_e32 v194, v196
	v_permlane32_swap_b32_e32 v195, v197
	s_and_saveexec_b64 s[64:65], s[16:17]
	s_waitcnt lgkmcnt(0)
	v_pk_add_f32 v[194:195], v[194:195], v[196:197]
	global_store_dwordx2 v[186:187], v[194:195], off

; __device__ __forceinline__ u32x4 pack8f(f32x4 a, f32x4 b) { u32x4 w; w.x = cvt_pk_bf16(a[0], a[1]); w.y = cvt_pk_bf16(a[2], a[3]); w.z = cvt_pk_bf16(b[0], b[1]); w.w = cvt_pk_bf16(b[2], b[3]); return w; }
; __device__ __forceinline__ float dpp_x1(float x) { return __builtin_bit_cast(float, __builtin_amdgcn_update_dpp(0, __builtin_bit_cast(int, x), 0xB1, 0xF, 0xF, false)); }
;     __device__ __forceinline__ void operator()(const f32x4 (&acc)[2][2][4][2], const Unit& u, int wr, int wc, int fr, int fq, const EpiCtx& X) const {
;     ...
;                 const f32x4 o0a = acc[ai][0][m][0], o0b = acc[ai][0][m][1], o1a = acc[ai][1][m][0], o1b = acc[ai][1][m][1];
;                 const f32x4 ra_ = dpp_swap1(odd ? o0a : o1a), rb_ = dpp_swap1(odd ? o0b : o1b);
;                 const f32x4 pa[2] = {odd ? ra_ : o0a, odd ? o1a : ra_}, pb[2] = {odd ? rb_ : o0b, odd ? o1b : rb_};
; #pragma unroll
;                 for (int q = 0; q < 2; ++q) {
;                     const u32x4 w0 = raw[2 * m + q];
;                     const f32x4 r0 = (f32x4){bf_lo(w0.x), bf_hi(w0.x), bf_lo(w0.y), bf_hi(w0.y)}, r1 = (f32x4){bf_lo(w0.z), bf_hi(w0.z), bf_lo(w0.w), bf_hi(w0.w)};
;                     f32x4 y0, y1;
;                     if (RESN) { const f32x2 t = tbl[rl + q]; const float mu = t.x, ra = t.y * ALPHA; y0 = (r0 - mu) * ra * g0 + b0 + pa[q]; y1 = (r1 - mu) * ra * g1 + b1 + pb[q]; }
;                     else { y0 = r0 * ALPHA + pa[q]; y1 = r1 * ALPHA + pb[q]; }
;                     { const u32x4 w = pack8f(y0, y1); *(u32x4*)(xb + off + q * 128) = w;
;                         y0 = (f32x4){bf_lo(w.x), bf_hi(w.x), bf_lo(w.y), bf_hi(w.y)}; y1 = (f32x4){bf_lo(w.z), bf_hi(w.z), bf_lo(w.w), bf_hi(w.w)}; }
;                     float sa = ((y0[0] + y0[1]) + (y0[2] + y0[3])) + ((y1[0] + y1[1]) + (y1[2] + y1[3]));
;                     float sb = ((y0[0] * y0[0] + y0[1] * y0[1]) + (y0[2] * y0[2] + y0[3] * y0[3])) + ((y1[0] * y1[0] + y1[1] * y1[1]) + (y1[2] * y1[2] + y1[3] * y1[3]));
;                     sa += dpp_x1(sa);
;                     sb += dpp_x1(sb);
;                     sa += __shfl_xor(sa, 16); sa += __shfl_xor(sa, 32); sb += __shfl_xor(sb, 16); sb += __shfl_xor(sb, 32);
;                     if (fq == 0 && !odd) ps[(size_t)(rl + q) * 64] = (f32x2){sa, sb};
.LBB0_1467:
	s_or_b64 exec, exec, s[64:65]
	s_waitcnt lgkmcnt(0)
	v_cndmask_b32_e64 v122, v116, v108, s[10:11]
	s_nop 0
	v_cndmask_b32_e64 v121, v117, v109, s[10:11]
	s_waitcnt lgkmcnt(0)
	v_cndmask_b32_e64 v123, v118, v110, s[10:11]
	v_mov_b32_dpp v120, v122 quad_perm:[1,0,3,2] row_mask:0xf bank_mask:0xf
	s_nop 0
	v_cndmask_b32_e64 v124, v119, v111, s[10:11]
	v_cndmask_b32_e64 v126, v112, v104, s[10:11]
	v_mov_b32_dpp v122, v121 quad_perm:[1,0,3,2] row_mask:0xf bank_mask:0xf
	s_nop 0
	v_cndmask_b32_e64 v125, v113, v105, s[10:11]
	v_cndmask_b32_e64 v127, v114, v106, s[10:11]
	v_mov_b32_dpp v121, v123 quad_perm:[1,0,3,2] row_mask:0xf bank_mask:0xf
	s_nop 0
	v_cndmask_b32_e64 v152, v115, v107, s[10:11]
	s_waitcnt vmcnt(13)
	v_and_b32_e32 v153, 0xffff0000, v148
	v_mov_b32_dpp v123, v124 quad_perm:[1,0,3,2] row_mask:0xf bank_mask:0xf
	s_nop 0
	v_lshlrev_b32_e32 v154, 16, v149
	v_and_b32_e32 v155, 0xffff0000, v149
	v_mov_b32_dpp v124, v126 quad_perm:[1,0,3,2] row_mask:0xf bank_mask:0xf
	s_nop 0
	v_lshlrev_b32_e32 v189, 16, v150
	v_and_b32_e32 v191, 0xffff0000, v150
	v_mov_b32_dpp v126, v125 quad_perm:[1,0,3,2] row_mask:0xf bank_mask:0xf
	s_nop 0
	v_lshlrev_b32_e32 v193, 16, v151
	v_and_b32_e32 v151, 0xffff0000, v151
	v_mov_b32_dpp v125, v127 quad_perm:[1,0,3,2] row_mask:0xf bank_mask:0xf
	s_nop 0
	v_cndmask_b32_e64 v117, v122, v117, s[10:11]
	v_cndmask_b32_e64 v116, v120, v116, s[10:11]
	v_mov_b32_dpp v127, v152 quad_perm:[1,0,3,2] row_mask:0xf bank_mask:0xf
	v_lshlrev_b32_e32 v152, 16, v148
	ds_read_b64 v[148:149], v201 offset:128
	v_cndmask_b32_e64 v119, v123, v119, s[10:11]
	v_cndmask_b32_e64 v118, v121, v118, s[10:11]
	v_cndmask_b32_e64 v113, v126, v113, s[10:11]
	v_cndmask_b32_e64 v112, v124, v112, s[10:11]
	s_waitcnt lgkmcnt(0)
	v_mul_f32_e32 v150, 0x3fb504f3, v149
	v_sub_f32_e32 v153, v153, v148
	v_sub_f32_e32 v152, v152, v148
	v_pk_mul_f32 v[152:153], v[152:153], v[150:151] op_sel_hi:[1,0]
	v_sub_f32_e32 v155, v155, v148
	v_pk_fma_f32 v[152:153], v[76:77], v[152:153], v[184:185]
	v_sub_f32_e32 v154, v154, v148
	v_pk_add_f32 v[116:117], v[116:117], v[152:153]
	v_sub_f32_e32 v153, v191, v148
	v_sub_f32_e32 v152, v189, v148
	v_sub_f32_e32 v149, v151, v148
	v_sub_f32_e32 v148, v193, v148
	v_pk_mul_f32 v[154:155], v[154:155], v[150:151] op_sel_hi:[1,0]
	v_pk_mul_f32 v[148:149], v[148:149], v[150:151] op_sel_hi:[1,0]
	v_pk_mul_f32 v[150:151], v[152:153], v[150:151] op_sel_hi:[1,0]
	v_cndmask_b32_e64 v115, v127, v115, s[10:11]
	v_cndmask_b32_e64 v114, v125, v114, s[10:11]
	v_pk_fma_f32 v[154:155], v[78:79], v[154:155], v[182:183]
	v_pk_fma_f32 v[150:151], v[72:73], v[150:151], v[180:181]
	v_pk_fma_f32 v[148:149], v[74:75], v[148:149], v[178:179]
	v_pk_add_f32 v[118:119], v[118:119], v[154:155]
	v_pk_add_f32 v[114:115], v[114:115], v[148:149]
	v_pk_add_f32 v[112:113], v[112:113], v[150:151]
	v_cvt_pk_bf16_f32 v148, v116, v117
	v_cvt_pk_bf16_f32 v149, v118, v119
	v_mov_b32_e32 v193, v165
	v_cvt_pk_bf16_f32 v150, v112, v113
	v_cvt_pk_bf16_f32 v151, v114, v115
	v_lshlrev_b32_e32 v112, 16, v148
	v_and_b32_e32 v114, 0xffff0000, v148
	v_lshlrev_b32_e32 v116, 16, v149
	v_and_b32_e32 v118, 0xffff0000, v149
	v_lshlrev_b32_e32 v152, 16, v150
	v_and_b32_e32 v154, 0xffff0000, v150
	v_lshlrev_b32_e32 v194, 16, v151
	v_and_b32_e32 v196, 0xffff0000, v151
	v_mul_f32_e32 v113, v112, v112
	v_mul_f32_e32 v115, v114, v114
	v_mul_f32_e32 v117, v116, v116
	v_mul_f32_e32 v119, v118, v118
	v_mul_f32_e32 v153, v152, v152
	v_mul_f32_e32 v155, v154, v154
	v_mul_f32_e32 v195, v194, v194
	v_mul_f32_e32 v197, v196, v196
	v_pk_add_f32 v[112:113], v[112:113], v[114:115]
	v_pk_add_f32 v[114:115], v[116:117], v[118:119]
	v_pk_add_f32 v[116:117], v[194:195], v[196:197]
	v_pk_add_f32 v[112:113], v[112:113], v[114:115]
	v_pk_add_f32 v[114:115], v[152:153], v[154:155]
	s_nop 0
	v_pk_add_f32 v[114:115], v[114:115], v[116:117]
	s_nop 0
	v_pk_add_f32 v[112:113], v[112:113], v[114:115]
	v_mov_b32_e32 v114, v165
	v_mov_b32_e32 v115, v165
	s_nop 0
	v_mov_b32_dpp v114, v112 quad_perm:[1,0,3,2] row_mask:0xf bank_mask:0xf
	v_mov_b32_dpp v115, v113 quad_perm:[1,0,3,2] row_mask:0xf bank_mask:0xf
	v_pk_add_f32 v[112:113], v[112:113], v[114:115]
	v_mov_b32_e32 v114, v112
	v_mov_b32_e32 v115, v113
	s_nop 1
	v_permlane16_swap_b32_e32 v112, v114
	v_permlane16_swap_b32_e32 v113, v115
	s_waitcnt lgkmcnt(0)
	v_pk_add_f32 v[114:115], v[112:113], v[114:115]
	v_mov_b32_e32 v116, v114
	v_mov_b32_e32 v117, v115
	s_nop 1
	v_permlane32_swap_b32_e32 v114, v116
	v_permlane32_swap_b32_e32 v115, v117
	v_lshl_add_u64 v[112:113], s[20:21], 0, v[192:193]
	global_store_dwordx4 v[112:113], v[148:151], off
	s_and_saveexec_b64 s[64:65], s[16:17]
	s_waitcnt lgkmcnt(0)
	v_pk_add_f32 v[114:115], v[114:115], v[116:117]
	v_add_co_u32_e32 v116, vcc, 0x2000, v186
	s_nop 1
	v_addc_co_u32_e32 v117, vcc, 0, v187, vcc
	global_store_dwordx2 v[116:117], v[114:115], off

; __device__ __forceinline__ u32x4 pack8f(f32x4 a, f32x4 b) { u32x4 w; w.x = cvt_pk_bf16(a[0], a[1]); w.y = cvt_pk_bf16(a[2], a[3]); w.z = cvt_pk_bf16(b[0], b[1]); w.w = cvt_pk_bf16(b[2], b[3]); return w; }
; __device__ __forceinline__ float dpp_x1(float x) { return __builtin_bit_cast(float, __builtin_amdgcn_update_dpp(0, __builtin_bit_cast(int, x), 0xB1, 0xF, 0xF, false)); }
;     __device__ __forceinline__ void operator()(const f32x4 (&acc)[2][2][4][2], const Unit& u, int wr, int wc, int fr, int fq, const EpiCtx& X) const {
;     ...
;                 const f32x4 o0a = acc[ai][0][m][0], o0b = acc[ai][0][m][1], o1a = acc[ai][1][m][0], o1b = acc[ai][1][m][1];
;                 const f32x4 ra_ = dpp_swap1(odd ? o0a : o1a), rb_ = dpp_swap1(odd ? o0b : o1b);
;                 const f32x4 pa[2] = {odd ? ra_ : o0a, odd ? o1a : ra_}, pb[2] = {odd ? rb_ : o0b, odd ? o1b : rb_};
; #pragma unroll
;                 for (int q = 0; q < 2; ++q) {
;                     const u32x4 w0 = raw[2 * m + q];
;                     const f32x4 r0 = (f32x4){bf_lo(w0.x), bf_hi(w0.x), bf_lo(w0.y), bf_hi(w0.y)}, r1 = (f32x4){bf_lo(w0.z), bf_hi(w0.z), bf_lo(w0.w), bf_hi(w0.w)};
;                     f32x4 y0, y1;
;                     if (RESN) { const f32x2 t = tbl[rl + q]; const float mu = t.x, ra = t.y * ALPHA; y0 = (r0 - mu) * ra * g0 + b0 + pa[q]; y1 = (r1 - mu) * ra * g1 + b1 + pb[q]; }
;                     else { y0 = r0 * ALPHA + pa[q]; y1 = r1 * ALPHA + pb[q]; }
;                     { const u32x4 w = pack8f(y0, y1); *(u32x4*)(xb + off + q * 128) = w;
;                         y0 = (f32x4){bf_lo(w.x), bf_hi(w.x), bf_lo(w.y), bf_hi(w.y)}; y1 = (f32x4){bf_lo(w.z), bf_hi(w.z), bf_lo(w.w), bf_hi(w.w)}; }
;                     float sa = ((y0[0] + y0[1]) + (y0[2] + y0[3])) + ((y1[0] + y1[1]) + (y1[2] + y1[3]));
;                     float sb = ((y0[0] * y0[0] + y0[1] * y0[1]) + (y0[2] * y0[2] + y0[3] * y0[3])) + ((y1[0] * y1[0] + y1[1] * y1[1]) + (y1[2] * y1[2] + y1[3] * y1[3]));
;                     sa += dpp_x1(sa);
;                     sb += dpp_x1(sb);
;                     sa += __shfl_xor(sa, 16); sa += __shfl_xor(sa, 32); sb += __shfl_xor(sb, 16); sb += __shfl_xor(sb, 32);
;                     if (fq == 0 && !odd) ps[(size_t)(rl + q) * 64] = (f32x2){sa, sb};
.LBB0_1471:
	s_or_b64 exec, exec, s[64:65]
	s_waitcnt lgkmcnt(0)
	v_cndmask_b32_e64 v106, v100, v92, s[10:11]
	s_nop 0
	v_cndmask_b32_e64 v105, v101, v93, s[10:11]
	s_waitcnt lgkmcnt(0)
	v_cndmask_b32_e64 v107, v102, v94, s[10:11]
	v_mov_b32_dpp v104, v106 quad_perm:[1,0,3,2] row_mask:0xf bank_mask:0xf
	s_nop 0
	v_cndmask_b32_e64 v108, v103, v95, s[10:11]
	v_cndmask_b32_e64 v110, v96, v88, s[10:11]
	v_mov_b32_dpp v106, v105 quad_perm:[1,0,3,2] row_mask:0xf bank_mask:0xf
	s_nop 0
	v_cndmask_b32_e64 v109, v97, v89, s[10:11]
	v_cndmask_b32_e64 v111, v98, v90, s[10:11]
	v_mov_b32_dpp v105, v107 quad_perm:[1,0,3,2] row_mask:0xf bank_mask:0xf
	s_nop 0
	v_cndmask_b32_e64 v112, v99, v91, s[10:11]
	s_waitcnt vmcnt(15)
	v_lshlrev_b32_e32 v115, 16, v140
	v_mov_b32_dpp v107, v108 quad_perm:[1,0,3,2] row_mask:0xf bank_mask:0xf
	s_nop 0
	v_and_b32_e32 v116, 0xffff0000, v140
	v_cndmask_b32_e64 v101, v106, v101, s[10:11]
	v_mov_b32_dpp v108, v110 quad_perm:[1,0,3,2] row_mask:0xf bank_mask:0xf
	s_nop 0
	v_cndmask_b32_e64 v100, v104, v100, s[10:11]
	v_lshlrev_b32_e32 v118, 16, v141
	v_mov_b32_dpp v110, v109 quad_perm:[1,0,3,2] row_mask:0xf bank_mask:0xf
	s_nop 0
	v_and_b32_e32 v119, 0xffff0000, v141
	v_lshlrev_b32_e32 v120, 16, v142
	v_mov_b32_dpp v109, v111 quad_perm:[1,0,3,2] row_mask:0xf bank_mask:0xf
	s_nop 0
	v_and_b32_e32 v121, 0xffff0000, v142
	v_lshlrev_b32_e32 v122, 16, v143
	v_mov_b32_dpp v111, v112 quad_perm:[1,0,3,2] row_mask:0xf bank_mask:0xf
	ds_read_b64 v[112:113], v201 offset:256
	v_and_b32_e32 v123, 0xffff0000, v143
	v_cndmask_b32_e64 v103, v107, v103, s[10:11]
	v_cndmask_b32_e64 v102, v105, v102, s[10:11]
	v_cndmask_b32_e64 v97, v110, v97, s[10:11]
	s_waitcnt lgkmcnt(0)
	v_mul_f32_e32 v114, 0x3fb504f3, v113
	v_sub_f32_e32 v117, v116, v112
	v_sub_f32_e32 v116, v115, v112
	v_pk_mul_f32 v[116:117], v[116:117], v[114:115] op_sel_hi:[1,0]
	v_sub_f32_e32 v119, v119, v112
	v_pk_fma_f32 v[116:117], v[76:77], v[116:117], v[184:185]
	v_sub_f32_e32 v118, v118, v112
	v_pk_add_f32 v[100:101], v[100:101], v[116:117]
	v_sub_f32_e32 v117, v121, v112
	v_sub_f32_e32 v116, v120, v112
	v_sub_f32_e32 v113, v123, v112
	v_sub_f32_e32 v112, v122, v112
	v_pk_mul_f32 v[118:119], v[118:119], v[114:115] op_sel_hi:[1,0]
	v_pk_mul_f32 v[112:113], v[112:113], v[114:115] op_sel_hi:[1,0]
	v_pk_mul_f32 v[114:115], v[116:117], v[114:115] op_sel_hi:[1,0]
	v_cndmask_b32_e64 v96, v108, v96, s[10:11]
	v_cndmask_b32_e64 v99, v111, v99, s[10:11]
	v_cndmask_b32_e64 v98, v109, v98, s[10:11]
	v_pk_fma_f32 v[118:119], v[78:79], v[118:119], v[182:183]
	v_pk_fma_f32 v[114:115], v[72:73], v[114:115], v[180:181]
	v_pk_fma_f32 v[112:113], v[74:75], v[112:113], v[178:179]
	v_pk_add_f32 v[102:103], v[102:103], v[118:119]
	v_pk_add_f32 v[98:99], v[98:99], v[112:113]
	v_pk_add_f32 v[96:97], v[96:97], v[114:115]
	v_cvt_pk_bf16_f32 v112, v100, v101
	v_cvt_pk_bf16_f32 v113, v102, v103
	v_mov_b32_e32 v191, v165
	v_cvt_pk_bf16_f32 v114, v96, v97
	v_cvt_pk_bf16_f32 v115, v98, v99
	v_lshlrev_b32_e32 v96, 16, v112
	v_and_b32_e32 v98, 0xffff0000, v112
	v_lshlrev_b32_e32 v100, 16, v113
	v_and_b32_e32 v102, 0xffff0000, v113
	v_lshlrev_b32_e32 v116, 16, v114
	v_and_b32_e32 v118, 0xffff0000, v114
	v_lshlrev_b32_e32 v120, 16, v115
	v_and_b32_e32 v122, 0xffff0000, v115
	v_mul_f32_e32 v97, v96, v96
	v_mul_f32_e32 v99, v98, v98
	v_mul_f32_e32 v101, v100, v100
	v_mul_f32_e32 v103, v102, v102
	v_mul_f32_e32 v117, v116, v116
	v_mul_f32_e32 v119, v118, v118
	v_mul_f32_e32 v121, v120, v120
	v_mul_f32_e32 v123, v122, v122
	v_pk_add_f32 v[96:97], v[96:97], v[98:99]
	v_pk_add_f32 v[98:99], v[100:101], v[102:103]
	v_pk_add_f32 v[100:101], v[120:121], v[122:123]
	v_pk_add_f32 v[96:97], v[96:97], v[98:99]
	v_pk_add_f32 v[98:99], v[116:117], v[118:119]
	s_nop 0
	v_pk_add_f32 v[98:99], v[98:99], v[100:101]
	s_nop 0
	v_pk_add_f32 v[96:97], v[96:97], v[98:99]
	v_mov_b32_e32 v98, v165
	v_mov_b32_e32 v99, v165
	s_nop 0
	v_mov_b32_dpp v98, v96 quad_perm:[1,0,3,2] row_mask:0xf bank_mask:0xf
	v_mov_b32_dpp v99, v97 quad_perm:[1,0,3,2] row_mask:0xf bank_mask:0xf
	v_pk_add_f32 v[96:97], v[96:97], v[98:99]
	v_mov_b32_e32 v98, v96
	v_mov_b32_e32 v99, v97
	s_nop 1
	v_permlane16_swap_b32_e32 v96, v98
	v_permlane16_swap_b32_e32 v97, v99
	s_waitcnt lgkmcnt(0)
	v_pk_add_f32 v[98:99], v[96:97], v[98:99]
	v_mov_b32_e32 v100, v98
	v_mov_b32_e32 v101, v99
	s_nop 1
	v_permlane32_swap_b32_e32 v98, v100
	v_permlane32_swap_b32_e32 v99, v101
	v_lshl_add_u64 v[96:97], s[20:21], 0, v[190:191]
	global_store_dwordx4 v[96:97], v[112:115], off
	s_and_saveexec_b64 s[64:65], s[16:17]
	s_waitcnt lgkmcnt(0)
	v_pk_add_f32 v[98:99], v[98:99], v[100:101]
	v_add_co_u32_e32 v100, vcc, 0x4000, v186
	s_nop 1
	v_addc_co_u32_e32 v101, vcc, 0, v187, vcc
	global_store_dwordx2 v[100:101], v[98:99], off

; __device__ __forceinline__ u32x4 pack8f(f32x4 a, f32x4 b) { u32x4 w; w.x = cvt_pk_bf16(a[0], a[1]); w.y = cvt_pk_bf16(a[2], a[3]); w.z = cvt_pk_bf16(b[0], b[1]); w.w = cvt_pk_bf16(b[2], b[3]); return w; }
; __device__ __forceinline__ float dpp_x1(float x) { return __builtin_bit_cast(float, __builtin_amdgcn_update_dpp(0, __builtin_bit_cast(int, x), 0xB1, 0xF, 0xF, false)); }
;     __device__ __forceinline__ void operator()(const f32x4 (&acc)[2][2][4][2], const Unit& u, int wr, int wc, int fr, int fq, const EpiCtx& X) const {
;     ...
;                 const f32x4 o0a = acc[ai][0][m][0], o0b = acc[ai][0][m][1], o1a = acc[ai][1][m][0], o1b = acc[ai][1][m][1];
;                 const f32x4 ra_ = dpp_swap1(odd ? o0a : o1a), rb_ = dpp_swap1(odd ? o0b : o1b);
;                 const f32x4 pa[2] = {odd ? ra_ : o0a, odd ? o1a : ra_}, pb[2] = {odd ? rb_ : o0b, odd ? o1b : rb_};
; #pragma unroll
;                 for (int q = 0; q < 2; ++q) {
;                     const u32x4 w0 = raw[2 * m + q];
;                     const f32x4 r0 = (f32x4){bf_lo(w0.x), bf_hi(w0.x), bf_lo(w0.y), bf_hi(w0.y)}, r1 = (f32x4){bf_lo(w0.z), bf_hi(w0.z), bf_lo(w0.w), bf_hi(w0.w)};
;                     f32x4 y0, y1;
;                     if (RESN) { const f32x2 t = tbl[rl + q]; const float mu = t.x, ra = t.y * ALPHA; y0 = (r0 - mu) * ra * g0 + b0 + pa[q]; y1 = (r1 - mu) * ra * g1 + b1 + pb[q]; }
;                     else { y0 = r0 * ALPHA + pa[q]; y1 = r1 * ALPHA + pb[q]; }
;                     { const u32x4 w = pack8f(y0, y1); *(u32x4*)(xb + off + q * 128) = w;
;                         y0 = (f32x4){bf_lo(w.x), bf_hi(w.x), bf_lo(w.y), bf_hi(w.y)}; y1 = (f32x4){bf_lo(w.z), bf_hi(w.z), bf_lo(w.w), bf_hi(w.w)}; }
;                     float sa = ((y0[0] + y0[1]) + (y0[2] + y0[3])) + ((y1[0] + y1[1]) + (y1[2] + y1[3]));
;                     float sb = ((y0[0] * y0[0] + y0[1] * y0[1]) + (y0[2] * y0[2] + y0[3] * y0[3])) + ((y1[0] * y1[0] + y1[1] * y1[1]) + (y1[2] * y1[2] + y1[3] * y1[3]));
;                     sa += dpp_x1(sa);
;                     sb += dpp_x1(sb);
;                     sa += __shfl_xor(sa, 16); sa += __shfl_xor(sa, 32); sb += __shfl_xor(sb, 16); sb += __shfl_xor(sb, 32);
;                     if (fq == 0 && !odd) ps[(size_t)(rl + q) * 64] = (f32x2){sa, sb};
.LBB0_1475:
	s_or_b64 exec, exec, s[64:65]
	s_waitcnt lgkmcnt(0)
	v_cndmask_b32_e64 v90, v84, v68, s[10:11]
	s_nop 0
	v_cndmask_b32_e64 v89, v85, v69, s[10:11]
	s_waitcnt lgkmcnt(0)
	v_cndmask_b32_e64 v91, v86, v70, s[10:11]
	v_mov_b32_dpp v88, v90 quad_perm:[1,0,3,2] row_mask:0xf bank_mask:0xf
	s_nop 0
	v_cndmask_b32_e64 v92, v87, v71, s[10:11]
	v_cndmask_b32_e64 v94, v80, v64, s[10:11]
	v_mov_b32_dpp v90, v89 quad_perm:[1,0,3,2] row_mask:0xf bank_mask:0xf
	s_nop 0
	v_cndmask_b32_e64 v93, v81, v65, s[10:11]
	v_cndmask_b32_e64 v95, v82, v66, s[10:11]
	v_mov_b32_dpp v89, v91 quad_perm:[1,0,3,2] row_mask:0xf bank_mask:0xf
	s_nop 0
	v_cndmask_b32_e64 v96, v83, v67, s[10:11]
	s_waitcnt vmcnt(17)
	v_lshlrev_b32_e32 v99, 16, v132
	v_mov_b32_dpp v91, v92 quad_perm:[1,0,3,2] row_mask:0xf bank_mask:0xf
	s_nop 0
	v_and_b32_e32 v100, 0xffff0000, v132
	v_cndmask_b32_e64 v85, v90, v85, s[10:11]
	v_mov_b32_dpp v92, v94 quad_perm:[1,0,3,2] row_mask:0xf bank_mask:0xf
	s_nop 0
	v_cndmask_b32_e64 v84, v88, v84, s[10:11]
	v_lshlrev_b32_e32 v102, 16, v133
	v_mov_b32_dpp v94, v93 quad_perm:[1,0,3,2] row_mask:0xf bank_mask:0xf
	s_nop 0
	v_and_b32_e32 v103, 0xffff0000, v133
	v_lshlrev_b32_e32 v104, 16, v134
	v_mov_b32_dpp v93, v95 quad_perm:[1,0,3,2] row_mask:0xf bank_mask:0xf
	s_nop 0
	v_and_b32_e32 v105, 0xffff0000, v134
	v_lshlrev_b32_e32 v106, 16, v135
	v_mov_b32_dpp v95, v96 quad_perm:[1,0,3,2] row_mask:0xf bank_mask:0xf
	ds_read_b64 v[96:97], v201 offset:384
	v_and_b32_e32 v107, 0xffff0000, v135
	v_cndmask_b32_e64 v87, v91, v87, s[10:11]
	v_cndmask_b32_e64 v86, v89, v86, s[10:11]
	v_cndmask_b32_e64 v81, v94, v81, s[10:11]
	s_waitcnt lgkmcnt(0)
	v_mul_f32_e32 v98, 0x3fb504f3, v97
	v_sub_f32_e32 v101, v100, v96
	v_sub_f32_e32 v100, v99, v96
	v_pk_mul_f32 v[100:101], v[100:101], v[98:99] op_sel_hi:[1,0]
	v_sub_f32_e32 v103, v103, v96
	v_pk_fma_f32 v[100:101], v[76:77], v[100:101], v[184:185]
	v_sub_f32_e32 v102, v102, v96
	v_pk_add_f32 v[84:85], v[84:85], v[100:101]
	v_sub_f32_e32 v101, v105, v96
	v_sub_f32_e32 v100, v104, v96
	v_sub_f32_e32 v97, v107, v96
	v_sub_f32_e32 v96, v106, v96
	v_pk_mul_f32 v[102:103], v[102:103], v[98:99] op_sel_hi:[1,0]
	v_pk_mul_f32 v[96:97], v[96:97], v[98:99] op_sel_hi:[1,0]
	v_pk_mul_f32 v[98:99], v[100:101], v[98:99] op_sel_hi:[1,0]
	v_cndmask_b32_e64 v80, v92, v80, s[10:11]
	v_cndmask_b32_e64 v83, v95, v83, s[10:11]
	v_cndmask_b32_e64 v82, v93, v82, s[10:11]
	v_pk_fma_f32 v[102:103], v[78:79], v[102:103], v[182:183]
	v_pk_fma_f32 v[98:99], v[72:73], v[98:99], v[180:181]
	v_pk_fma_f32 v[96:97], v[74:75], v[96:97], v[178:179]
	v_pk_add_f32 v[86:87], v[86:87], v[102:103]
	v_pk_add_f32 v[82:83], v[82:83], v[96:97]
	v_pk_add_f32 v[80:81], v[80:81], v[98:99]
	v_cvt_pk_bf16_f32 v96, v84, v85
	v_cvt_pk_bf16_f32 v97, v86, v87
	v_mov_b32_e32 v189, v165
	v_cvt_pk_bf16_f32 v98, v80, v81
	v_cvt_pk_bf16_f32 v99, v82, v83
	v_lshlrev_b32_e32 v80, 16, v96
	v_and_b32_e32 v82, 0xffff0000, v96
	v_lshlrev_b32_e32 v84, 16, v97
	v_and_b32_e32 v86, 0xffff0000, v97
	v_lshlrev_b32_e32 v100, 16, v98
	v_and_b32_e32 v102, 0xffff0000, v98
	v_lshlrev_b32_e32 v104, 16, v99
	v_and_b32_e32 v106, 0xffff0000, v99
	v_mul_f32_e32 v81, v80, v80
	v_mul_f32_e32 v83, v82, v82
	v_mul_f32_e32 v85, v84, v84
	v_mul_f32_e32 v87, v86, v86
	v_mul_f32_e32 v101, v100, v100
	v_mul_f32_e32 v103, v102, v102
	v_mul_f32_e32 v105, v104, v104
	v_mul_f32_e32 v107, v106, v106
	v_pk_add_f32 v[80:81], v[80:81], v[82:83]
	v_pk_add_f32 v[82:83], v[84:85], v[86:87]
	v_pk_add_f32 v[84:85], v[104:105], v[106:107]
	v_pk_add_f32 v[80:81], v[80:81], v[82:83]
	v_pk_add_f32 v[82:83], v[100:101], v[102:103]
	s_nop 0
	v_pk_add_f32 v[82:83], v[82:83], v[84:85]
	s_nop 0
	v_pk_add_f32 v[80:81], v[80:81], v[82:83]
	v_mov_b32_e32 v82, v165
	v_mov_b32_e32 v83, v165
	s_nop 0
	v_mov_b32_dpp v82, v80 quad_perm:[1,0,3,2] row_mask:0xf bank_mask:0xf
	v_mov_b32_dpp v83, v81 quad_perm:[1,0,3,2] row_mask:0xf bank_mask:0xf
	v_pk_add_f32 v[80:81], v[80:81], v[82:83]
	v_mov_b32_e32 v82, v80
	v_mov_b32_e32 v83, v81
	s_nop 1
	v_permlane16_swap_b32_e32 v80, v82
	v_permlane16_swap_b32_e32 v81, v83
	s_waitcnt lgkmcnt(0)
	v_pk_add_f32 v[82:83], v[80:81], v[82:83]
	v_mov_b32_e32 v84, v82
	v_mov_b32_e32 v85, v83
	s_nop 1
	v_permlane32_swap_b32_e32 v82, v84
	v_permlane32_swap_b32_e32 v83, v85
	v_lshl_add_u64 v[80:81], s[20:21], 0, v[188:189]
	global_store_dwordx4 v[80:81], v[96:99], off
	s_and_saveexec_b64 s[64:65], s[16:17]
	s_waitcnt lgkmcnt(0)
	v_pk_add_f32 v[82:83], v[82:83], v[84:85]
	v_add_co_u32_e32 v84, vcc, 0x6000, v186
	s_nop 1
	v_addc_co_u32_e32 v85, vcc, 0, v187, vcc
	global_store_dwordx2 v[84:85], v[82:83], off

;     __device__ __forceinline__ void operator()(const f32x4 (&acc)[2][2][4][2], const Unit& u, int wr, int wc, int fr, int fq, const EpiCtx& X) const {
;     ...
;             for (int m = 0; m < 4; ++m) { const unsigned off = lo + (unsigned)((ai * HALF + m * 16) * 64) * 2u; raw[2 * m] = *(const u32x4*)(xb + off); raw[2 * m + 1] = *(const u32x4*)(xb + off + 128); }
; #pragma unroll
;             for (int m = 0; m < 4; ++m) {
;                 const int rl = ai * HALF + m * 16; const unsigned off = lo + (unsigned)(rl * 64) * 2u;
;                 const f32x4 o0a = acc[ai][0][m][0], o0b = acc[ai][0][m][1], o1a = acc[ai][1][m][0], o1b = acc[ai][1][m][1];
;                 const f32x4 ra_ = dpp_swap1(odd ? o0a : o1a), rb_ = dpp_swap1(odd ? o0b : o1b);
;                 const f32x4 pa[2] = {odd ? ra_ : o0a, odd ? o1a : ra_}, pb[2] = {odd ? rb_ : o0b, odd ? o1b : rb_};
; #pragma unroll
;                 for (int q = 0; q < 2; ++q) {
;                     const u32x4 w0 = raw[2 * m + q];
;                     const f32x4 r0 = (f32x4){bf_lo(w0.x), bf_hi(w0.x), bf_lo(w0.y), bf_hi(w0.y)}, r1 = (f32x4){bf_lo(w0.z), bf_hi(w0.z), bf_lo(w0.w), bf_hi(w0.w)};
;                     f32x4 y0, y1;
;                     if (RESN) { const f32x2 t = tbl[rl + q]; const float mu = t.x, ra = t.y * ALPHA; y0 = (r0 - mu) * ra * g0 + b0 + pa[q]; y1 = (r1 - mu) * ra * g1 + b1 + pb[q]; }
;                     else { y0 = r0 * ALPHA + pa[q]; y1 = r1 * ALPHA + pb[q]; }
;                     { const u32x4 w = pack8f(y0, y1); *(u32x4*)(xb + off + q * 128) = w;
;                         y0 = (f32x4){bf_lo(w.x), bf_hi(w.x), bf_lo(w.y), bf_hi(w.y)}; y1 = (f32x4){bf_lo(w.z), bf_hi(w.z), bf_lo(w.w), bf_hi(w.w)}; }
;                     float sa = ((y0[0] + y0[1]) + (y0[2] + y0[3])) + ((y1[0] + y1[1]) + (y1[2] + y1[3]));
;                     float sb = ((y0[0] * y0[0] + y0[1] * y0[1]) + (y0[2] * y0[2] + y0[3] * y0[3])) + ((y1[0] * y1[0] + y1[1] * y1[1]) + (y1[2] * y1[2] + y1[3] * y1[3]));
;                     sa += dpp_x1(sa);
;                     sb += dpp_x1(sb);
;                     sa += __shfl_xor(sa, 16); sa += __shfl_xor(sa, 32); sb += __shfl_xor(sb, 16); sb += __shfl_xor(sb, 32);
;                     if (fq == 0 && !odd) ps[(size_t)(rl + q) * 64] = (f32x2){sa, sb};
.LBB0_1479:
	s_or_b64 exec, exec, s[64:65]
	v_add_u32_e32 v104, 0x4000, v164
	s_waitcnt vmcnt(16)
	v_mov_b32_e32 v112, v230
	v_mov_b32_e32 v113, v231
	v_mov_b32_e32 v114, v232
	v_mov_b32_e32 v115, v233
	v_add_u32_e32 v102, 0x4800, v164
	v_add_u32_e32 v100, 0x5000, v164
	v_add_u32_e32 v164, 0x5800, v164
	v_mov_b32_e32 v96, v234
	v_mov_b32_e32 v97, v235
	v_mov_b32_e32 v98, v236
	v_mov_b32_e32 v99, v237
	v_mov_b32_e32 v92, v238
	v_mov_b32_e32 v93, v239
	v_mov_b32_e32 v94, v240
	v_mov_b32_e32 v95, v241
	v_mov_b32_e32 v88, v242
	v_mov_b32_e32 v89, v243
	v_mov_b32_e32 v90, v244
	v_mov_b32_e32 v91, v245
	global_load_dwordx4 v[84:87], v100, s[20:21]
	global_load_dwordx4 v[80:83], v100, s[20:21] offset:128
	global_load_dwordx4 v[68:71], v164, s[20:21]
	s_waitcnt lgkmcnt(0)
	global_load_dwordx4 v[64:67], v164, s[20:21] offset:128
	v_cndmask_b32_e64 v116, v62, v54, s[10:11]
	v_cndmask_b32_e64 v117, v61, v53, s[10:11]
	s_nop 0
	s_nop 0
	v_cndmask_b32_e64 v111, v63, v55, s[10:11]
	v_mov_b32_dpp v105, v117 quad_perm:[1,0,3,2] row_mask:0xf bank_mask:0xf
	v_mov_b32_dpp v103, v116 quad_perm:[1,0,3,2] row_mask:0xf bank_mask:0xf
	ds_read_b64 v[116:117], v201 offset:1024
	v_cndmask_b32_e64 v118, v60, v52, s[10:11]
	s_nop 0
	s_nop 0
	v_cndmask_b32_e64 v119, v59, v51, s[10:11]
	v_cndmask_b32_e64 v120, v58, v50, s[10:11]
	v_cndmask_b32_e64 v121, v57, v49, s[10:11]
	v_cndmask_b32_e64 v122, v56, v48, s[10:11]
	s_nop 0
	s_nop 0
	s_nop 0
	s_nop 0
	v_mov_b32_dpp v101, v118 quad_perm:[1,0,3,2] row_mask:0xf bank_mask:0xf
	v_mov_b32_dpp v106, v111 quad_perm:[1,0,3,2] row_mask:0xf bank_mask:0xf
	v_mov_b32_dpp v107, v122 quad_perm:[1,0,3,2] row_mask:0xf bank_mask:0xf
	v_mov_b32_dpp v109, v121 quad_perm:[1,0,3,2] row_mask:0xf bank_mask:0xf
	v_mov_b32_dpp v108, v120 quad_perm:[1,0,3,2] row_mask:0xf bank_mask:0xf
	v_mov_b32_dpp v110, v119 quad_perm:[1,0,3,2] row_mask:0xf bank_mask:0xf
	s_waitcnt lgkmcnt(0)
	v_mul_f32_e32 v118, 0x3fb504f3, v117
	v_cndmask_b32_e64 v61, v105, v61, s[10:11]
	v_cndmask_b32_e64 v60, v101, v60, s[10:11]
	v_cndmask_b32_e64 v63, v106, v63, s[10:11]
	v_cndmask_b32_e64 v62, v103, v62, s[10:11]
	v_cndmask_b32_e64 v57, v109, v57, s[10:11]
	v_cndmask_b32_e64 v56, v107, v56, s[10:11]
	v_cndmask_b32_e64 v59, v110, v59, s[10:11]
	v_cndmask_b32_e64 v58, v108, v58, s[10:11]
	v_lshlrev_b32_e32 v111, 16, v112
	v_and_b32_e32 v112, 0xffff0000, v112
	v_lshlrev_b32_e32 v117, 16, v113
	v_and_b32_e32 v119, 0xffff0000, v113
	v_lshlrev_b32_e32 v120, 16, v114
	v_and_b32_e32 v121, 0xffff0000, v114
	v_lshlrev_b32_e32 v122, 16, v115
	v_and_b32_e32 v123, 0xffff0000, v115
	v_sub_f32_e32 v113, v112, v116
	v_sub_f32_e32 v112, v111, v116
	v_sub_f32_e32 v115, v119, v116
	v_sub_f32_e32 v114, v117, v116
	v_sub_f32_e32 v121, v121, v116
	v_sub_f32_e32 v120, v120, v116
	v_sub_f32_e32 v117, v123, v116
	v_sub_f32_e32 v116, v122, v116
	v_pk_mul_f32 v[114:115], v[114:115], v[118:119] op_sel_hi:[1,0]
	v_pk_mul_f32 v[112:113], v[112:113], v[118:119] op_sel_hi:[1,0]
	v_pk_mul_f32 v[116:117], v[116:117], v[118:119] op_sel_hi:[1,0]
	v_pk_mul_f32 v[118:119], v[120:121], v[118:119] op_sel_hi:[1,0]
	v_pk_fma_f32 v[112:113], v[76:77], v[112:113], v[184:185]
	v_pk_fma_f32 v[114:115], v[78:79], v[114:115], v[182:183]
	v_pk_fma_f32 v[118:119], v[72:73], v[118:119], v[180:181]
	v_pk_fma_f32 v[116:117], v[74:75], v[116:117], v[178:179]
	v_pk_add_f32 v[62:63], v[62:63], v[114:115]
	v_pk_add_f32 v[60:61], v[60:61], v[112:113]
	v_pk_add_f32 v[58:59], v[58:59], v[116:117]
	v_pk_add_f32 v[56:57], v[56:57], v[118:119]
	v_cvt_pk_bf16_f32 v60, v60, v61
	v_cvt_pk_bf16_f32 v61, v62, v63
	s_nop 0
	v_cvt_pk_bf16_f32 v62, v56, v57
	v_cvt_pk_bf16_f32 v63, v58, v59
	v_lshlrev_b32_e32 v56, 16, v60
	v_and_b32_e32 v58, 0xffff0000, v60
	v_lshlrev_b32_e32 v112, 16, v61
	v_and_b32_e32 v114, 0xffff0000, v61
	v_lshlrev_b32_e32 v116, 16, v62
	v_and_b32_e32 v118, 0xffff0000, v62
	v_lshlrev_b32_e32 v120, 16, v63
	v_and_b32_e32 v122, 0xffff0000, v63
	v_mul_f32_e32 v57, v56, v56
	v_mul_f32_e32 v59, v58, v58
	v_mul_f32_e32 v113, v112, v112
	v_mul_f32_e32 v115, v114, v114
	v_mul_f32_e32 v117, v116, v116
	v_mul_f32_e32 v119, v118, v118
	v_mul_f32_e32 v121, v120, v120
	v_mul_f32_e32 v123, v122, v122
	v_pk_add_f32 v[56:57], v[56:57], v[58:59]
	v_pk_add_f32 v[58:59], v[112:113], v[114:115]
	v_pk_add_f32 v[112:113], v[120:121], v[122:123]
	v_pk_add_f32 v[56:57], v[56:57], v[58:59]
	v_pk_add_f32 v[58:59], v[116:117], v[118:119]
	global_store_dwordx4 v104, v[60:63], s[20:21]
	v_pk_add_f32 v[58:59], v[58:59], v[112:113]
	s_nop 0
	v_pk_add_f32 v[56:57], v[56:57], v[58:59]
	v_mov_b32_e32 v58, v165
	v_mov_b32_e32 v59, v165
	s_nop 0
	v_mov_b32_dpp v58, v56 quad_perm:[1,0,3,2] row_mask:0xf bank_mask:0xf
	v_mov_b32_dpp v59, v57 quad_perm:[1,0,3,2] row_mask:0xf bank_mask:0xf
	v_pk_add_f32 v[56:57], v[56:57], v[58:59]
	v_mov_b32_e32 v58, v56
	v_mov_b32_e32 v59, v57
	s_nop 1
	v_permlane16_swap_b32_e32 v56, v58
	v_permlane16_swap_b32_e32 v57, v59
	s_waitcnt lgkmcnt(0)
	v_pk_add_f32 v[56:57], v[56:57], v[58:59]
	v_mov_b32_e32 v58, v56
	v_mov_b32_e32 v59, v57
	s_nop 1
	v_permlane32_swap_b32_e32 v56, v58
	v_permlane32_swap_b32_e32 v57, v59
	s_and_saveexec_b64 s[64:65], s[16:17]
	s_cbranch_execz .LBB0_1481
	s_waitcnt lgkmcnt(0)
	v_pk_add_f32 v[56:57], v[56:57], v[58:59]
	v_add_co_u32_e32 v58, vcc, 0x10000, v186
	s_nop 1
	v_addc_co_u32_e32 v59, vcc, 0, v187, vcc
	global_store_dwordx2 v[58:59], v[56:57], off

; __device__ __forceinline__ u32x4 pack8f(f32x4 a, f32x4 b) { u32x4 w; w.x = cvt_pk_bf16(a[0], a[1]); w.y = cvt_pk_bf16(a[2], a[3]); w.z = cvt_pk_bf16(b[0], b[1]); w.w = cvt_pk_bf16(b[2], b[3]); return w; }
; __device__ __forceinline__ float dpp_x1(float x) { return __builtin_bit_cast(float, __builtin_amdgcn_update_dpp(0, __builtin_bit_cast(int, x), 0xB1, 0xF, 0xF, false)); }
;     __device__ __forceinline__ void operator()(const f32x4 (&acc)[2][2][4][2], const Unit& u, int wr, int wc, int fr, int fq, const EpiCtx& X) const {
;     ...
;                 const f32x4 o0a = acc[ai][0][m][0], o0b = acc[ai][0][m][1], o1a = acc[ai][1][m][0], o1b = acc[ai][1][m][1];
;                 const f32x4 ra_ = dpp_swap1(odd ? o0a : o1a), rb_ = dpp_swap1(odd ? o0b : o1b);
;                 const f32x4 pa[2] = {odd ? ra_ : o0a, odd ? o1a : ra_}, pb[2] = {odd ? rb_ : o0b, odd ? o1b : rb_};
; #pragma unroll
;                 for (int q = 0; q < 2; ++q) {
;                     const u32x4 w0 = raw[2 * m + q];
;                     const f32x4 r0 = (f32x4){bf_lo(w0.x), bf_hi(w0.x), bf_lo(w0.y), bf_hi(w0.y)}, r1 = (f32x4){bf_lo(w0.z), bf_hi(w0.z), bf_lo(w0.w), bf_hi(w0.w)};
;                     f32x4 y0, y1;
;                     if (RESN) { const f32x2 t = tbl[rl + q]; const float mu = t.x, ra = t.y * ALPHA; y0 = (r0 - mu) * ra * g0 + b0 + pa[q]; y1 = (r1 - mu) * ra * g1 + b1 + pb[q]; }
;                     else { y0 = r0 * ALPHA + pa[q]; y1 = r1 * ALPHA + pb[q]; }
;                     { const u32x4 w = pack8f(y0, y1); *(u32x4*)(xb + off + q * 128) = w;
;                         y0 = (f32x4){bf_lo(w.x), bf_hi(w.x), bf_lo(w.y), bf_hi(w.y)}; y1 = (f32x4){bf_lo(w.z), bf_hi(w.z), bf_lo(w.w), bf_hi(w.w)}; }
;                     float sa = ((y0[0] + y0[1]) + (y0[2] + y0[3])) + ((y1[0] + y1[1]) + (y1[2] + y1[3]));
;                     float sb = ((y0[0] * y0[0] + y0[1] * y0[1]) + (y0[2] * y0[2] + y0[3] * y0[3])) + ((y1[0] * y1[0] + y1[1] * y1[1]) + (y1[2] * y1[2] + y1[3] * y1[3]));
;                     sa += dpp_x1(sa);
;                     sb += dpp_x1(sb);
;                     sa += __shfl_xor(sa, 16); sa += __shfl_xor(sa, 32); sb += __shfl_xor(sb, 16); sb += __shfl_xor(sb, 32);
;                     if (fq == 0 && !odd) ps[(size_t)(rl + q) * 64] = (f32x2){sa, sb};
.LBB0_1483:
	s_or_b64 exec, exec, s[64:65]
	s_waitcnt lgkmcnt(0)
	v_cndmask_b32_e64 v50, v44, v36, s[10:11]
	s_nop 0
	v_cndmask_b32_e64 v49, v45, v37, s[10:11]
	s_waitcnt lgkmcnt(0)
	v_cndmask_b32_e64 v51, v46, v38, s[10:11]
	v_mov_b32_dpp v48, v50 quad_perm:[1,0,3,2] row_mask:0xf bank_mask:0xf
	s_nop 0
	v_cndmask_b32_e64 v52, v47, v39, s[10:11]
	v_cndmask_b32_e64 v54, v40, v32, s[10:11]
	v_mov_b32_dpp v50, v49 quad_perm:[1,0,3,2] row_mask:0xf bank_mask:0xf
	s_nop 0
	v_cndmask_b32_e64 v53, v41, v33, s[10:11]
	v_cndmask_b32_e64 v55, v42, v34, s[10:11]
	v_mov_b32_dpp v49, v51 quad_perm:[1,0,3,2] row_mask:0xf bank_mask:0xf
	s_nop 0
	v_cndmask_b32_e64 v56, v43, v35, s[10:11]
	v_lshlrev_b32_e32 v59, 16, v92
	v_mov_b32_dpp v51, v52 quad_perm:[1,0,3,2] row_mask:0xf bank_mask:0xf
	s_nop 0
	v_and_b32_e32 v60, 0xffff0000, v92
	v_cndmask_b32_e64 v45, v50, v45, s[10:11]
	v_mov_b32_dpp v52, v54 quad_perm:[1,0,3,2] row_mask:0xf bank_mask:0xf
	s_nop 0
	v_cndmask_b32_e64 v44, v48, v44, s[10:11]
	v_lshlrev_b32_e32 v62, 16, v93
	v_mov_b32_dpp v54, v53 quad_perm:[1,0,3,2] row_mask:0xf bank_mask:0xf
	s_nop 0
	v_and_b32_e32 v63, 0xffff0000, v93
	v_lshlrev_b32_e32 v92, 16, v94
	v_mov_b32_dpp v53, v55 quad_perm:[1,0,3,2] row_mask:0xf bank_mask:0xf
	s_nop 0
	v_and_b32_e32 v93, 0xffff0000, v94
	v_lshlrev_b32_e32 v94, 16, v95
	v_mov_b32_dpp v55, v56 quad_perm:[1,0,3,2] row_mask:0xf bank_mask:0xf
	ds_read_b64 v[56:57], v201 offset:1152
	v_and_b32_e32 v95, 0xffff0000, v95
	v_cndmask_b32_e64 v47, v51, v47, s[10:11]
	v_cndmask_b32_e64 v46, v49, v46, s[10:11]
	v_cndmask_b32_e64 v41, v54, v41, s[10:11]
	s_waitcnt lgkmcnt(0)
	v_mul_f32_e32 v58, 0x3fb504f3, v57
	v_sub_f32_e32 v61, v60, v56
	v_sub_f32_e32 v60, v59, v56
	v_pk_mul_f32 v[60:61], v[60:61], v[58:59] op_sel_hi:[1,0]
	v_sub_f32_e32 v63, v63, v56
	v_pk_fma_f32 v[60:61], v[76:77], v[60:61], v[184:185]
	v_sub_f32_e32 v62, v62, v56
	v_pk_add_f32 v[44:45], v[44:45], v[60:61]
	v_sub_f32_e32 v61, v93, v56
	v_sub_f32_e32 v60, v92, v56
	v_sub_f32_e32 v57, v95, v56
	v_sub_f32_e32 v56, v94, v56
	v_pk_mul_f32 v[62:63], v[62:63], v[58:59] op_sel_hi:[1,0]
	v_pk_mul_f32 v[56:57], v[56:57], v[58:59] op_sel_hi:[1,0]
	v_pk_mul_f32 v[58:59], v[60:61], v[58:59] op_sel_hi:[1,0]
	v_cndmask_b32_e64 v40, v52, v40, s[10:11]
	v_cndmask_b32_e64 v43, v55, v43, s[10:11]
	v_cndmask_b32_e64 v42, v53, v42, s[10:11]
	v_pk_fma_f32 v[62:63], v[78:79], v[62:63], v[182:183]
	v_pk_fma_f32 v[58:59], v[72:73], v[58:59], v[180:181]
	v_pk_fma_f32 v[56:57], v[74:75], v[56:57], v[178:179]
	v_pk_add_f32 v[46:47], v[46:47], v[62:63]
	v_pk_add_f32 v[42:43], v[42:43], v[56:57]
	v_pk_add_f32 v[40:41], v[40:41], v[58:59]
	v_cvt_pk_bf16_f32 v56, v44, v45
	v_cvt_pk_bf16_f32 v57, v46, v47
	v_mov_b32_e32 v103, v165
	v_cvt_pk_bf16_f32 v58, v40, v41
	v_cvt_pk_bf16_f32 v59, v42, v43
	v_lshlrev_b32_e32 v40, 16, v56
	v_and_b32_e32 v42, 0xffff0000, v56
	v_lshlrev_b32_e32 v44, 16, v57
	v_and_b32_e32 v46, 0xffff0000, v57
	v_lshlrev_b32_e32 v60, 16, v58
	v_and_b32_e32 v62, 0xffff0000, v58
	v_lshlrev_b32_e32 v92, 16, v59
	v_and_b32_e32 v94, 0xffff0000, v59
	v_mul_f32_e32 v41, v40, v40
	v_mul_f32_e32 v43, v42, v42
	v_mul_f32_e32 v45, v44, v44
	v_mul_f32_e32 v47, v46, v46
	v_mul_f32_e32 v61, v60, v60
	v_mul_f32_e32 v63, v62, v62
	v_mul_f32_e32 v93, v92, v92
	v_mul_f32_e32 v95, v94, v94
	v_pk_add_f32 v[40:41], v[40:41], v[42:43]
	v_pk_add_f32 v[42:43], v[44:45], v[46:47]
	v_pk_add_f32 v[44:45], v[92:93], v[94:95]
	v_pk_add_f32 v[40:41], v[40:41], v[42:43]
	v_pk_add_f32 v[42:43], v[60:61], v[62:63]
	s_nop 0
	v_pk_add_f32 v[42:43], v[42:43], v[44:45]
	s_nop 0
	v_pk_add_f32 v[40:41], v[40:41], v[42:43]
	v_mov_b32_e32 v42, v165
	v_mov_b32_e32 v43, v165
	s_nop 0
	v_mov_b32_dpp v42, v40 quad_perm:[1,0,3,2] row_mask:0xf bank_mask:0xf
	v_mov_b32_dpp v43, v41 quad_perm:[1,0,3,2] row_mask:0xf bank_mask:0xf
	v_pk_add_f32 v[40:41], v[40:41], v[42:43]
	v_mov_b32_e32 v42, v40
	v_mov_b32_e32 v43, v41
	s_nop 1
	v_permlane16_swap_b32_e32 v40, v42
	v_permlane16_swap_b32_e32 v41, v43
	s_waitcnt lgkmcnt(0)
	v_pk_add_f32 v[42:43], v[40:41], v[42:43]
	v_mov_b32_e32 v44, v42
	v_mov_b32_e32 v45, v43
	s_nop 1
	v_permlane32_swap_b32_e32 v42, v44
	v_permlane32_swap_b32_e32 v43, v45
	v_lshl_add_u64 v[40:41], s[20:21], 0, v[102:103]
	global_store_dwordx4 v[40:41], v[56:59], off
	s_and_saveexec_b64 s[64:65], s[16:17]
	s_cbranch_execz .LBB0_1485
	s_waitcnt lgkmcnt(0)
	v_pk_add_f32 v[42:43], v[42:43], v[44:45]
	v_add_co_u32_e32 v44, vcc, 0x12000, v186
	s_nop 1
	v_addc_co_u32_e32 v45, vcc, 0, v187, vcc
	global_store_dwordx2 v[44:45], v[42:43], off

; __device__ __forceinline__ u32x4 pack8f(f32x4 a, f32x4 b) { u32x4 w; w.x = cvt_pk_bf16(a[0], a[1]); w.y = cvt_pk_bf16(a[2], a[3]); w.z = cvt_pk_bf16(b[0], b[1]); w.w = cvt_pk_bf16(b[2], b[3]); return w; }
; __device__ __forceinline__ float dpp_x1(float x) { return __builtin_bit_cast(float, __builtin_amdgcn_update_dpp(0, __builtin_bit_cast(int, x), 0xB1, 0xF, 0xF, false)); }
;     __device__ __forceinline__ void operator()(const f32x4 (&acc)[2][2][4][2], const Unit& u, int wr, int wc, int fr, int fq, const EpiCtx& X) const {
;     ...
;                 const f32x4 o0a = acc[ai][0][m][0], o0b = acc[ai][0][m][1], o1a = acc[ai][1][m][0], o1b = acc[ai][1][m][1];
;                 const f32x4 ra_ = dpp_swap1(odd ? o0a : o1a), rb_ = dpp_swap1(odd ? o0b : o1b);
;                 const f32x4 pa[2] = {odd ? ra_ : o0a, odd ? o1a : ra_}, pb[2] = {odd ? rb_ : o0b, odd ? o1b : rb_};
; #pragma unroll
;                 for (int q = 0; q < 2; ++q) {
;                     const u32x4 w0 = raw[2 * m + q];
;                     const f32x4 r0 = (f32x4){bf_lo(w0.x), bf_hi(w0.x), bf_lo(w0.y), bf_hi(w0.y)}, r1 = (f32x4){bf_lo(w0.z), bf_hi(w0.z), bf_lo(w0.w), bf_hi(w0.w)};
;                     f32x4 y0, y1;
;                     if (RESN) { const f32x2 t = tbl[rl + q]; const float mu = t.x, ra = t.y * ALPHA; y0 = (r0 - mu) * ra * g0 + b0 + pa[q]; y1 = (r1 - mu) * ra * g1 + b1 + pb[q]; }
;                     else { y0 = r0 * ALPHA + pa[q]; y1 = r1 * ALPHA + pb[q]; }
;                     { const u32x4 w = pack8f(y0, y1); *(u32x4*)(xb + off + q * 128) = w;
;                         y0 = (f32x4){bf_lo(w.x), bf_hi(w.x), bf_lo(w.y), bf_hi(w.y)}; y1 = (f32x4){bf_lo(w.z), bf_hi(w.z), bf_lo(w.w), bf_hi(w.w)}; }
;                     float sa = ((y0[0] + y0[1]) + (y0[2] + y0[3])) + ((y1[0] + y1[1]) + (y1[2] + y1[3]));
;                     float sb = ((y0[0] * y0[0] + y0[1] * y0[1]) + (y0[2] * y0[2] + y0[3] * y0[3])) + ((y1[0] * y1[0] + y1[1] * y1[1]) + (y1[2] * y1[2] + y1[3] * y1[3]));
;                     sa += dpp_x1(sa);
;                     sb += dpp_x1(sb);
;                     sa += __shfl_xor(sa, 16); sa += __shfl_xor(sa, 32); sb += __shfl_xor(sb, 16); sb += __shfl_xor(sb, 32);
;                     if (fq == 0 && !odd) ps[(size_t)(rl + q) * 64] = (f32x2){sa, sb};
.LBB0_1487:
	s_or_b64 exec, exec, s[64:65]
	s_waitcnt lgkmcnt(0)
	v_cndmask_b32_e64 v34, v28, v20, s[10:11]
	s_nop 0
	v_cndmask_b32_e64 v33, v29, v21, s[10:11]
	s_waitcnt lgkmcnt(0)
	v_cndmask_b32_e64 v35, v30, v22, s[10:11]
	v_mov_b32_dpp v32, v34 quad_perm:[1,0,3,2] row_mask:0xf bank_mask:0xf
	s_nop 0
	v_cndmask_b32_e64 v36, v31, v23, s[10:11]
	v_cndmask_b32_e64 v38, v24, v16, s[10:11]
	v_mov_b32_dpp v34, v33 quad_perm:[1,0,3,2] row_mask:0xf bank_mask:0xf
	s_nop 0
	v_cndmask_b32_e64 v37, v25, v17, s[10:11]
	v_cndmask_b32_e64 v39, v26, v18, s[10:11]
	v_mov_b32_dpp v33, v35 quad_perm:[1,0,3,2] row_mask:0xf bank_mask:0xf
	s_nop 0
	v_cndmask_b32_e64 v40, v27, v19, s[10:11]
	s_waitcnt vmcnt(11)
	v_lshlrev_b32_e32 v43, 16, v84
	v_mov_b32_dpp v35, v36 quad_perm:[1,0,3,2] row_mask:0xf bank_mask:0xf
	s_nop 0
	v_and_b32_e32 v44, 0xffff0000, v84
	v_cndmask_b32_e64 v29, v34, v29, s[10:11]
	v_mov_b32_dpp v36, v38 quad_perm:[1,0,3,2] row_mask:0xf bank_mask:0xf
	s_nop 0
	v_cndmask_b32_e64 v28, v32, v28, s[10:11]
	v_lshlrev_b32_e32 v46, 16, v85
	v_mov_b32_dpp v38, v37 quad_perm:[1,0,3,2] row_mask:0xf bank_mask:0xf
	s_nop 0
	v_and_b32_e32 v47, 0xffff0000, v85
	v_lshlrev_b32_e32 v48, 16, v86
	v_mov_b32_dpp v37, v39 quad_perm:[1,0,3,2] row_mask:0xf bank_mask:0xf
	s_nop 0
	v_and_b32_e32 v49, 0xffff0000, v86
	v_lshlrev_b32_e32 v50, 16, v87
	v_mov_b32_dpp v39, v40 quad_perm:[1,0,3,2] row_mask:0xf bank_mask:0xf
	ds_read_b64 v[40:41], v201 offset:1280
	v_and_b32_e32 v51, 0xffff0000, v87
	v_cndmask_b32_e64 v31, v35, v31, s[10:11]
	v_cndmask_b32_e64 v30, v33, v30, s[10:11]
	v_cndmask_b32_e64 v25, v38, v25, s[10:11]
	s_waitcnt lgkmcnt(0)
	v_mul_f32_e32 v42, 0x3fb504f3, v41
	v_sub_f32_e32 v45, v44, v40
	v_sub_f32_e32 v44, v43, v40
	v_pk_mul_f32 v[44:45], v[44:45], v[42:43] op_sel_hi:[1,0]
	v_sub_f32_e32 v47, v47, v40
	v_pk_fma_f32 v[44:45], v[76:77], v[44:45], v[184:185]
	v_sub_f32_e32 v46, v46, v40
	v_pk_add_f32 v[28:29], v[28:29], v[44:45]
	v_sub_f32_e32 v45, v49, v40
	v_sub_f32_e32 v44, v48, v40
	v_sub_f32_e32 v41, v51, v40
	v_sub_f32_e32 v40, v50, v40
	v_pk_mul_f32 v[46:47], v[46:47], v[42:43] op_sel_hi:[1,0]
	v_pk_mul_f32 v[40:41], v[40:41], v[42:43] op_sel_hi:[1,0]
	v_pk_mul_f32 v[42:43], v[44:45], v[42:43] op_sel_hi:[1,0]
	v_cndmask_b32_e64 v24, v36, v24, s[10:11]
	v_cndmask_b32_e64 v27, v39, v27, s[10:11]
	v_cndmask_b32_e64 v26, v37, v26, s[10:11]
	v_pk_fma_f32 v[46:47], v[78:79], v[46:47], v[182:183]
	v_pk_fma_f32 v[42:43], v[72:73], v[42:43], v[180:181]
	v_pk_fma_f32 v[40:41], v[74:75], v[40:41], v[178:179]
	v_pk_add_f32 v[30:31], v[30:31], v[46:47]
	v_pk_add_f32 v[26:27], v[26:27], v[40:41]
	v_pk_add_f32 v[24:25], v[24:25], v[42:43]
	v_cvt_pk_bf16_f32 v40, v28, v29
	v_cvt_pk_bf16_f32 v41, v30, v31
	v_mov_b32_e32 v101, v165
	v_cvt_pk_bf16_f32 v42, v24, v25
	v_cvt_pk_bf16_f32 v43, v26, v27
	v_lshlrev_b32_e32 v24, 16, v40
	v_and_b32_e32 v26, 0xffff0000, v40
	v_lshlrev_b32_e32 v28, 16, v41
	v_and_b32_e32 v30, 0xffff0000, v41
	v_lshlrev_b32_e32 v44, 16, v42
	v_and_b32_e32 v46, 0xffff0000, v42
	v_lshlrev_b32_e32 v48, 16, v43
	v_and_b32_e32 v50, 0xffff0000, v43
	v_mul_f32_e32 v25, v24, v24
	v_mul_f32_e32 v27, v26, v26
	v_mul_f32_e32 v29, v28, v28
	v_mul_f32_e32 v31, v30, v30
	v_mul_f32_e32 v45, v44, v44
	v_mul_f32_e32 v47, v46, v46
	v_mul_f32_e32 v49, v48, v48
	v_mul_f32_e32 v51, v50, v50
	v_pk_add_f32 v[24:25], v[24:25], v[26:27]
	v_pk_add_f32 v[26:27], v[28:29], v[30:31]
	v_pk_add_f32 v[28:29], v[48:49], v[50:51]
	v_pk_add_f32 v[24:25], v[24:25], v[26:27]
	v_pk_add_f32 v[26:27], v[44:45], v[46:47]
	s_nop 0
	v_pk_add_f32 v[26:27], v[26:27], v[28:29]
	s_nop 0
	v_pk_add_f32 v[24:25], v[24:25], v[26:27]
	v_mov_b32_e32 v26, v165
	v_mov_b32_e32 v27, v165
	s_nop 0
	v_mov_b32_dpp v26, v24 quad_perm:[1,0,3,2] row_mask:0xf bank_mask:0xf
	v_mov_b32_dpp v27, v25 quad_perm:[1,0,3,2] row_mask:0xf bank_mask:0xf
	v_pk_add_f32 v[24:25], v[24:25], v[26:27]
	v_mov_b32_e32 v26, v24
	v_mov_b32_e32 v27, v25
	s_nop 1
	v_permlane16_swap_b32_e32 v24, v26
	v_permlane16_swap_b32_e32 v25, v27
	s_waitcnt lgkmcnt(0)
	v_pk_add_f32 v[26:27], v[24:25], v[26:27]
	v_mov_b32_e32 v28, v26
	v_mov_b32_e32 v29, v27
	s_nop 1
	v_permlane32_swap_b32_e32 v26, v28
	v_permlane32_swap_b32_e32 v27, v29
	v_lshl_add_u64 v[24:25], s[20:21], 0, v[100:101]
	global_store_dwordx4 v[24:25], v[40:43], off
	s_and_saveexec_b64 s[64:65], s[16:17]
	s_cbranch_execz .LBB0_1489
	s_waitcnt lgkmcnt(0)
	v_pk_add_f32 v[26:27], v[26:27], v[28:29]
	v_add_co_u32_e32 v28, vcc, 0x14000, v186
	s_nop 1
	v_addc_co_u32_e32 v29, vcc, 0, v187, vcc
	global_store_dwordx2 v[28:29], v[26:27], off

; __device__ __forceinline__ u32x4 pack8f(f32x4 a, f32x4 b) { u32x4 w; w.x = cvt_pk_bf16(a[0], a[1]); w.y = cvt_pk_bf16(a[2], a[3]); w.z = cvt_pk_bf16(b[0], b[1]); w.w = cvt_pk_bf16(b[2], b[3]); return w; }
; __device__ __forceinline__ float dpp_x1(float x) { return __builtin_bit_cast(float, __builtin_amdgcn_update_dpp(0, __builtin_bit_cast(int, x), 0xB1, 0xF, 0xF, false)); }
;     __device__ __forceinline__ void operator()(const f32x4 (&acc)[2][2][4][2], const Unit& u, int wr, int wc, int fr, int fq, const EpiCtx& X) const {
;     ...
;                 const f32x4 o0a = acc[ai][0][m][0], o0b = acc[ai][0][m][1], o1a = acc[ai][1][m][0], o1b = acc[ai][1][m][1];
;                 const f32x4 ra_ = dpp_swap1(odd ? o0a : o1a), rb_ = dpp_swap1(odd ? o0b : o1b);
;                 const f32x4 pa[2] = {odd ? ra_ : o0a, odd ? o1a : ra_}, pb[2] = {odd ? rb_ : o0b, odd ? o1b : rb_};
; #pragma unroll
;                 for (int q = 0; q < 2; ++q) {
;                     const u32x4 w0 = raw[2 * m + q];
;                     const f32x4 r0 = (f32x4){bf_lo(w0.x), bf_hi(w0.x), bf_lo(w0.y), bf_hi(w0.y)}, r1 = (f32x4){bf_lo(w0.z), bf_hi(w0.z), bf_lo(w0.w), bf_hi(w0.w)};
;                     f32x4 y0, y1;
;                     if (RESN) { const f32x2 t = tbl[rl + q]; const float mu = t.x, ra = t.y * ALPHA; y0 = (r0 - mu) * ra * g0 + b0 + pa[q]; y1 = (r1 - mu) * ra * g1 + b1 + pb[q]; }
;                     else { y0 = r0 * ALPHA + pa[q]; y1 = r1 * ALPHA + pb[q]; }
;                     { const u32x4 w = pack8f(y0, y1); *(u32x4*)(xb + off + q * 128) = w;
;                         y0 = (f32x4){bf_lo(w.x), bf_hi(w.x), bf_lo(w.y), bf_hi(w.y)}; y1 = (f32x4){bf_lo(w.z), bf_hi(w.z), bf_lo(w.w), bf_hi(w.w)}; }
;                     float sa = ((y0[0] + y0[1]) + (y0[2] + y0[3])) + ((y1[0] + y1[1]) + (y1[2] + y1[3]));
;                     float sb = ((y0[0] * y0[0] + y0[1] * y0[1]) + (y0[2] * y0[2] + y0[3] * y0[3])) + ((y1[0] * y1[0] + y1[1] * y1[1]) + (y1[2] * y1[2] + y1[3] * y1[3]));
;                     sa += dpp_x1(sa);
;                     sb += dpp_x1(sb);
;                     sa += __shfl_xor(sa, 16); sa += __shfl_xor(sa, 32); sb += __shfl_xor(sb, 16); sb += __shfl_xor(sb, 32);
;                     if (fq == 0 && !odd) ps[(size_t)(rl + q) * 64] = (f32x2){sa, sb};
.LBB0_1491:
	s_or_b64 exec, exec, s[64:65]
	s_waitcnt lgkmcnt(0)
	v_cndmask_b32_e64 v18, v12, v4, s[10:11]
	s_nop 0
	v_cndmask_b32_e64 v17, v13, v5, s[10:11]
	s_waitcnt lgkmcnt(0)
	v_cndmask_b32_e64 v19, v14, v6, s[10:11]
	v_mov_b32_dpp v16, v18 quad_perm:[1,0,3,2] row_mask:0xf bank_mask:0xf
	s_nop 0
	v_cndmask_b32_e64 v20, v15, v7, s[10:11]
	v_cndmask_b32_e64 v22, v8, v0, s[10:11]
	v_mov_b32_dpp v18, v17 quad_perm:[1,0,3,2] row_mask:0xf bank_mask:0xf
	s_nop 0
	v_cndmask_b32_e64 v21, v9, v1, s[10:11]
	v_cndmask_b32_e64 v23, v10, v2, s[10:11]
	v_mov_b32_dpp v17, v19 quad_perm:[1,0,3,2] row_mask:0xf bank_mask:0xf
	s_nop 0
	v_cndmask_b32_e64 v24, v11, v3, s[10:11]
	s_waitcnt vmcnt(13)
	v_lshlrev_b32_e32 v27, 16, v68
	v_mov_b32_dpp v19, v20 quad_perm:[1,0,3,2] row_mask:0xf bank_mask:0xf
	s_nop 0
	v_and_b32_e32 v28, 0xffff0000, v68
	v_cndmask_b32_e64 v13, v18, v13, s[10:11]
	v_mov_b32_dpp v20, v22 quad_perm:[1,0,3,2] row_mask:0xf bank_mask:0xf
	s_nop 0
	v_cndmask_b32_e64 v12, v16, v12, s[10:11]
	v_lshlrev_b32_e32 v30, 16, v69
	v_mov_b32_dpp v22, v21 quad_perm:[1,0,3,2] row_mask:0xf bank_mask:0xf
	s_nop 0
	v_and_b32_e32 v31, 0xffff0000, v69
	v_lshlrev_b32_e32 v32, 16, v70
	v_mov_b32_dpp v21, v23 quad_perm:[1,0,3,2] row_mask:0xf bank_mask:0xf
	s_nop 0
	v_and_b32_e32 v33, 0xffff0000, v70
	v_lshlrev_b32_e32 v34, 16, v71
	v_mov_b32_dpp v23, v24 quad_perm:[1,0,3,2] row_mask:0xf bank_mask:0xf
	ds_read_b64 v[24:25], v201 offset:1408
	v_and_b32_e32 v35, 0xffff0000, v71
	v_cndmask_b32_e64 v15, v19, v15, s[10:11]
	v_cndmask_b32_e64 v14, v17, v14, s[10:11]
	v_cndmask_b32_e64 v9, v22, v9, s[10:11]
	s_waitcnt lgkmcnt(0)
	v_mul_f32_e32 v26, 0x3fb504f3, v25
	v_sub_f32_e32 v29, v28, v24
	v_sub_f32_e32 v28, v27, v24
	v_pk_mul_f32 v[28:29], v[28:29], v[26:27] op_sel_hi:[1,0]
	v_sub_f32_e32 v31, v31, v24
	v_pk_fma_f32 v[28:29], v[76:77], v[28:29], v[184:185]
	v_sub_f32_e32 v30, v30, v24
	v_pk_add_f32 v[12:13], v[12:13], v[28:29]
	v_sub_f32_e32 v29, v33, v24
	v_sub_f32_e32 v28, v32, v24
	v_sub_f32_e32 v25, v35, v24
	v_sub_f32_e32 v24, v34, v24
	v_pk_mul_f32 v[30:31], v[30:31], v[26:27] op_sel_hi:[1,0]
	v_pk_mul_f32 v[24:25], v[24:25], v[26:27] op_sel_hi:[1,0]
	v_pk_mul_f32 v[26:27], v[28:29], v[26:27] op_sel_hi:[1,0]
	v_cndmask_b32_e64 v8, v20, v8, s[10:11]
	v_cndmask_b32_e64 v11, v23, v11, s[10:11]
	v_cndmask_b32_e64 v10, v21, v10, s[10:11]
	v_pk_fma_f32 v[30:31], v[78:79], v[30:31], v[182:183]
	v_pk_fma_f32 v[26:27], v[72:73], v[26:27], v[180:181]
	v_pk_fma_f32 v[24:25], v[74:75], v[24:25], v[178:179]
	v_pk_add_f32 v[14:15], v[14:15], v[30:31]
	v_pk_add_f32 v[10:11], v[10:11], v[24:25]
	v_pk_add_f32 v[8:9], v[8:9], v[26:27]
	v_cvt_pk_bf16_f32 v24, v12, v13
	v_cvt_pk_bf16_f32 v25, v14, v15
	s_nop 0
	v_cvt_pk_bf16_f32 v26, v8, v9
	v_cvt_pk_bf16_f32 v27, v10, v11
	v_lshlrev_b32_e32 v8, 16, v24
	v_and_b32_e32 v10, 0xffff0000, v24
	v_lshlrev_b32_e32 v12, 16, v25
	v_and_b32_e32 v14, 0xffff0000, v25
	v_lshlrev_b32_e32 v28, 16, v26
	v_and_b32_e32 v30, 0xffff0000, v26
	v_lshlrev_b32_e32 v32, 16, v27
	v_and_b32_e32 v34, 0xffff0000, v27
	v_mul_f32_e32 v9, v8, v8
	v_mul_f32_e32 v11, v10, v10
	v_mul_f32_e32 v13, v12, v12
	v_mul_f32_e32 v15, v14, v14
	v_mul_f32_e32 v29, v28, v28
	v_mul_f32_e32 v31, v30, v30
	v_mul_f32_e32 v33, v32, v32
	v_mul_f32_e32 v35, v34, v34
	v_pk_add_f32 v[8:9], v[8:9], v[10:11]
	v_pk_add_f32 v[10:11], v[12:13], v[14:15]
	v_pk_add_f32 v[12:13], v[32:33], v[34:35]
	v_pk_add_f32 v[8:9], v[8:9], v[10:11]
	v_pk_add_f32 v[10:11], v[28:29], v[30:31]
	s_nop 0
	v_pk_add_f32 v[10:11], v[10:11], v[12:13]
	s_nop 0
	v_pk_add_f32 v[8:9], v[8:9], v[10:11]
	v_mov_b32_e32 v10, v165
	v_mov_b32_e32 v11, v165
	s_nop 0
	v_mov_b32_dpp v10, v8 quad_perm:[1,0,3,2] row_mask:0xf bank_mask:0xf
	v_mov_b32_dpp v11, v9 quad_perm:[1,0,3,2] row_mask:0xf bank_mask:0xf
	v_pk_add_f32 v[8:9], v[8:9], v[10:11]
	v_mov_b32_e32 v10, v8
	v_mov_b32_e32 v11, v9
	s_nop 1
	v_permlane16_swap_b32_e32 v8, v10
	v_permlane16_swap_b32_e32 v9, v11
	s_waitcnt lgkmcnt(0)
	v_pk_add_f32 v[10:11], v[8:9], v[10:11]
	v_mov_b32_e32 v12, v10
	v_mov_b32_e32 v13, v11
	s_nop 1
	v_permlane32_swap_b32_e32 v10, v12
	v_permlane32_swap_b32_e32 v11, v13
	v_lshl_add_u64 v[8:9], s[20:21], 0, v[164:165]
	global_store_dwordx4 v[8:9], v[24:27], off
	s_and_saveexec_b64 s[20:21], s[16:17]
	s_cbranch_execz .LBB0_1493
	s_waitcnt lgkmcnt(0)
	v_pk_add_f32 v[10:11], v[10:11], v[12:13]
	v_add_co_u32_e32 v12, vcc, 0x16000, v186
	s_nop 1
	v_addc_co_u32_e32 v13, vcc, 0, v187, vcc
	global_store_dwordx2 v[12:13], v[10:11], off

; #define LAS __attribute__((address_space(3)))
;     __device__ __forceinline__ void operator()(const f32x4 (&acc)[2][2][4][2], const Unit& u, int wr, int wc, int fr, int fq, const EpiCtx& X) const {
;     ...
;         char* yb = nullptr; char* xb = (char*)(XB + (size_t)u.pm * BM * DM + (size_t)(u.pn * 4 + wc) * (BM * 64));
;         unsigned lo = (unsigned)((wr * 64 + fe) * 64 + o32 + 8 * fq) * 2u; EPI_OPAQUE(lo);
;         const int col = u.pn * BM + wc * 64 + o32 + 8 * fq;
;         f32x4 g0, g1, b0, b1;
;         if (RESN) { ensure_tbl(PSp, sidp, u.pm, X);
;             g0 = *(const f32x4*)(gp + col); g1 = *(const f32x4*)(gp + col + 4); b0 = *(const f32x4*)(bp + col) * ALPHA; b1 = *(const f32x4*)(bp + col + 4) * ALPHA; }
;         const LAS f32x2* tbl = (const LAS f32x2*)(X.lds + TBL_OFF) + wr * 64 + fe;
;         f32x2* ps = PSn + ((size_t)u.pm * BM + wr * 64 + fe) * 64 + u.pn * 4 + wc;
; #pragma unroll
;         for (int ai = 0; ai < 2; ++ai) {
;             u32x4 raw[8];
; #pragma unroll
;             for (int m = 0; m < 4; ++m) { const unsigned off = lo + (unsigned)((ai * HALF + m * 16) * 64) * 2u; raw[2 * m] = *(const u32x4*)(xb + off); raw[2 * m + 1] = *(const u32x4*)(xb + off + 128); }
; #pragma unroll
;             for (int m = 0; m < 4; ++m) {
;                 const int rl = ai * HALF + m * 16; const unsigned off = lo + (unsigned)(rl * 64) * 2u;
;                 const f32x4 o0a = acc[ai][0][m][0], o0b = acc[ai][0][m][1], o1a = acc[ai][1][m][0], o1b = acc[ai][1][m][1];
;                 const f32x4 ra_ = dpp_swap1(odd ? o0a : o1a), rb_ = dpp_swap1(odd ? o0b : o1b);
;                 const f32x4 pa[2] = {odd ? ra_ : o0a, odd ? o1a : ra_}, pb[2] = {odd ? rb_ : o0b, odd ? o1b : rb_};
; #pragma unroll
;                 for (int q = 0; q < 2; ++q) {
;                     const u32x4 w0 = raw[2 * m + q];
;                     const f32x4 r0 = (f32x4){bf_lo(w0.x), bf_hi(w0.x), bf_lo(w0.y), bf_hi(w0.y)}, r1 = (f32x4){bf_lo(w0.z), bf_hi(w0.z), bf_lo(w0.w), bf_hi(w0.w)};
;                     f32x4 y0, y1;
;                     if (RESN) { const f32x2 t = tbl[rl + q]; const float mu = t.x, ra = t.y * ALPHA; y0 = (r0 - mu) * ra * g0 + b0 + pa[q]; y1 = (r1 - mu) * ra * g1 + b1 + pb[q]; }
;                     else { y0 = r0 * ALPHA + pa[q]; y1 = r1 * ALPHA + pb[q]; }
;                     { const u32x4 w = pack8f(y0, y1); *(u32x4*)(xb + off + q * 128) = w;
.LBB0_1697:
	s_lshl_b64 s[16:17], s[58:59], 21
	s_add_u32 s35, s31, s16
	s_addc_u32 s38, s68, s17
	s_lshl_b32 s58, s56, 2
	s_or_b32 s16, s58, s41
	s_ashr_i32 s17, s16, 31
	v_lshl_add_u32 v72, s56, 8, v200
	v_ashrrev_i32_e32 v73, 31, v72
	s_lshl_b64 s[16:17], s[16:17], 15
	v_lshlrev_b64 v[72:73], 2, v[72:73]
	s_add_u32 s16, s35, s16
	v_lshl_add_u64 v[74:75], s[26:27], 0, v[72:73]
	s_addc_u32 s17, s38, s17
	global_load_dwordx4 v[194:197], v[74:75], off offset:16
	global_load_dwordx4 v[178:181], v[74:75], off
	global_load_dwordx4 v[214:217], v164, s[16:17]
	v_lshl_add_u64 v[72:73], s[24:25], 0, v[72:73]
	s_waitcnt lgkmcnt(0)
	global_load_dwordx4 v[76:79], v[72:73], off
	s_nop 0
	global_load_dwordx4 v[72:75], v[72:73], off offset:16
	v_cndmask_b32_e64 v136, v135, v127, s[6:7]
	v_cndmask_b32_e64 v137, v134, v126, s[6:7]
	v_cndmask_b32_e64 v138, v133, v125, s[6:7]
	v_cndmask_b32_e64 v139, v132, v124, s[6:7]
	s_nop 0
	s_nop 0
	s_nop 0
	s_nop 0
	v_cndmask_b32_e64 v140, v131, v123, s[6:7]
	v_cndmask_b32_e64 v141, v130, v122, s[6:7]
	v_cndmask_b32_e64 v142, v129, v121, s[6:7]
	v_cndmask_b32_e64 v143, v128, v120, s[6:7]
	s_nop 0
	s_nop 0
	s_nop 0
	s_nop 0
	v_mov_b32_dpp v189, v139 quad_perm:[1,0,3,2] row_mask:0xf bank_mask:0xf
	v_mov_b32_dpp v193, v138 quad_perm:[1,0,3,2] row_mask:0xf bank_mask:0xf
	v_mov_b32_dpp v191, v137 quad_perm:[1,0,3,2] row_mask:0xf bank_mask:0xf
	v_mov_b32_dpp v209, v136 quad_perm:[1,0,3,2] row_mask:0xf bank_mask:0xf
	v_mov_b32_dpp v210, v143 quad_perm:[1,0,3,2] row_mask:0xf bank_mask:0xf
	v_mov_b32_dpp v212, v142 quad_perm:[1,0,3,2] row_mask:0xf bank_mask:0xf
	v_mov_b32_dpp v211, v141 quad_perm:[1,0,3,2] row_mask:0xf bank_mask:0xf
	v_mov_b32_dpp v213, v140 quad_perm:[1,0,3,2] row_mask:0xf bank_mask:0xf
	v_add_u32_e32 v192, 0x800, v164
	v_add_u32_e32 v190, 0x1000, v164
	v_add_u32_e32 v188, 0x1800, v164
	ds_read_b64 v[218:219], v201
	v_cndmask_b32_e64 v221, v193, v133, s[6:7]
	v_cndmask_b32_e64 v220, v189, v132, s[6:7]
	v_cndmask_b32_e64 v223, v209, v135, s[6:7]
	v_cndmask_b32_e64 v222, v191, v134, s[6:7]
	v_cndmask_b32_e64 v225, v212, v129, s[6:7]
	v_cndmask_b32_e64 v224, v210, v128, s[6:7]
	v_cndmask_b32_e64 v227, v213, v131, s[6:7]
	v_cndmask_b32_e64 v226, v211, v130, s[6:7]
	global_load_dwordx4 v[152:155], v164, s[16:17] offset:128
	global_load_dwordx4 v[148:151], v192, s[16:17]
	global_load_dwordx4 v[144:147], v192, s[16:17] offset:128
	global_load_dwordx4 v[140:143], v190, s[16:17]
	global_load_dwordx4 v[136:139], v190, s[16:17] offset:128
	global_load_dwordx4 v[132:135], v188, s[16:17]
	global_load_dwordx4 v[128:131], v188, s[16:17] offset:128
	s_waitcnt lgkmcnt(0)
	v_mul_f32_e32 v208, 0x3fb504f3, v219
	v_lshl_add_u64 v[186:187], v[166:167], 0, s[60:61]
	s_ashr_i32 s59, s58, 31
	v_lshl_add_u64 v[186:187], s[58:59], 3, v[186:187]
	v_lshl_add_u64 v[186:187], v[186:187], 0, s[20:21]
	v_add_u32_e32 v246, 0x4000, v164
	v_add_u32_e32 v247, 0x4800, v164
	global_load_dwordx4 v[230:233], v246, s[16:17]
	global_load_dwordx4 v[234:237], v246, s[16:17] offset:128
	global_load_dwordx4 v[238:241], v247, s[16:17]
	global_load_dwordx4 v[242:245], v247, s[16:17] offset:128
	s_waitcnt vmcnt(14)
	v_pk_mul_f32 v[182:183], v[180:181], s[46:47] op_sel_hi:[1,0]
	v_pk_mul_f32 v[184:185], v[178:179], s[46:47] op_sel_hi:[1,0]
	v_pk_mul_f32 v[178:179], v[196:197], s[46:47] op_sel_hi:[1,0]
	v_pk_mul_f32 v[180:181], v[194:195], s[46:47] op_sel_hi:[1,0]
	s_waitcnt vmcnt(13)
	v_lshlrev_b32_e32 v194, 16, v214
	v_and_b32_e32 v195, 0xffff0000, v214
	v_lshlrev_b32_e32 v196, 16, v215
	v_and_b32_e32 v197, 0xffff0000, v215
	v_lshlrev_b32_e32 v207, 16, v216
	v_and_b32_e32 v214, 0xffff0000, v216
	v_lshlrev_b32_e32 v216, 16, v217
	v_and_b32_e32 v217, 0xffff0000, v217
	v_sub_f32_e32 v195, v195, v218
	v_sub_f32_e32 v194, v194, v218
	v_sub_f32_e32 v197, v197, v218
	v_sub_f32_e32 v196, v196, v218
	v_sub_f32_e32 v215, v214, v218
	v_sub_f32_e32 v214, v207, v218
	v_sub_f32_e32 v217, v217, v218
	v_sub_f32_e32 v216, v216, v218
	v_pk_mul_f32 v[196:197], v[196:197], v[208:209] op_sel_hi:[1,0]
	v_pk_mul_f32 v[194:195], v[194:195], v[208:209] op_sel_hi:[1,0]
	v_pk_mul_f32 v[216:217], v[216:217], v[208:209] op_sel_hi:[1,0]
	v_pk_mul_f32 v[214:215], v[214:215], v[208:209] op_sel_hi:[1,0]
	s_waitcnt vmcnt(12)
	v_pk_fma_f32 v[194:195], v[76:77], v[194:195], v[184:185]
	v_pk_fma_f32 v[196:197], v[78:79], v[196:197], v[182:183]
	s_waitcnt vmcnt(11)
	v_pk_fma_f32 v[214:215], v[72:73], v[214:215], v[180:181]
	v_pk_fma_f32 v[216:217], v[74:75], v[216:217], v[178:179]
	v_pk_add_f32 v[196:197], v[222:223], v[196:197]
	v_pk_add_f32 v[194:195], v[220:221], v[194:195]
	v_pk_add_f32 v[218:219], v[226:227], v[216:217]
	v_pk_add_f32 v[216:217], v[224:225], v[214:215]
	v_cvt_pk_bf16_f32 v214, v194, v195
	v_cvt_pk_bf16_f32 v215, v196, v197
	v_and_b32_e32 v208, 64, v206
	v_cvt_pk_bf16_f32 v216, v216, v217
	v_cvt_pk_bf16_f32 v217, v218, v219
	v_lshlrev_b32_e32 v194, 16, v214
	v_and_b32_e32 v196, 0xffff0000, v214
	v_lshlrev_b32_e32 v218, 16, v215
	v_and_b32_e32 v220, 0xffff0000, v215
	v_lshlrev_b32_e32 v222, 16, v216
	v_and_b32_e32 v224, 0xffff0000, v216
	v_lshlrev_b32_e32 v226, 16, v217
	v_and_b32_e32 v228, 0xffff0000, v217
	v_mul_f32_e32 v195, v194, v194
	v_mul_f32_e32 v197, v196, v196
	v_mul_f32_e32 v219, v218, v218
	v_mul_f32_e32 v221, v220, v220
	v_mul_f32_e32 v223, v222, v222
	v_mul_f32_e32 v225, v224, v224
	v_mul_f32_e32 v227, v226, v226
	v_mul_f32_e32 v229, v228, v228
	v_pk_add_f32 v[194:195], v[194:195], v[196:197]
	v_pk_add_f32 v[196:197], v[218:219], v[220:221]
	v_pk_add_f32 v[218:219], v[226:227], v[228:229]
	v_pk_add_f32 v[194:195], v[194:195], v[196:197]
	v_pk_add_f32 v[196:197], v[222:223], v[224:225]
	v_xor_b32_e32 v207, 16, v206
	v_add_u32_e32 v208, 64, v208
	v_pk_add_f32 v[196:197], v[196:197], v[218:219]
	v_cmp_lt_i32_e32 vcc, v207, v208
	v_pk_add_f32 v[194:195], v[194:195], v[196:197]
	s_nop 0
	s_nop 0
	v_cndmask_b32_e32 v207, v206, v207, vcc
	v_mov_b32_dpp v196, v194 quad_perm:[1,0,3,2] row_mask:0xf bank_mask:0xf
	v_mov_b32_dpp v197, v195 quad_perm:[1,0,3,2] row_mask:0xf bank_mask:0xf
	v_lshlrev_b32_e32 v207, 2, v207
	v_pk_add_f32 v[194:195], v[194:195], v[196:197]
	v_mov_b32_e32 v196, v194
	v_mov_b32_e32 v197, v195
	s_nop 1
	v_permlane16_swap_b32_e32 v194, v196
	v_permlane16_swap_b32_e32 v195, v197
	v_xor_b32_e32 v218, 32, v206
	v_cmp_lt_i32_e32 vcc, v218, v208
	global_store_dwordx4 v164, v[214:217], s[16:17]
	s_waitcnt lgkmcnt(0)
	v_pk_add_f32 v[194:195], v[194:195], v[196:197]
	v_cndmask_b32_e32 v208, v206, v218, vcc
	v_lshlrev_b32_e32 v208, 2, v208
	v_mov_b32_e32 v196, v194
	v_mov_b32_e32 v197, v195
	s_nop 1
	v_permlane32_swap_b32_e32 v194, v196
	v_permlane32_swap_b32_e32 v195, v197
	s_and_saveexec_b64 s[56:57], s[12:13]
	s_waitcnt lgkmcnt(0)
	v_pk_add_f32 v[194:195], v[194:195], v[196:197]
	global_store_dwordx2 v[186:187], v[194:195], off

; __device__ __forceinline__ u32x4 pack8f(f32x4 a, f32x4 b) { u32x4 w; w.x = cvt_pk_bf16(a[0], a[1]); w.y = cvt_pk_bf16(a[2], a[3]); w.z = cvt_pk_bf16(b[0], b[1]); w.w = cvt_pk_bf16(b[2], b[3]); return w; }
;     __device__ __forceinline__ void operator()(const f32x4 (&acc)[2][2][4][2], const Unit& u, int wr, int wc, int fr, int fq, const EpiCtx& X) const {
;     ...
;             for (int m = 0; m < 4; ++m) {
;                 const int rl = ai * HALF + m * 16; const unsigned off = lo + (unsigned)(rl * 64) * 2u;
;                 const f32x4 o0a = acc[ai][0][m][0], o0b = acc[ai][0][m][1], o1a = acc[ai][1][m][0], o1b = acc[ai][1][m][1];
;                 const f32x4 ra_ = dpp_swap1(odd ? o0a : o1a), rb_ = dpp_swap1(odd ? o0b : o1b);
;                 const f32x4 pa[2] = {odd ? ra_ : o0a, odd ? o1a : ra_}, pb[2] = {odd ? rb_ : o0b, odd ? o1b : rb_};
; #pragma unroll
;                 for (int q = 0; q < 2; ++q) {
;                     const u32x4 w0 = raw[2 * m + q];
;                     const f32x4 r0 = (f32x4){bf_lo(w0.x), bf_hi(w0.x), bf_lo(w0.y), bf_hi(w0.y)}, r1 = (f32x4){bf_lo(w0.z), bf_hi(w0.z), bf_lo(w0.w), bf_hi(w0.w)};
;                     f32x4 y0, y1;
;                     if (RESN) { const f32x2 t = tbl[rl + q]; const float mu = t.x, ra = t.y * ALPHA; y0 = (r0 - mu) * ra * g0 + b0 + pa[q]; y1 = (r1 - mu) * ra * g1 + b1 + pb[q]; }
;                     else { y0 = r0 * ALPHA + pa[q]; y1 = r1 * ALPHA + pb[q]; }
;                     { const u32x4 w = pack8f(y0, y1); *(u32x4*)(xb + off + q * 128) = w;
;                         y0 = (f32x4){bf_lo(w.x), bf_hi(w.x), bf_lo(w.y), bf_hi(w.y)}; y1 = (f32x4){bf_lo(w.z), bf_hi(w.z), bf_lo(w.w), bf_hi(w.w)}; }
;                     float sa = ((y0[0] + y0[1]) + (y0[2] + y0[3])) + ((y1[0] + y1[1]) + (y1[2] + y1[3]));
;                     float sb = ((y0[0] * y0[0] + y0[1] * y0[1]) + (y0[2] * y0[2] + y0[3] * y0[3])) + ((y1[0] * y1[0] + y1[1] * y1[1]) + (y1[2] * y1[2] + y1[3] * y1[3]));
;                     sa += dpp_x1(sa);
;                     sb += dpp_x1(sb);
;                     sa += __shfl_xor(sa, 16); sa += __shfl_xor(sa, 32); sb += __shfl_xor(sb, 16); sb += __shfl_xor(sb, 32);
;                     if (fq == 0 && !odd) ps[(size_t)(rl + q) * 64] = (f32x2){sa, sb};
;                 }
.LBB0_1701:
	s_or_b64 exec, exec, s[56:57]
	s_waitcnt lgkmcnt(0)
	v_cndmask_b32_e64 v122, v116, v108, s[6:7]
	s_nop 0
	v_cndmask_b32_e64 v121, v117, v109, s[6:7]
	s_waitcnt lgkmcnt(0)
	v_cndmask_b32_e64 v123, v118, v110, s[6:7]
	v_mov_b32_dpp v120, v122 quad_perm:[1,0,3,2] row_mask:0xf bank_mask:0xf
	s_nop 0
	v_cndmask_b32_e64 v124, v119, v111, s[6:7]
	v_cndmask_b32_e64 v126, v112, v104, s[6:7]
	v_mov_b32_dpp v122, v121 quad_perm:[1,0,3,2] row_mask:0xf bank_mask:0xf
	s_nop 0
	v_cndmask_b32_e64 v125, v113, v105, s[6:7]
	v_cndmask_b32_e64 v127, v114, v106, s[6:7]
	v_mov_b32_dpp v121, v123 quad_perm:[1,0,3,2] row_mask:0xf bank_mask:0xf
	s_nop 0
	v_cndmask_b32_e64 v152, v115, v107, s[6:7]
	s_waitcnt vmcnt(13)
	v_and_b32_e32 v153, 0xffff0000, v148
	v_mov_b32_dpp v123, v124 quad_perm:[1,0,3,2] row_mask:0xf bank_mask:0xf
	s_nop 0
	v_lshlrev_b32_e32 v154, 16, v149
	v_and_b32_e32 v155, 0xffff0000, v149
	v_mov_b32_dpp v124, v126 quad_perm:[1,0,3,2] row_mask:0xf bank_mask:0xf
	s_nop 0
	v_lshlrev_b32_e32 v189, 16, v150
	v_and_b32_e32 v191, 0xffff0000, v150
	v_mov_b32_dpp v126, v125 quad_perm:[1,0,3,2] row_mask:0xf bank_mask:0xf
	s_nop 0
	v_lshlrev_b32_e32 v193, 16, v151
	v_and_b32_e32 v151, 0xffff0000, v151
	v_mov_b32_dpp v125, v127 quad_perm:[1,0,3,2] row_mask:0xf bank_mask:0xf
	s_nop 0
	v_cndmask_b32_e64 v117, v122, v117, s[6:7]
	v_cndmask_b32_e64 v116, v120, v116, s[6:7]
	v_mov_b32_dpp v127, v152 quad_perm:[1,0,3,2] row_mask:0xf bank_mask:0xf
	v_lshlrev_b32_e32 v152, 16, v148
	ds_read_b64 v[148:149], v201 offset:128
	v_cndmask_b32_e64 v119, v123, v119, s[6:7]
	v_cndmask_b32_e64 v118, v121, v118, s[6:7]
	v_cndmask_b32_e64 v113, v126, v113, s[6:7]
	v_cndmask_b32_e64 v112, v124, v112, s[6:7]
	s_waitcnt lgkmcnt(0)
	v_mul_f32_e32 v150, 0x3fb504f3, v149
	v_sub_f32_e32 v153, v153, v148
	v_sub_f32_e32 v152, v152, v148
	v_pk_mul_f32 v[152:153], v[152:153], v[150:151] op_sel_hi:[1,0]
	v_sub_f32_e32 v155, v155, v148
	v_pk_fma_f32 v[152:153], v[76:77], v[152:153], v[184:185]
	v_sub_f32_e32 v154, v154, v148
	v_pk_add_f32 v[116:117], v[116:117], v[152:153]
	v_sub_f32_e32 v153, v191, v148
	v_sub_f32_e32 v152, v189, v148
	v_sub_f32_e32 v149, v151, v148
	v_sub_f32_e32 v148, v193, v148
	v_pk_mul_f32 v[154:155], v[154:155], v[150:151] op_sel_hi:[1,0]
	v_pk_mul_f32 v[148:149], v[148:149], v[150:151] op_sel_hi:[1,0]
	v_pk_mul_f32 v[150:151], v[152:153], v[150:151] op_sel_hi:[1,0]
	v_cndmask_b32_e64 v115, v127, v115, s[6:7]
	v_cndmask_b32_e64 v114, v125, v114, s[6:7]
	v_pk_fma_f32 v[154:155], v[78:79], v[154:155], v[182:183]
	v_pk_fma_f32 v[150:151], v[72:73], v[150:151], v[180:181]
	v_pk_fma_f32 v[148:149], v[74:75], v[148:149], v[178:179]
	v_pk_add_f32 v[118:119], v[118:119], v[154:155]
	v_pk_add_f32 v[114:115], v[114:115], v[148:149]
	v_pk_add_f32 v[112:113], v[112:113], v[150:151]
	v_cvt_pk_bf16_f32 v148, v116, v117
	v_cvt_pk_bf16_f32 v149, v118, v119
	v_mov_b32_e32 v193, v165
	v_cvt_pk_bf16_f32 v150, v112, v113
	v_cvt_pk_bf16_f32 v151, v114, v115
	v_lshlrev_b32_e32 v112, 16, v148
	v_and_b32_e32 v114, 0xffff0000, v148
	v_lshlrev_b32_e32 v116, 16, v149
	v_and_b32_e32 v118, 0xffff0000, v149
	v_lshlrev_b32_e32 v152, 16, v150
	v_and_b32_e32 v154, 0xffff0000, v150
	v_lshlrev_b32_e32 v194, 16, v151
	v_and_b32_e32 v196, 0xffff0000, v151
	v_mul_f32_e32 v113, v112, v112
	v_mul_f32_e32 v115, v114, v114
	v_mul_f32_e32 v117, v116, v116
	v_mul_f32_e32 v119, v118, v118
	v_mul_f32_e32 v153, v152, v152
	v_mul_f32_e32 v155, v154, v154
	v_mul_f32_e32 v195, v194, v194
	v_mul_f32_e32 v197, v196, v196
	v_pk_add_f32 v[112:113], v[112:113], v[114:115]
	v_pk_add_f32 v[114:115], v[116:117], v[118:119]
	v_pk_add_f32 v[116:117], v[194:195], v[196:197]
	v_pk_add_f32 v[112:113], v[112:113], v[114:115]
	v_pk_add_f32 v[114:115], v[152:153], v[154:155]
	s_nop 0
	v_pk_add_f32 v[114:115], v[114:115], v[116:117]
	s_nop 0
	v_pk_add_f32 v[112:113], v[112:113], v[114:115]
	v_mov_b32_e32 v114, v165
	v_mov_b32_e32 v115, v165
	s_nop 0
	v_mov_b32_dpp v114, v112 quad_perm:[1,0,3,2] row_mask:0xf bank_mask:0xf
	v_mov_b32_dpp v115, v113 quad_perm:[1,0,3,2] row_mask:0xf bank_mask:0xf
	v_pk_add_f32 v[112:113], v[112:113], v[114:115]
	v_mov_b32_e32 v114, v112
	v_mov_b32_e32 v115, v113
	s_nop 1
	v_permlane16_swap_b32_e32 v112, v114
	v_permlane16_swap_b32_e32 v113, v115
	s_waitcnt lgkmcnt(0)
	v_pk_add_f32 v[114:115], v[112:113], v[114:115]
	v_mov_b32_e32 v116, v114
	v_mov_b32_e32 v117, v115
	s_nop 1
	v_permlane32_swap_b32_e32 v114, v116
	v_permlane32_swap_b32_e32 v115, v117
	v_lshl_add_u64 v[112:113], s[16:17], 0, v[192:193]
	global_store_dwordx4 v[112:113], v[148:151], off
	s_and_saveexec_b64 s[56:57], s[12:13]
	s_waitcnt lgkmcnt(0)
	v_pk_add_f32 v[114:115], v[114:115], v[116:117]
	v_add_co_u32_e32 v116, vcc, 0x2000, v186
	s_nop 1
	v_addc_co_u32_e32 v117, vcc, 0, v187, vcc
	global_store_dwordx2 v[116:117], v[114:115], off

; __device__ __forceinline__ u32x4 pack8f(f32x4 a, f32x4 b) { u32x4 w; w.x = cvt_pk_bf16(a[0], a[1]); w.y = cvt_pk_bf16(a[2], a[3]); w.z = cvt_pk_bf16(b[0], b[1]); w.w = cvt_pk_bf16(b[2], b[3]); return w; }
;     __device__ __forceinline__ void operator()(const f32x4 (&acc)[2][2][4][2], const Unit& u, int wr, int wc, int fr, int fq, const EpiCtx& X) const {
;     ...
;             for (int m = 0; m < 4; ++m) {
;                 const int rl = ai * HALF + m * 16; const unsigned off = lo + (unsigned)(rl * 64) * 2u;
;                 const f32x4 o0a = acc[ai][0][m][0], o0b = acc[ai][0][m][1], o1a = acc[ai][1][m][0], o1b = acc[ai][1][m][1];
;                 const f32x4 ra_ = dpp_swap1(odd ? o0a : o1a), rb_ = dpp_swap1(odd ? o0b : o1b);
;                 const f32x4 pa[2] = {odd ? ra_ : o0a, odd ? o1a : ra_}, pb[2] = {odd ? rb_ : o0b, odd ? o1b : rb_};
; #pragma unroll
;                 for (int q = 0; q < 2; ++q) {
;                     const u32x4 w0 = raw[2 * m + q];
;                     const f32x4 r0 = (f32x4){bf_lo(w0.x), bf_hi(w0.x), bf_lo(w0.y), bf_hi(w0.y)}, r1 = (f32x4){bf_lo(w0.z), bf_hi(w0.z), bf_lo(w0.w), bf_hi(w0.w)};
;                     f32x4 y0, y1;
;                     if (RESN) { const f32x2 t = tbl[rl + q]; const float mu = t.x, ra = t.y * ALPHA; y0 = (r0 - mu) * ra * g0 + b0 + pa[q]; y1 = (r1 - mu) * ra * g1 + b1 + pb[q]; }
;                     else { y0 = r0 * ALPHA + pa[q]; y1 = r1 * ALPHA + pb[q]; }
;                     { const u32x4 w = pack8f(y0, y1); *(u32x4*)(xb + off + q * 128) = w;
;                         y0 = (f32x4){bf_lo(w.x), bf_hi(w.x), bf_lo(w.y), bf_hi(w.y)}; y1 = (f32x4){bf_lo(w.z), bf_hi(w.z), bf_lo(w.w), bf_hi(w.w)}; }
;                     float sa = ((y0[0] + y0[1]) + (y0[2] + y0[3])) + ((y1[0] + y1[1]) + (y1[2] + y1[3]));
;                     float sb = ((y0[0] * y0[0] + y0[1] * y0[1]) + (y0[2] * y0[2] + y0[3] * y0[3])) + ((y1[0] * y1[0] + y1[1] * y1[1]) + (y1[2] * y1[2] + y1[3] * y1[3]));
;                     sa += dpp_x1(sa);
;                     sb += dpp_x1(sb);
;                     sa += __shfl_xor(sa, 16); sa += __shfl_xor(sa, 32); sb += __shfl_xor(sb, 16); sb += __shfl_xor(sb, 32);
;                     if (fq == 0 && !odd) ps[(size_t)(rl + q) * 64] = (f32x2){sa, sb};
;                 }
.LBB0_1705:
	s_or_b64 exec, exec, s[56:57]
	s_waitcnt lgkmcnt(0)
	v_cndmask_b32_e64 v106, v100, v92, s[6:7]
	s_nop 0
	v_cndmask_b32_e64 v105, v101, v93, s[6:7]
	s_waitcnt lgkmcnt(0)
	v_cndmask_b32_e64 v107, v102, v94, s[6:7]
	v_mov_b32_dpp v104, v106 quad_perm:[1,0,3,2] row_mask:0xf bank_mask:0xf
	s_nop 0
	v_cndmask_b32_e64 v108, v103, v95, s[6:7]
	v_cndmask_b32_e64 v110, v96, v88, s[6:7]
	v_mov_b32_dpp v106, v105 quad_perm:[1,0,3,2] row_mask:0xf bank_mask:0xf
	s_nop 0
	v_cndmask_b32_e64 v109, v97, v89, s[6:7]
	v_cndmask_b32_e64 v111, v98, v90, s[6:7]
	v_mov_b32_dpp v105, v107 quad_perm:[1,0,3,2] row_mask:0xf bank_mask:0xf
	s_nop 0
	v_cndmask_b32_e64 v112, v99, v91, s[6:7]
	s_waitcnt vmcnt(15)
	v_lshlrev_b32_e32 v115, 16, v140
	v_mov_b32_dpp v107, v108 quad_perm:[1,0,3,2] row_mask:0xf bank_mask:0xf
	s_nop 0
	v_and_b32_e32 v116, 0xffff0000, v140
	v_cndmask_b32_e64 v101, v106, v101, s[6:7]
	v_mov_b32_dpp v108, v110 quad_perm:[1,0,3,2] row_mask:0xf bank_mask:0xf
	s_nop 0
	v_cndmask_b32_e64 v100, v104, v100, s[6:7]
	v_lshlrev_b32_e32 v118, 16, v141
	v_mov_b32_dpp v110, v109 quad_perm:[1,0,3,2] row_mask:0xf bank_mask:0xf
	s_nop 0
	v_and_b32_e32 v119, 0xffff0000, v141
	v_lshlrev_b32_e32 v120, 16, v142
	v_mov_b32_dpp v109, v111 quad_perm:[1,0,3,2] row_mask:0xf bank_mask:0xf
	s_nop 0
	v_and_b32_e32 v121, 0xffff0000, v142
	v_lshlrev_b32_e32 v122, 16, v143
	v_mov_b32_dpp v111, v112 quad_perm:[1,0,3,2] row_mask:0xf bank_mask:0xf
	ds_read_b64 v[112:113], v201 offset:256
	v_and_b32_e32 v123, 0xffff0000, v143
	v_cndmask_b32_e64 v103, v107, v103, s[6:7]
	v_cndmask_b32_e64 v102, v105, v102, s[6:7]
	v_cndmask_b32_e64 v97, v110, v97, s[6:7]
	s_waitcnt lgkmcnt(0)
	v_mul_f32_e32 v114, 0x3fb504f3, v113
	v_sub_f32_e32 v117, v116, v112
	v_sub_f32_e32 v116, v115, v112
	v_pk_mul_f32 v[116:117], v[116:117], v[114:115] op_sel_hi:[1,0]
	v_sub_f32_e32 v119, v119, v112
	v_pk_fma_f32 v[116:117], v[76:77], v[116:117], v[184:185]
	v_sub_f32_e32 v118, v118, v112
	v_pk_add_f32 v[100:101], v[100:101], v[116:117]
	v_sub_f32_e32 v117, v121, v112
	v_sub_f32_e32 v116, v120, v112
	v_sub_f32_e32 v113, v123, v112
	v_sub_f32_e32 v112, v122, v112
	v_pk_mul_f32 v[118:119], v[118:119], v[114:115] op_sel_hi:[1,0]
	v_pk_mul_f32 v[112:113], v[112:113], v[114:115] op_sel_hi:[1,0]
	v_pk_mul_f32 v[114:115], v[116:117], v[114:115] op_sel_hi:[1,0]
	v_cndmask_b32_e64 v96, v108, v96, s[6:7]
	v_cndmask_b32_e64 v99, v111, v99, s[6:7]
	v_cndmask_b32_e64 v98, v109, v98, s[6:7]
	v_pk_fma_f32 v[118:119], v[78:79], v[118:119], v[182:183]
	v_pk_fma_f32 v[114:115], v[72:73], v[114:115], v[180:181]
	v_pk_fma_f32 v[112:113], v[74:75], v[112:113], v[178:179]
	v_pk_add_f32 v[102:103], v[102:103], v[118:119]
	v_pk_add_f32 v[98:99], v[98:99], v[112:113]
	v_pk_add_f32 v[96:97], v[96:97], v[114:115]
	v_cvt_pk_bf16_f32 v112, v100, v101
	v_cvt_pk_bf16_f32 v113, v102, v103
	v_mov_b32_e32 v191, v165
	v_cvt_pk_bf16_f32 v114, v96, v97
	v_cvt_pk_bf16_f32 v115, v98, v99
	v_lshlrev_b32_e32 v96, 16, v112
	v_and_b32_e32 v98, 0xffff0000, v112
	v_lshlrev_b32_e32 v100, 16, v113
	v_and_b32_e32 v102, 0xffff0000, v113
	v_lshlrev_b32_e32 v116, 16, v114
	v_and_b32_e32 v118, 0xffff0000, v114
	v_lshlrev_b32_e32 v120, 16, v115
	v_and_b32_e32 v122, 0xffff0000, v115
	v_mul_f32_e32 v97, v96, v96
	v_mul_f32_e32 v99, v98, v98
	v_mul_f32_e32 v101, v100, v100
	v_mul_f32_e32 v103, v102, v102
	v_mul_f32_e32 v117, v116, v116
	v_mul_f32_e32 v119, v118, v118
	v_mul_f32_e32 v121, v120, v120
	v_mul_f32_e32 v123, v122, v122
	v_pk_add_f32 v[96:97], v[96:97], v[98:99]
	v_pk_add_f32 v[98:99], v[100:101], v[102:103]
	v_pk_add_f32 v[100:101], v[120:121], v[122:123]
	v_pk_add_f32 v[96:97], v[96:97], v[98:99]
	v_pk_add_f32 v[98:99], v[116:117], v[118:119]
	s_nop 0
	v_pk_add_f32 v[98:99], v[98:99], v[100:101]
	s_nop 0
	v_pk_add_f32 v[96:97], v[96:97], v[98:99]
	v_mov_b32_e32 v98, v165
	v_mov_b32_e32 v99, v165
	s_nop 0
	v_mov_b32_dpp v98, v96 quad_perm:[1,0,3,2] row_mask:0xf bank_mask:0xf
	v_mov_b32_dpp v99, v97 quad_perm:[1,0,3,2] row_mask:0xf bank_mask:0xf
	v_pk_add_f32 v[96:97], v[96:97], v[98:99]
	v_mov_b32_e32 v98, v96
	v_mov_b32_e32 v99, v97
	s_nop 1
	v_permlane16_swap_b32_e32 v96, v98
	v_permlane16_swap_b32_e32 v97, v99
	s_waitcnt lgkmcnt(0)
	v_pk_add_f32 v[98:99], v[96:97], v[98:99]
	v_mov_b32_e32 v100, v98
	v_mov_b32_e32 v101, v99
	s_nop 1
	v_permlane32_swap_b32_e32 v98, v100
	v_permlane32_swap_b32_e32 v99, v101
	v_lshl_add_u64 v[96:97], s[16:17], 0, v[190:191]
	global_store_dwordx4 v[96:97], v[112:115], off
	s_and_saveexec_b64 s[56:57], s[12:13]
	s_waitcnt lgkmcnt(0)
	v_pk_add_f32 v[98:99], v[98:99], v[100:101]
	v_add_co_u32_e32 v100, vcc, 0x4000, v186
	s_nop 1
	v_addc_co_u32_e32 v101, vcc, 0, v187, vcc
	global_store_dwordx2 v[100:101], v[98:99], off

; __device__ __forceinline__ u32x4 pack8f(f32x4 a, f32x4 b) { u32x4 w; w.x = cvt_pk_bf16(a[0], a[1]); w.y = cvt_pk_bf16(a[2], a[3]); w.z = cvt_pk_bf16(b[0], b[1]); w.w = cvt_pk_bf16(b[2], b[3]); return w; }
;     __device__ __forceinline__ void operator()(const f32x4 (&acc)[2][2][4][2], const Unit& u, int wr, int wc, int fr, int fq, const EpiCtx& X) const {
;     ...
;             for (int m = 0; m < 4; ++m) {
;                 const int rl = ai * HALF + m * 16; const unsigned off = lo + (unsigned)(rl * 64) * 2u;
;                 const f32x4 o0a = acc[ai][0][m][0], o0b = acc[ai][0][m][1], o1a = acc[ai][1][m][0], o1b = acc[ai][1][m][1];
;                 const f32x4 ra_ = dpp_swap1(odd ? o0a : o1a), rb_ = dpp_swap1(odd ? o0b : o1b);
;                 const f32x4 pa[2] = {odd ? ra_ : o0a, odd ? o1a : ra_}, pb[2] = {odd ? rb_ : o0b, odd ? o1b : rb_};
; #pragma unroll
;                 for (int q = 0; q < 2; ++q) {
;                     const u32x4 w0 = raw[2 * m + q];
;                     const f32x4 r0 = (f32x4){bf_lo(w0.x), bf_hi(w0.x), bf_lo(w0.y), bf_hi(w0.y)}, r1 = (f32x4){bf_lo(w0.z), bf_hi(w0.z), bf_lo(w0.w), bf_hi(w0.w)};
;                     f32x4 y0, y1;
;                     if (RESN) { const f32x2 t = tbl[rl + q]; const float mu = t.x, ra = t.y * ALPHA; y0 = (r0 - mu) * ra * g0 + b0 + pa[q]; y1 = (r1 - mu) * ra * g1 + b1 + pb[q]; }
;                     else { y0 = r0 * ALPHA + pa[q]; y1 = r1 * ALPHA + pb[q]; }
;                     { const u32x4 w = pack8f(y0, y1); *(u32x4*)(xb + off + q * 128) = w;
;                         y0 = (f32x4){bf_lo(w.x), bf_hi(w.x), bf_lo(w.y), bf_hi(w.y)}; y1 = (f32x4){bf_lo(w.z), bf_hi(w.z), bf_lo(w.w), bf_hi(w.w)}; }
;                     float sa = ((y0[0] + y0[1]) + (y0[2] + y0[3])) + ((y1[0] + y1[1]) + (y1[2] + y1[3]));
;                     float sb = ((y0[0] * y0[0] + y0[1] * y0[1]) + (y0[2] * y0[2] + y0[3] * y0[3])) + ((y1[0] * y1[0] + y1[1] * y1[1]) + (y1[2] * y1[2] + y1[3] * y1[3]));
;                     sa += dpp_x1(sa);
;                     sb += dpp_x1(sb);
;                     sa += __shfl_xor(sa, 16); sa += __shfl_xor(sa, 32); sb += __shfl_xor(sb, 16); sb += __shfl_xor(sb, 32);
;                     if (fq == 0 && !odd) ps[(size_t)(rl + q) * 64] = (f32x2){sa, sb};
;                 }
.LBB0_1709:
	s_or_b64 exec, exec, s[56:57]
	s_waitcnt lgkmcnt(0)
	v_cndmask_b32_e64 v90, v84, v68, s[6:7]
	s_nop 0
	v_cndmask_b32_e64 v89, v85, v69, s[6:7]
	s_waitcnt lgkmcnt(0)
	v_cndmask_b32_e64 v91, v86, v70, s[6:7]
	v_mov_b32_dpp v88, v90 quad_perm:[1,0,3,2] row_mask:0xf bank_mask:0xf
	s_nop 0
	v_cndmask_b32_e64 v92, v87, v71, s[6:7]
	v_cndmask_b32_e64 v94, v80, v64, s[6:7]
	v_mov_b32_dpp v90, v89 quad_perm:[1,0,3,2] row_mask:0xf bank_mask:0xf
	s_nop 0
	v_cndmask_b32_e64 v93, v81, v65, s[6:7]
	v_cndmask_b32_e64 v95, v82, v66, s[6:7]
	v_mov_b32_dpp v89, v91 quad_perm:[1,0,3,2] row_mask:0xf bank_mask:0xf
	s_nop 0
	v_cndmask_b32_e64 v96, v83, v67, s[6:7]
	s_waitcnt vmcnt(17)
	v_lshlrev_b32_e32 v99, 16, v132
	v_mov_b32_dpp v91, v92 quad_perm:[1,0,3,2] row_mask:0xf bank_mask:0xf
	s_nop 0
	v_and_b32_e32 v100, 0xffff0000, v132
	v_cndmask_b32_e64 v85, v90, v85, s[6:7]
	v_mov_b32_dpp v92, v94 quad_perm:[1,0,3,2] row_mask:0xf bank_mask:0xf
	s_nop 0
	v_cndmask_b32_e64 v84, v88, v84, s[6:7]
	v_lshlrev_b32_e32 v102, 16, v133
	v_mov_b32_dpp v94, v93 quad_perm:[1,0,3,2] row_mask:0xf bank_mask:0xf
	s_nop 0
	v_and_b32_e32 v103, 0xffff0000, v133
	v_lshlrev_b32_e32 v104, 16, v134
	v_mov_b32_dpp v93, v95 quad_perm:[1,0,3,2] row_mask:0xf bank_mask:0xf
	s_nop 0
	v_and_b32_e32 v105, 0xffff0000, v134
	v_lshlrev_b32_e32 v106, 16, v135
	v_mov_b32_dpp v95, v96 quad_perm:[1,0,3,2] row_mask:0xf bank_mask:0xf
	ds_read_b64 v[96:97], v201 offset:384
	v_and_b32_e32 v107, 0xffff0000, v135
	v_cndmask_b32_e64 v87, v91, v87, s[6:7]
	v_cndmask_b32_e64 v86, v89, v86, s[6:7]
	v_cndmask_b32_e64 v81, v94, v81, s[6:7]
	s_waitcnt lgkmcnt(0)
	v_mul_f32_e32 v98, 0x3fb504f3, v97
	v_sub_f32_e32 v101, v100, v96
	v_sub_f32_e32 v100, v99, v96
	v_pk_mul_f32 v[100:101], v[100:101], v[98:99] op_sel_hi:[1,0]
	v_sub_f32_e32 v103, v103, v96
	v_pk_fma_f32 v[100:101], v[76:77], v[100:101], v[184:185]
	v_sub_f32_e32 v102, v102, v96
	v_pk_add_f32 v[84:85], v[84:85], v[100:101]
	v_sub_f32_e32 v101, v105, v96
	v_sub_f32_e32 v100, v104, v96
	v_sub_f32_e32 v97, v107, v96
	v_sub_f32_e32 v96, v106, v96
	v_pk_mul_f32 v[102:103], v[102:103], v[98:99] op_sel_hi:[1,0]
	v_pk_mul_f32 v[96:97], v[96:97], v[98:99] op_sel_hi:[1,0]
	v_pk_mul_f32 v[98:99], v[100:101], v[98:99] op_sel_hi:[1,0]
	v_cndmask_b32_e64 v80, v92, v80, s[6:7]
	v_cndmask_b32_e64 v83, v95, v83, s[6:7]
	v_cndmask_b32_e64 v82, v93, v82, s[6:7]
	v_pk_fma_f32 v[102:103], v[78:79], v[102:103], v[182:183]
	v_pk_fma_f32 v[98:99], v[72:73], v[98:99], v[180:181]
	v_pk_fma_f32 v[96:97], v[74:75], v[96:97], v[178:179]
	v_pk_add_f32 v[86:87], v[86:87], v[102:103]
	v_pk_add_f32 v[82:83], v[82:83], v[96:97]
	v_pk_add_f32 v[80:81], v[80:81], v[98:99]
	v_cvt_pk_bf16_f32 v96, v84, v85
	v_cvt_pk_bf16_f32 v97, v86, v87
	v_mov_b32_e32 v189, v165
	v_cvt_pk_bf16_f32 v98, v80, v81
	v_cvt_pk_bf16_f32 v99, v82, v83
	v_lshlrev_b32_e32 v80, 16, v96
	v_and_b32_e32 v82, 0xffff0000, v96
	v_lshlrev_b32_e32 v84, 16, v97
	v_and_b32_e32 v86, 0xffff0000, v97
	v_lshlrev_b32_e32 v100, 16, v98
	v_and_b32_e32 v102, 0xffff0000, v98
	v_lshlrev_b32_e32 v104, 16, v99
	v_and_b32_e32 v106, 0xffff0000, v99
	v_mul_f32_e32 v81, v80, v80
	v_mul_f32_e32 v83, v82, v82
	v_mul_f32_e32 v85, v84, v84
	v_mul_f32_e32 v87, v86, v86
	v_mul_f32_e32 v101, v100, v100
	v_mul_f32_e32 v103, v102, v102
	v_mul_f32_e32 v105, v104, v104
	v_mul_f32_e32 v107, v106, v106
	v_pk_add_f32 v[80:81], v[80:81], v[82:83]
	v_pk_add_f32 v[82:83], v[84:85], v[86:87]
	v_pk_add_f32 v[84:85], v[104:105], v[106:107]
	v_pk_add_f32 v[80:81], v[80:81], v[82:83]
	v_pk_add_f32 v[82:83], v[100:101], v[102:103]
	s_nop 0
	v_pk_add_f32 v[82:83], v[82:83], v[84:85]
	s_nop 0
	v_pk_add_f32 v[80:81], v[80:81], v[82:83]
	v_mov_b32_e32 v82, v165
	v_mov_b32_e32 v83, v165
	s_nop 0
	v_mov_b32_dpp v82, v80 quad_perm:[1,0,3,2] row_mask:0xf bank_mask:0xf
	v_mov_b32_dpp v83, v81 quad_perm:[1,0,3,2] row_mask:0xf bank_mask:0xf
	v_pk_add_f32 v[80:81], v[80:81], v[82:83]
	v_mov_b32_e32 v82, v80
	v_mov_b32_e32 v83, v81
	s_nop 1
	v_permlane16_swap_b32_e32 v80, v82
	v_permlane16_swap_b32_e32 v81, v83
	s_waitcnt lgkmcnt(0)
	v_pk_add_f32 v[82:83], v[80:81], v[82:83]
	v_mov_b32_e32 v84, v82
	v_mov_b32_e32 v85, v83
	s_nop 1
	v_permlane32_swap_b32_e32 v82, v84
	v_permlane32_swap_b32_e32 v83, v85
	v_lshl_add_u64 v[80:81], s[16:17], 0, v[188:189]
	global_store_dwordx4 v[80:81], v[96:99], off
	s_and_saveexec_b64 s[56:57], s[12:13]
	s_waitcnt lgkmcnt(0)
	v_pk_add_f32 v[82:83], v[82:83], v[84:85]
	v_add_co_u32_e32 v84, vcc, 0x6000, v186
	s_nop 1
	v_addc_co_u32_e32 v85, vcc, 0, v187, vcc
	global_store_dwordx2 v[84:85], v[82:83], off

;     __device__ __forceinline__ void operator()(const f32x4 (&acc)[2][2][4][2], const Unit& u, int wr, int wc, int fr, int fq, const EpiCtx& X) const {
;     ...
;             for (int m = 0; m < 4; ++m) { const unsigned off = lo + (unsigned)((ai * HALF + m * 16) * 64) * 2u; raw[2 * m] = *(const u32x4*)(xb + off); raw[2 * m + 1] = *(const u32x4*)(xb + off + 128); }
; #pragma unroll
;             for (int m = 0; m < 4; ++m) {
;                 const int rl = ai * HALF + m * 16; const unsigned off = lo + (unsigned)(rl * 64) * 2u;
;                 const f32x4 o0a = acc[ai][0][m][0], o0b = acc[ai][0][m][1], o1a = acc[ai][1][m][0], o1b = acc[ai][1][m][1];
;                 const f32x4 ra_ = dpp_swap1(odd ? o0a : o1a), rb_ = dpp_swap1(odd ? o0b : o1b);
;                 const f32x4 pa[2] = {odd ? ra_ : o0a, odd ? o1a : ra_}, pb[2] = {odd ? rb_ : o0b, odd ? o1b : rb_};
; #pragma unroll
;                 for (int q = 0; q < 2; ++q) {
;                     const u32x4 w0 = raw[2 * m + q];
;                     const f32x4 r0 = (f32x4){bf_lo(w0.x), bf_hi(w0.x), bf_lo(w0.y), bf_hi(w0.y)}, r1 = (f32x4){bf_lo(w0.z), bf_hi(w0.z), bf_lo(w0.w), bf_hi(w0.w)};
;                     f32x4 y0, y1;
;                     if (RESN) { const f32x2 t = tbl[rl + q]; const float mu = t.x, ra = t.y * ALPHA; y0 = (r0 - mu) * ra * g0 + b0 + pa[q]; y1 = (r1 - mu) * ra * g1 + b1 + pb[q]; }
;                     else { y0 = r0 * ALPHA + pa[q]; y1 = r1 * ALPHA + pb[q]; }
;                     { const u32x4 w = pack8f(y0, y1); *(u32x4*)(xb + off + q * 128) = w;
;                         y0 = (f32x4){bf_lo(w.x), bf_hi(w.x), bf_lo(w.y), bf_hi(w.y)}; y1 = (f32x4){bf_lo(w.z), bf_hi(w.z), bf_lo(w.w), bf_hi(w.w)}; }
;                     float sa = ((y0[0] + y0[1]) + (y0[2] + y0[3])) + ((y1[0] + y1[1]) + (y1[2] + y1[3]));
;                     float sb = ((y0[0] * y0[0] + y0[1] * y0[1]) + (y0[2] * y0[2] + y0[3] * y0[3])) + ((y1[0] * y1[0] + y1[1] * y1[1]) + (y1[2] * y1[2] + y1[3] * y1[3]));
;                     sa += dpp_x1(sa);
;                     sb += dpp_x1(sb);
;                     sa += __shfl_xor(sa, 16); sa += __shfl_xor(sa, 32); sb += __shfl_xor(sb, 16); sb += __shfl_xor(sb, 32);
;                     if (fq == 0 && !odd) ps[(size_t)(rl + q) * 64] = (f32x2){sa, sb};
;                 }
.LBB0_1713:
	s_or_b64 exec, exec, s[56:57]
	v_add_u32_e32 v104, 0x4000, v164
	s_waitcnt vmcnt(16)
	v_mov_b32_e32 v112, v230
	v_mov_b32_e32 v113, v231
	v_mov_b32_e32 v114, v232
	v_mov_b32_e32 v115, v233
	v_add_u32_e32 v102, 0x4800, v164
	v_add_u32_e32 v100, 0x5000, v164
	v_add_u32_e32 v164, 0x5800, v164
	v_mov_b32_e32 v96, v234
	v_mov_b32_e32 v97, v235
	v_mov_b32_e32 v98, v236
	v_mov_b32_e32 v99, v237
	v_mov_b32_e32 v92, v238
	v_mov_b32_e32 v93, v239
	v_mov_b32_e32 v94, v240
	v_mov_b32_e32 v95, v241
	v_mov_b32_e32 v88, v242
	v_mov_b32_e32 v89, v243
	v_mov_b32_e32 v90, v244
	v_mov_b32_e32 v91, v245
	global_load_dwordx4 v[84:87], v100, s[16:17]
	global_load_dwordx4 v[80:83], v100, s[16:17] offset:128
	global_load_dwordx4 v[68:71], v164, s[16:17]
	s_waitcnt lgkmcnt(0)
	global_load_dwordx4 v[64:67], v164, s[16:17] offset:128
	v_cndmask_b32_e64 v116, v62, v54, s[6:7]
	v_cndmask_b32_e64 v117, v61, v53, s[6:7]
	s_nop 0
	s_nop 0
	v_cndmask_b32_e64 v111, v63, v55, s[6:7]
	v_mov_b32_dpp v105, v117 quad_perm:[1,0,3,2] row_mask:0xf bank_mask:0xf
	v_mov_b32_dpp v103, v116 quad_perm:[1,0,3,2] row_mask:0xf bank_mask:0xf
	ds_read_b64 v[116:117], v201 offset:1024
	v_cndmask_b32_e64 v118, v60, v52, s[6:7]
	s_nop 0
	s_nop 0
	v_cndmask_b32_e64 v119, v59, v51, s[6:7]
	v_cndmask_b32_e64 v120, v58, v50, s[6:7]
	v_cndmask_b32_e64 v121, v57, v49, s[6:7]
	v_cndmask_b32_e64 v122, v56, v48, s[6:7]
	s_nop 0
	s_nop 0
	s_nop 0
	s_nop 0
	v_mov_b32_dpp v101, v118 quad_perm:[1,0,3,2] row_mask:0xf bank_mask:0xf
	v_mov_b32_dpp v106, v111 quad_perm:[1,0,3,2] row_mask:0xf bank_mask:0xf
	v_mov_b32_dpp v107, v122 quad_perm:[1,0,3,2] row_mask:0xf bank_mask:0xf
	v_mov_b32_dpp v109, v121 quad_perm:[1,0,3,2] row_mask:0xf bank_mask:0xf
	v_mov_b32_dpp v108, v120 quad_perm:[1,0,3,2] row_mask:0xf bank_mask:0xf
	v_mov_b32_dpp v110, v119 quad_perm:[1,0,3,2] row_mask:0xf bank_mask:0xf
	s_waitcnt lgkmcnt(0)
	v_mul_f32_e32 v118, 0x3fb504f3, v117
	v_cndmask_b32_e64 v61, v105, v61, s[6:7]
	v_cndmask_b32_e64 v60, v101, v60, s[6:7]
	v_cndmask_b32_e64 v63, v106, v63, s[6:7]
	v_cndmask_b32_e64 v62, v103, v62, s[6:7]
	v_cndmask_b32_e64 v57, v109, v57, s[6:7]
	v_cndmask_b32_e64 v56, v107, v56, s[6:7]
	v_cndmask_b32_e64 v59, v110, v59, s[6:7]
	v_cndmask_b32_e64 v58, v108, v58, s[6:7]
	v_lshlrev_b32_e32 v111, 16, v112
	v_and_b32_e32 v112, 0xffff0000, v112
	v_lshlrev_b32_e32 v117, 16, v113
	v_and_b32_e32 v119, 0xffff0000, v113
	v_lshlrev_b32_e32 v120, 16, v114
	v_and_b32_e32 v121, 0xffff0000, v114
	v_lshlrev_b32_e32 v122, 16, v115
	v_and_b32_e32 v123, 0xffff0000, v115
	v_sub_f32_e32 v113, v112, v116
	v_sub_f32_e32 v112, v111, v116
	v_sub_f32_e32 v115, v119, v116
	v_sub_f32_e32 v114, v117, v116
	v_sub_f32_e32 v121, v121, v116
	v_sub_f32_e32 v120, v120, v116
	v_sub_f32_e32 v117, v123, v116
	v_sub_f32_e32 v116, v122, v116
	v_pk_mul_f32 v[114:115], v[114:115], v[118:119] op_sel_hi:[1,0]
	v_pk_mul_f32 v[112:113], v[112:113], v[118:119] op_sel_hi:[1,0]
	v_pk_mul_f32 v[116:117], v[116:117], v[118:119] op_sel_hi:[1,0]
	v_pk_mul_f32 v[118:119], v[120:121], v[118:119] op_sel_hi:[1,0]
	v_pk_fma_f32 v[112:113], v[76:77], v[112:113], v[184:185]
	v_pk_fma_f32 v[114:115], v[78:79], v[114:115], v[182:183]
	v_pk_fma_f32 v[118:119], v[72:73], v[118:119], v[180:181]
	v_pk_fma_f32 v[116:117], v[74:75], v[116:117], v[178:179]
	v_pk_add_f32 v[62:63], v[62:63], v[114:115]
	v_pk_add_f32 v[60:61], v[60:61], v[112:113]
	v_pk_add_f32 v[58:59], v[58:59], v[116:117]
	v_pk_add_f32 v[56:57], v[56:57], v[118:119]
	v_cvt_pk_bf16_f32 v60, v60, v61
	v_cvt_pk_bf16_f32 v61, v62, v63
	s_nop 0
	v_cvt_pk_bf16_f32 v62, v56, v57
	v_cvt_pk_bf16_f32 v63, v58, v59
	v_lshlrev_b32_e32 v56, 16, v60
	v_and_b32_e32 v58, 0xffff0000, v60
	v_lshlrev_b32_e32 v112, 16, v61
	v_and_b32_e32 v114, 0xffff0000, v61
	v_lshlrev_b32_e32 v116, 16, v62
	v_and_b32_e32 v118, 0xffff0000, v62
	v_lshlrev_b32_e32 v120, 16, v63
	v_and_b32_e32 v122, 0xffff0000, v63
	v_mul_f32_e32 v57, v56, v56
	v_mul_f32_e32 v59, v58, v58
	v_mul_f32_e32 v113, v112, v112
	v_mul_f32_e32 v115, v114, v114
	v_mul_f32_e32 v117, v116, v116
	v_mul_f32_e32 v119, v118, v118
	v_mul_f32_e32 v121, v120, v120
	v_mul_f32_e32 v123, v122, v122
	v_pk_add_f32 v[56:57], v[56:57], v[58:59]
	v_pk_add_f32 v[58:59], v[112:113], v[114:115]
	v_pk_add_f32 v[112:113], v[120:121], v[122:123]
	v_pk_add_f32 v[56:57], v[56:57], v[58:59]
	v_pk_add_f32 v[58:59], v[116:117], v[118:119]
	global_store_dwordx4 v104, v[60:63], s[16:17]
	v_pk_add_f32 v[58:59], v[58:59], v[112:113]
	s_nop 0
	v_pk_add_f32 v[56:57], v[56:57], v[58:59]
	v_mov_b32_e32 v58, v165
	v_mov_b32_e32 v59, v165
	s_nop 0
	v_mov_b32_dpp v58, v56 quad_perm:[1,0,3,2] row_mask:0xf bank_mask:0xf
	v_mov_b32_dpp v59, v57 quad_perm:[1,0,3,2] row_mask:0xf bank_mask:0xf
	v_pk_add_f32 v[56:57], v[56:57], v[58:59]
	v_mov_b32_e32 v58, v56
	v_mov_b32_e32 v59, v57
	s_nop 1
	v_permlane16_swap_b32_e32 v56, v58
	v_permlane16_swap_b32_e32 v57, v59
	s_waitcnt lgkmcnt(0)
	v_pk_add_f32 v[56:57], v[56:57], v[58:59]
	v_mov_b32_e32 v58, v56
	v_mov_b32_e32 v59, v57
	s_nop 1
	v_permlane32_swap_b32_e32 v56, v58
	v_permlane32_swap_b32_e32 v57, v59
	s_and_saveexec_b64 s[56:57], s[12:13]
	s_cbranch_execz .LBB0_1715
	s_waitcnt lgkmcnt(0)
	v_pk_add_f32 v[56:57], v[56:57], v[58:59]
	v_add_co_u32_e32 v58, vcc, 0x10000, v186
	s_nop 1
	v_addc_co_u32_e32 v59, vcc, 0, v187, vcc
	global_store_dwordx2 v[58:59], v[56:57], off

; __device__ __forceinline__ u32x4 pack8f(f32x4 a, f32x4 b) { u32x4 w; w.x = cvt_pk_bf16(a[0], a[1]); w.y = cvt_pk_bf16(a[2], a[3]); w.z = cvt_pk_bf16(b[0], b[1]); w.w = cvt_pk_bf16(b[2], b[3]); return w; }
;     __device__ __forceinline__ void operator()(const f32x4 (&acc)[2][2][4][2], const Unit& u, int wr, int wc, int fr, int fq, const EpiCtx& X) const {
;     ...
;             for (int m = 0; m < 4; ++m) {
;                 const int rl = ai * HALF + m * 16; const unsigned off = lo + (unsigned)(rl * 64) * 2u;
;                 const f32x4 o0a = acc[ai][0][m][0], o0b = acc[ai][0][m][1], o1a = acc[ai][1][m][0], o1b = acc[ai][1][m][1];
;                 const f32x4 ra_ = dpp_swap1(odd ? o0a : o1a), rb_ = dpp_swap1(odd ? o0b : o1b);
;                 const f32x4 pa[2] = {odd ? ra_ : o0a, odd ? o1a : ra_}, pb[2] = {odd ? rb_ : o0b, odd ? o1b : rb_};
; #pragma unroll
;                 for (int q = 0; q < 2; ++q) {
;                     const u32x4 w0 = raw[2 * m + q];
;                     const f32x4 r0 = (f32x4){bf_lo(w0.x), bf_hi(w0.x), bf_lo(w0.y), bf_hi(w0.y)}, r1 = (f32x4){bf_lo(w0.z), bf_hi(w0.z), bf_lo(w0.w), bf_hi(w0.w)};
;                     f32x4 y0, y1;
;                     if (RESN) { const f32x2 t = tbl[rl + q]; const float mu = t.x, ra = t.y * ALPHA; y0 = (r0 - mu) * ra * g0 + b0 + pa[q]; y1 = (r1 - mu) * ra * g1 + b1 + pb[q]; }
;                     else { y0 = r0 * ALPHA + pa[q]; y1 = r1 * ALPHA + pb[q]; }
;                     { const u32x4 w = pack8f(y0, y1); *(u32x4*)(xb + off + q * 128) = w;
;                         y0 = (f32x4){bf_lo(w.x), bf_hi(w.x), bf_lo(w.y), bf_hi(w.y)}; y1 = (f32x4){bf_lo(w.z), bf_hi(w.z), bf_lo(w.w), bf_hi(w.w)}; }
;                     float sa = ((y0[0] + y0[1]) + (y0[2] + y0[3])) + ((y1[0] + y1[1]) + (y1[2] + y1[3]));
;                     float sb = ((y0[0] * y0[0] + y0[1] * y0[1]) + (y0[2] * y0[2] + y0[3] * y0[3])) + ((y1[0] * y1[0] + y1[1] * y1[1]) + (y1[2] * y1[2] + y1[3] * y1[3]));
;                     sa += dpp_x1(sa);
;                     sb += dpp_x1(sb);
;                     sa += __shfl_xor(sa, 16); sa += __shfl_xor(sa, 32); sb += __shfl_xor(sb, 16); sb += __shfl_xor(sb, 32);
;                     if (fq == 0 && !odd) ps[(size_t)(rl + q) * 64] = (f32x2){sa, sb};
;                 }
.LBB0_1717:
	s_or_b64 exec, exec, s[56:57]
	s_waitcnt lgkmcnt(0)
	v_cndmask_b32_e64 v50, v44, v36, s[6:7]
	s_nop 0
	v_cndmask_b32_e64 v49, v45, v37, s[6:7]
	s_waitcnt lgkmcnt(0)
	v_cndmask_b32_e64 v51, v46, v38, s[6:7]
	v_mov_b32_dpp v48, v50 quad_perm:[1,0,3,2] row_mask:0xf bank_mask:0xf
	s_nop 0
	v_cndmask_b32_e64 v52, v47, v39, s[6:7]
	v_cndmask_b32_e64 v54, v40, v32, s[6:7]
	v_mov_b32_dpp v50, v49 quad_perm:[1,0,3,2] row_mask:0xf bank_mask:0xf
	s_nop 0
	v_cndmask_b32_e64 v53, v41, v33, s[6:7]
	v_cndmask_b32_e64 v55, v42, v34, s[6:7]
	v_mov_b32_dpp v49, v51 quad_perm:[1,0,3,2] row_mask:0xf bank_mask:0xf
	s_nop 0
	v_cndmask_b32_e64 v56, v43, v35, s[6:7]
	v_lshlrev_b32_e32 v59, 16, v92
	v_mov_b32_dpp v51, v52 quad_perm:[1,0,3,2] row_mask:0xf bank_mask:0xf
	s_nop 0
	v_and_b32_e32 v60, 0xffff0000, v92
	v_cndmask_b32_e64 v45, v50, v45, s[6:7]
	v_mov_b32_dpp v52, v54 quad_perm:[1,0,3,2] row_mask:0xf bank_mask:0xf
	s_nop 0
	v_cndmask_b32_e64 v44, v48, v44, s[6:7]
	v_lshlrev_b32_e32 v62, 16, v93
	v_mov_b32_dpp v54, v53 quad_perm:[1,0,3,2] row_mask:0xf bank_mask:0xf
	s_nop 0
	v_and_b32_e32 v63, 0xffff0000, v93
	v_lshlrev_b32_e32 v92, 16, v94
	v_mov_b32_dpp v53, v55 quad_perm:[1,0,3,2] row_mask:0xf bank_mask:0xf
	s_nop 0
	v_and_b32_e32 v93, 0xffff0000, v94
	v_lshlrev_b32_e32 v94, 16, v95
	v_mov_b32_dpp v55, v56 quad_perm:[1,0,3,2] row_mask:0xf bank_mask:0xf
	ds_read_b64 v[56:57], v201 offset:1152
	v_and_b32_e32 v95, 0xffff0000, v95
	v_cndmask_b32_e64 v47, v51, v47, s[6:7]
	v_cndmask_b32_e64 v46, v49, v46, s[6:7]
	v_cndmask_b32_e64 v41, v54, v41, s[6:7]
	s_waitcnt lgkmcnt(0)
	v_mul_f32_e32 v58, 0x3fb504f3, v57
	v_sub_f32_e32 v61, v60, v56
	v_sub_f32_e32 v60, v59, v56
	v_pk_mul_f32 v[60:61], v[60:61], v[58:59] op_sel_hi:[1,0]
	v_sub_f32_e32 v63, v63, v56
	v_pk_fma_f32 v[60:61], v[76:77], v[60:61], v[184:185]
	v_sub_f32_e32 v62, v62, v56
	v_pk_add_f32 v[44:45], v[44:45], v[60:61]
	v_sub_f32_e32 v61, v93, v56
	v_sub_f32_e32 v60, v92, v56
	v_sub_f32_e32 v57, v95, v56
	v_sub_f32_e32 v56, v94, v56
	v_pk_mul_f32 v[62:63], v[62:63], v[58:59] op_sel_hi:[1,0]
	v_pk_mul_f32 v[56:57], v[56:57], v[58:59] op_sel_hi:[1,0]
	v_pk_mul_f32 v[58:59], v[60:61], v[58:59] op_sel_hi:[1,0]
	v_cndmask_b32_e64 v40, v52, v40, s[6:7]
	v_cndmask_b32_e64 v43, v55, v43, s[6:7]
	v_cndmask_b32_e64 v42, v53, v42, s[6:7]
	v_pk_fma_f32 v[62:63], v[78:79], v[62:63], v[182:183]
	v_pk_fma_f32 v[58:59], v[72:73], v[58:59], v[180:181]
	v_pk_fma_f32 v[56:57], v[74:75], v[56:57], v[178:179]
	v_pk_add_f32 v[46:47], v[46:47], v[62:63]
	v_pk_add_f32 v[42:43], v[42:43], v[56:57]
	v_pk_add_f32 v[40:41], v[40:41], v[58:59]
	v_cvt_pk_bf16_f32 v56, v44, v45
	v_cvt_pk_bf16_f32 v57, v46, v47
	v_mov_b32_e32 v103, v165
	v_cvt_pk_bf16_f32 v58, v40, v41
	v_cvt_pk_bf16_f32 v59, v42, v43
	v_lshlrev_b32_e32 v40, 16, v56
	v_and_b32_e32 v42, 0xffff0000, v56
	v_lshlrev_b32_e32 v44, 16, v57
	v_and_b32_e32 v46, 0xffff0000, v57
	v_lshlrev_b32_e32 v60, 16, v58
	v_and_b32_e32 v62, 0xffff0000, v58
	v_lshlrev_b32_e32 v92, 16, v59
	v_and_b32_e32 v94, 0xffff0000, v59
	v_mul_f32_e32 v41, v40, v40
	v_mul_f32_e32 v43, v42, v42
	v_mul_f32_e32 v45, v44, v44
	v_mul_f32_e32 v47, v46, v46
	v_mul_f32_e32 v61, v60, v60
	v_mul_f32_e32 v63, v62, v62
	v_mul_f32_e32 v93, v92, v92
	v_mul_f32_e32 v95, v94, v94
	v_pk_add_f32 v[40:41], v[40:41], v[42:43]
	v_pk_add_f32 v[42:43], v[44:45], v[46:47]
	v_pk_add_f32 v[44:45], v[92:93], v[94:95]
	v_pk_add_f32 v[40:41], v[40:41], v[42:43]
	v_pk_add_f32 v[42:43], v[60:61], v[62:63]
	s_nop 0
	v_pk_add_f32 v[42:43], v[42:43], v[44:45]
	s_nop 0
	v_pk_add_f32 v[40:41], v[40:41], v[42:43]
	v_mov_b32_e32 v42, v165
	v_mov_b32_e32 v43, v165
	s_nop 0
	v_mov_b32_dpp v42, v40 quad_perm:[1,0,3,2] row_mask:0xf bank_mask:0xf
	v_mov_b32_dpp v43, v41 quad_perm:[1,0,3,2] row_mask:0xf bank_mask:0xf
	v_pk_add_f32 v[40:41], v[40:41], v[42:43]
	v_mov_b32_e32 v42, v40
	v_mov_b32_e32 v43, v41
	s_nop 1
	v_permlane16_swap_b32_e32 v40, v42
	v_permlane16_swap_b32_e32 v41, v43
	s_waitcnt lgkmcnt(0)
	v_pk_add_f32 v[42:43], v[40:41], v[42:43]
	v_mov_b32_e32 v44, v42
	v_mov_b32_e32 v45, v43
	s_nop 1
	v_permlane32_swap_b32_e32 v42, v44
	v_permlane32_swap_b32_e32 v43, v45
	v_lshl_add_u64 v[40:41], s[16:17], 0, v[102:103]
	global_store_dwordx4 v[40:41], v[56:59], off
	s_and_saveexec_b64 s[56:57], s[12:13]
	s_cbranch_execz .LBB0_1719
	s_waitcnt lgkmcnt(0)
	v_pk_add_f32 v[42:43], v[42:43], v[44:45]
	v_add_co_u32_e32 v44, vcc, 0x12000, v186
	s_nop 1
	v_addc_co_u32_e32 v45, vcc, 0, v187, vcc
	global_store_dwordx2 v[44:45], v[42:43], off

; __device__ __forceinline__ u32x4 pack8f(f32x4 a, f32x4 b) { u32x4 w; w.x = cvt_pk_bf16(a[0], a[1]); w.y = cvt_pk_bf16(a[2], a[3]); w.z = cvt_pk_bf16(b[0], b[1]); w.w = cvt_pk_bf16(b[2], b[3]); return w; }
;     __device__ __forceinline__ void operator()(const f32x4 (&acc)[2][2][4][2], const Unit& u, int wr, int wc, int fr, int fq, const EpiCtx& X) const {
;     ...
;             for (int m = 0; m < 4; ++m) {
;                 const int rl = ai * HALF + m * 16; const unsigned off = lo + (unsigned)(rl * 64) * 2u;
;                 const f32x4 o0a = acc[ai][0][m][0], o0b = acc[ai][0][m][1], o1a = acc[ai][1][m][0], o1b = acc[ai][1][m][1];
;                 const f32x4 ra_ = dpp_swap1(odd ? o0a : o1a), rb_ = dpp_swap1(odd ? o0b : o1b);
;                 const f32x4 pa[2] = {odd ? ra_ : o0a, odd ? o1a : ra_}, pb[2] = {odd ? rb_ : o0b, odd ? o1b : rb_};
; #pragma unroll
;                 for (int q = 0; q < 2; ++q) {
;                     const u32x4 w0 = raw[2 * m + q];
;                     const f32x4 r0 = (f32x4){bf_lo(w0.x), bf_hi(w0.x), bf_lo(w0.y), bf_hi(w0.y)}, r1 = (f32x4){bf_lo(w0.z), bf_hi(w0.z), bf_lo(w0.w), bf_hi(w0.w)};
;                     f32x4 y0, y1;
;                     if (RESN) { const f32x2 t = tbl[rl + q]; const float mu = t.x, ra = t.y * ALPHA; y0 = (r0 - mu) * ra * g0 + b0 + pa[q]; y1 = (r1 - mu) * ra * g1 + b1 + pb[q]; }
;                     else { y0 = r0 * ALPHA + pa[q]; y1 = r1 * ALPHA + pb[q]; }
;                     { const u32x4 w = pack8f(y0, y1); *(u32x4*)(xb + off + q * 128) = w;
;                         y0 = (f32x4){bf_lo(w.x), bf_hi(w.x), bf_lo(w.y), bf_hi(w.y)}; y1 = (f32x4){bf_lo(w.z), bf_hi(w.z), bf_lo(w.w), bf_hi(w.w)}; }
;                     float sa = ((y0[0] + y0[1]) + (y0[2] + y0[3])) + ((y1[0] + y1[1]) + (y1[2] + y1[3]));
;                     float sb = ((y0[0] * y0[0] + y0[1] * y0[1]) + (y0[2] * y0[2] + y0[3] * y0[3])) + ((y1[0] * y1[0] + y1[1] * y1[1]) + (y1[2] * y1[2] + y1[3] * y1[3]));
;                     sa += dpp_x1(sa);
;                     sb += dpp_x1(sb);
;                     sa += __shfl_xor(sa, 16); sa += __shfl_xor(sa, 32); sb += __shfl_xor(sb, 16); sb += __shfl_xor(sb, 32);
;                     if (fq == 0 && !odd) ps[(size_t)(rl + q) * 64] = (f32x2){sa, sb};
;                 }
.LBB0_1721:
	s_or_b64 exec, exec, s[56:57]
	s_waitcnt lgkmcnt(0)
	v_cndmask_b32_e64 v34, v28, v20, s[6:7]
	s_nop 0
	v_cndmask_b32_e64 v33, v29, v21, s[6:7]
	s_waitcnt lgkmcnt(0)
	v_cndmask_b32_e64 v35, v30, v22, s[6:7]
	v_mov_b32_dpp v32, v34 quad_perm:[1,0,3,2] row_mask:0xf bank_mask:0xf
	s_nop 0
	v_cndmask_b32_e64 v36, v31, v23, s[6:7]
	v_cndmask_b32_e64 v38, v24, v16, s[6:7]
	v_mov_b32_dpp v34, v33 quad_perm:[1,0,3,2] row_mask:0xf bank_mask:0xf
	s_nop 0
	v_cndmask_b32_e64 v37, v25, v17, s[6:7]
	v_cndmask_b32_e64 v39, v26, v18, s[6:7]
	v_mov_b32_dpp v33, v35 quad_perm:[1,0,3,2] row_mask:0xf bank_mask:0xf
	s_nop 0
	v_cndmask_b32_e64 v40, v27, v19, s[6:7]
	s_waitcnt vmcnt(11)
	v_lshlrev_b32_e32 v43, 16, v84
	v_mov_b32_dpp v35, v36 quad_perm:[1,0,3,2] row_mask:0xf bank_mask:0xf
	s_nop 0
	v_and_b32_e32 v44, 0xffff0000, v84
	v_cndmask_b32_e64 v29, v34, v29, s[6:7]
	v_mov_b32_dpp v36, v38 quad_perm:[1,0,3,2] row_mask:0xf bank_mask:0xf
	s_nop 0
	v_cndmask_b32_e64 v28, v32, v28, s[6:7]
	v_lshlrev_b32_e32 v46, 16, v85
	v_mov_b32_dpp v38, v37 quad_perm:[1,0,3,2] row_mask:0xf bank_mask:0xf
	s_nop 0
	v_and_b32_e32 v47, 0xffff0000, v85
	v_lshlrev_b32_e32 v48, 16, v86
	v_mov_b32_dpp v37, v39 quad_perm:[1,0,3,2] row_mask:0xf bank_mask:0xf
	s_nop 0
	v_and_b32_e32 v49, 0xffff0000, v86
	v_lshlrev_b32_e32 v50, 16, v87
	v_mov_b32_dpp v39, v40 quad_perm:[1,0,3,2] row_mask:0xf bank_mask:0xf
	ds_read_b64 v[40:41], v201 offset:1280
	v_and_b32_e32 v51, 0xffff0000, v87
	v_cndmask_b32_e64 v31, v35, v31, s[6:7]
	v_cndmask_b32_e64 v30, v33, v30, s[6:7]
	v_cndmask_b32_e64 v25, v38, v25, s[6:7]
	s_waitcnt lgkmcnt(0)
	v_mul_f32_e32 v42, 0x3fb504f3, v41
	v_sub_f32_e32 v45, v44, v40
	v_sub_f32_e32 v44, v43, v40
	v_pk_mul_f32 v[44:45], v[44:45], v[42:43] op_sel_hi:[1,0]
	v_sub_f32_e32 v47, v47, v40
	v_pk_fma_f32 v[44:45], v[76:77], v[44:45], v[184:185]
	v_sub_f32_e32 v46, v46, v40
	v_pk_add_f32 v[28:29], v[28:29], v[44:45]
	v_sub_f32_e32 v45, v49, v40
	v_sub_f32_e32 v44, v48, v40
	v_sub_f32_e32 v41, v51, v40
	v_sub_f32_e32 v40, v50, v40
	v_pk_mul_f32 v[46:47], v[46:47], v[42:43] op_sel_hi:[1,0]
	v_pk_mul_f32 v[40:41], v[40:41], v[42:43] op_sel_hi:[1,0]
	v_pk_mul_f32 v[42:43], v[44:45], v[42:43] op_sel_hi:[1,0]
	v_cndmask_b32_e64 v24, v36, v24, s[6:7]
	v_cndmask_b32_e64 v27, v39, v27, s[6:7]
	v_cndmask_b32_e64 v26, v37, v26, s[6:7]
	v_pk_fma_f32 v[46:47], v[78:79], v[46:47], v[182:183]
	v_pk_fma_f32 v[42:43], v[72:73], v[42:43], v[180:181]
	v_pk_fma_f32 v[40:41], v[74:75], v[40:41], v[178:179]
	v_pk_add_f32 v[30:31], v[30:31], v[46:47]
	v_pk_add_f32 v[26:27], v[26:27], v[40:41]
	v_pk_add_f32 v[24:25], v[24:25], v[42:43]
	v_cvt_pk_bf16_f32 v40, v28, v29
	v_cvt_pk_bf16_f32 v41, v30, v31
	v_mov_b32_e32 v101, v165
	v_cvt_pk_bf16_f32 v42, v24, v25
	v_cvt_pk_bf16_f32 v43, v26, v27
	v_lshlrev_b32_e32 v24, 16, v40
	v_and_b32_e32 v26, 0xffff0000, v40
	v_lshlrev_b32_e32 v28, 16, v41
	v_and_b32_e32 v30, 0xffff0000, v41
	v_lshlrev_b32_e32 v44, 16, v42
	v_and_b32_e32 v46, 0xffff0000, v42
	v_lshlrev_b32_e32 v48, 16, v43
	v_and_b32_e32 v50, 0xffff0000, v43
	v_mul_f32_e32 v25, v24, v24
	v_mul_f32_e32 v27, v26, v26
	v_mul_f32_e32 v29, v28, v28
	v_mul_f32_e32 v31, v30, v30
	v_mul_f32_e32 v45, v44, v44
	v_mul_f32_e32 v47, v46, v46
	v_mul_f32_e32 v49, v48, v48
	v_mul_f32_e32 v51, v50, v50
	v_pk_add_f32 v[24:25], v[24:25], v[26:27]
	v_pk_add_f32 v[26:27], v[28:29], v[30:31]
	v_pk_add_f32 v[28:29], v[48:49], v[50:51]
	v_pk_add_f32 v[24:25], v[24:25], v[26:27]
	v_pk_add_f32 v[26:27], v[44:45], v[46:47]
	s_nop 0
	v_pk_add_f32 v[26:27], v[26:27], v[28:29]
	s_nop 0
	v_pk_add_f32 v[24:25], v[24:25], v[26:27]
	v_mov_b32_e32 v26, v165
	v_mov_b32_e32 v27, v165
	s_nop 0
	v_mov_b32_dpp v26, v24 quad_perm:[1,0,3,2] row_mask:0xf bank_mask:0xf
	v_mov_b32_dpp v27, v25 quad_perm:[1,0,3,2] row_mask:0xf bank_mask:0xf
	v_pk_add_f32 v[24:25], v[24:25], v[26:27]
	v_mov_b32_e32 v26, v24
	v_mov_b32_e32 v27, v25
	s_nop 1
	v_permlane16_swap_b32_e32 v24, v26
	v_permlane16_swap_b32_e32 v25, v27
	s_waitcnt lgkmcnt(0)
	v_pk_add_f32 v[26:27], v[24:25], v[26:27]
	v_mov_b32_e32 v28, v26
	v_mov_b32_e32 v29, v27
	s_nop 1
	v_permlane32_swap_b32_e32 v26, v28
	v_permlane32_swap_b32_e32 v27, v29
	v_lshl_add_u64 v[24:25], s[16:17], 0, v[100:101]
	global_store_dwordx4 v[24:25], v[40:43], off
	s_and_saveexec_b64 s[56:57], s[12:13]
	s_cbranch_execz .LBB0_1723
	s_waitcnt lgkmcnt(0)
	v_pk_add_f32 v[26:27], v[26:27], v[28:29]
	v_add_co_u32_e32 v28, vcc, 0x14000, v186
	s_nop 1
	v_addc_co_u32_e32 v29, vcc, 0, v187, vcc
	global_store_dwordx2 v[28:29], v[26:27], off

; __device__ __forceinline__ u32x4 pack8f(f32x4 a, f32x4 b) { u32x4 w; w.x = cvt_pk_bf16(a[0], a[1]); w.y = cvt_pk_bf16(a[2], a[3]); w.z = cvt_pk_bf16(b[0], b[1]); w.w = cvt_pk_bf16(b[2], b[3]); return w; }
;     __device__ __forceinline__ void operator()(const f32x4 (&acc)[2][2][4][2], const Unit& u, int wr, int wc, int fr, int fq, const EpiCtx& X) const {
;     ...
;             for (int m = 0; m < 4; ++m) {
;                 const int rl = ai * HALF + m * 16; const unsigned off = lo + (unsigned)(rl * 64) * 2u;
;                 const f32x4 o0a = acc[ai][0][m][0], o0b = acc[ai][0][m][1], o1a = acc[ai][1][m][0], o1b = acc[ai][1][m][1];
;                 const f32x4 ra_ = dpp_swap1(odd ? o0a : o1a), rb_ = dpp_swap1(odd ? o0b : o1b);
;                 const f32x4 pa[2] = {odd ? ra_ : o0a, odd ? o1a : ra_}, pb[2] = {odd ? rb_ : o0b, odd ? o1b : rb_};
; #pragma unroll
;                 for (int q = 0; q < 2; ++q) {
;                     const u32x4 w0 = raw[2 * m + q];
;                     const f32x4 r0 = (f32x4){bf_lo(w0.x), bf_hi(w0.x), bf_lo(w0.y), bf_hi(w0.y)}, r1 = (f32x4){bf_lo(w0.z), bf_hi(w0.z), bf_lo(w0.w), bf_hi(w0.w)};
;                     f32x4 y0, y1;
;                     if (RESN) { const f32x2 t = tbl[rl + q]; const float mu = t.x, ra = t.y * ALPHA; y0 = (r0 - mu) * ra * g0 + b0 + pa[q]; y1 = (r1 - mu) * ra * g1 + b1 + pb[q]; }
;                     else { y0 = r0 * ALPHA + pa[q]; y1 = r1 * ALPHA + pb[q]; }
;                     { const u32x4 w = pack8f(y0, y1); *(u32x4*)(xb + off + q * 128) = w;
;                         y0 = (f32x4){bf_lo(w.x), bf_hi(w.x), bf_lo(w.y), bf_hi(w.y)}; y1 = (f32x4){bf_lo(w.z), bf_hi(w.z), bf_lo(w.w), bf_hi(w.w)}; }
;                     float sa = ((y0[0] + y0[1]) + (y0[2] + y0[3])) + ((y1[0] + y1[1]) + (y1[2] + y1[3]));
;                     float sb = ((y0[0] * y0[0] + y0[1] * y0[1]) + (y0[2] * y0[2] + y0[3] * y0[3])) + ((y1[0] * y1[0] + y1[1] * y1[1]) + (y1[2] * y1[2] + y1[3] * y1[3]));
;                     sa += dpp_x1(sa);
;                     sb += dpp_x1(sb);
;                     sa += __shfl_xor(sa, 16); sa += __shfl_xor(sa, 32); sb += __shfl_xor(sb, 16); sb += __shfl_xor(sb, 32);
;                     if (fq == 0 && !odd) ps[(size_t)(rl + q) * 64] = (f32x2){sa, sb};
;                 }
.LBB0_1725:
	s_or_b64 exec, exec, s[56:57]
	s_waitcnt lgkmcnt(0)
	v_cndmask_b32_e64 v18, v12, v4, s[6:7]
	s_nop 0
	v_cndmask_b32_e64 v17, v13, v5, s[6:7]
	s_waitcnt lgkmcnt(0)
	v_cndmask_b32_e64 v19, v14, v6, s[6:7]
	v_mov_b32_dpp v16, v18 quad_perm:[1,0,3,2] row_mask:0xf bank_mask:0xf
	s_nop 0
	v_cndmask_b32_e64 v20, v15, v7, s[6:7]
	v_cndmask_b32_e64 v22, v8, v0, s[6:7]
	v_mov_b32_dpp v18, v17 quad_perm:[1,0,3,2] row_mask:0xf bank_mask:0xf
	s_nop 0
	v_cndmask_b32_e64 v21, v9, v1, s[6:7]
	v_cndmask_b32_e64 v23, v10, v2, s[6:7]
	v_mov_b32_dpp v17, v19 quad_perm:[1,0,3,2] row_mask:0xf bank_mask:0xf
	s_nop 0
	v_cndmask_b32_e64 v24, v11, v3, s[6:7]
	s_waitcnt vmcnt(13)
	v_lshlrev_b32_e32 v27, 16, v68
	v_mov_b32_dpp v19, v20 quad_perm:[1,0,3,2] row_mask:0xf bank_mask:0xf
	s_nop 0
	v_and_b32_e32 v28, 0xffff0000, v68
	v_cndmask_b32_e64 v13, v18, v13, s[6:7]
	v_mov_b32_dpp v20, v22 quad_perm:[1,0,3,2] row_mask:0xf bank_mask:0xf
	s_nop 0
	v_cndmask_b32_e64 v12, v16, v12, s[6:7]
	v_lshlrev_b32_e32 v30, 16, v69
	v_mov_b32_dpp v22, v21 quad_perm:[1,0,3,2] row_mask:0xf bank_mask:0xf
	s_nop 0
	v_and_b32_e32 v31, 0xffff0000, v69
	v_lshlrev_b32_e32 v32, 16, v70
	v_mov_b32_dpp v21, v23 quad_perm:[1,0,3,2] row_mask:0xf bank_mask:0xf
	s_nop 0
	v_and_b32_e32 v33, 0xffff0000, v70
	v_lshlrev_b32_e32 v34, 16, v71
	v_mov_b32_dpp v23, v24 quad_perm:[1,0,3,2] row_mask:0xf bank_mask:0xf
	ds_read_b64 v[24:25], v201 offset:1408
	v_and_b32_e32 v35, 0xffff0000, v71
	v_cndmask_b32_e64 v15, v19, v15, s[6:7]
	v_cndmask_b32_e64 v14, v17, v14, s[6:7]
	v_cndmask_b32_e64 v9, v22, v9, s[6:7]
	s_waitcnt lgkmcnt(0)
	v_mul_f32_e32 v26, 0x3fb504f3, v25
	v_sub_f32_e32 v29, v28, v24
	v_sub_f32_e32 v28, v27, v24
	v_pk_mul_f32 v[28:29], v[28:29], v[26:27] op_sel_hi:[1,0]
	v_sub_f32_e32 v31, v31, v24
	v_pk_fma_f32 v[28:29], v[76:77], v[28:29], v[184:185]
	v_sub_f32_e32 v30, v30, v24
	v_pk_add_f32 v[12:13], v[12:13], v[28:29]
	v_sub_f32_e32 v29, v33, v24
	v_sub_f32_e32 v28, v32, v24
	v_sub_f32_e32 v25, v35, v24
	v_sub_f32_e32 v24, v34, v24
	v_pk_mul_f32 v[30:31], v[30:31], v[26:27] op_sel_hi:[1,0]
	v_pk_mul_f32 v[24:25], v[24:25], v[26:27] op_sel_hi:[1,0]
	v_pk_mul_f32 v[26:27], v[28:29], v[26:27] op_sel_hi:[1,0]
	v_cndmask_b32_e64 v8, v20, v8, s[6:7]
	v_cndmask_b32_e64 v11, v23, v11, s[6:7]
	v_cndmask_b32_e64 v10, v21, v10, s[6:7]
	v_pk_fma_f32 v[30:31], v[78:79], v[30:31], v[182:183]
	v_pk_fma_f32 v[26:27], v[72:73], v[26:27], v[180:181]
	v_pk_fma_f32 v[24:25], v[74:75], v[24:25], v[178:179]
	v_pk_add_f32 v[14:15], v[14:15], v[30:31]
	v_pk_add_f32 v[10:11], v[10:11], v[24:25]
	v_pk_add_f32 v[8:9], v[8:9], v[26:27]
	v_cvt_pk_bf16_f32 v24, v12, v13
	v_cvt_pk_bf16_f32 v25, v14, v15
	s_nop 0
	v_cvt_pk_bf16_f32 v26, v8, v9
	v_cvt_pk_bf16_f32 v27, v10, v11
	v_lshlrev_b32_e32 v8, 16, v24
	v_and_b32_e32 v10, 0xffff0000, v24
	v_lshlrev_b32_e32 v12, 16, v25
	v_and_b32_e32 v14, 0xffff0000, v25
	v_lshlrev_b32_e32 v28, 16, v26
	v_and_b32_e32 v30, 0xffff0000, v26
	v_lshlrev_b32_e32 v32, 16, v27
	v_and_b32_e32 v34, 0xffff0000, v27
	v_mul_f32_e32 v9, v8, v8
	v_mul_f32_e32 v11, v10, v10
	v_mul_f32_e32 v13, v12, v12
	v_mul_f32_e32 v15, v14, v14
	v_mul_f32_e32 v29, v28, v28
	v_mul_f32_e32 v31, v30, v30
	v_mul_f32_e32 v33, v32, v32
	v_mul_f32_e32 v35, v34, v34
	v_pk_add_f32 v[8:9], v[8:9], v[10:11]
	v_pk_add_f32 v[10:11], v[12:13], v[14:15]
	v_pk_add_f32 v[12:13], v[32:33], v[34:35]
	v_pk_add_f32 v[8:9], v[8:9], v[10:11]
	v_pk_add_f32 v[10:11], v[28:29], v[30:31]
	s_nop 0
	v_pk_add_f32 v[10:11], v[10:11], v[12:13]
	s_nop 0
	v_pk_add_f32 v[8:9], v[8:9], v[10:11]
	v_mov_b32_e32 v10, v165
	v_mov_b32_e32 v11, v165
	s_nop 0
	v_mov_b32_dpp v10, v8 quad_perm:[1,0,3,2] row_mask:0xf bank_mask:0xf
	v_mov_b32_dpp v11, v9 quad_perm:[1,0,3,2] row_mask:0xf bank_mask:0xf
	v_pk_add_f32 v[8:9], v[8:9], v[10:11]
	v_mov_b32_e32 v10, v8
	v_mov_b32_e32 v11, v9
	s_nop 1
	v_permlane16_swap_b32_e32 v8, v10
	v_permlane16_swap_b32_e32 v9, v11
	s_waitcnt lgkmcnt(0)
	v_pk_add_f32 v[10:11], v[8:9], v[10:11]
	v_mov_b32_e32 v12, v10
	v_mov_b32_e32 v13, v11
	s_nop 1
	v_permlane32_swap_b32_e32 v10, v12
	v_permlane32_swap_b32_e32 v11, v13
	v_lshl_add_u64 v[8:9], s[16:17], 0, v[164:165]
	global_store_dwordx4 v[8:9], v[24:27], off
	s_and_saveexec_b64 s[16:17], s[12:13]
	s_cbranch_execz .LBB0_1727
	s_waitcnt lgkmcnt(0)
	v_pk_add_f32 v[10:11], v[10:11], v[12:13]
	v_add_co_u32_e32 v12, vcc, 0x16000, v186
	s_nop 1
	v_addc_co_u32_e32 v13, vcc, 0, v187, vcc
	global_store_dwordx2 v[12:13], v[10:11], off
